# v31 plus scoring VALU reorder: v_cmp issued before the two independent ops so they cover the vcc hazard (one s_nop less per tile)
# baseline (speedup 1.0000x reference)
.Lidxd_p:
	v_mad_i64_i32 v[4:5], s[74:75], v2, s80, v[42:43]
	v_lshl_add_u64 v[4:5], v[4:5], 0, v[0:1]
	v_mov_b32_e32 v87, v1
	v_lshl_add_u64 v[4:5], v[4:5], 0, v[86:87]
	s_mov_b64 s[74:75], 0x1200
	v_lshl_add_u64 v[34:35], v[4:5], 0, s[74:75]
	v_add_co_u32_e32 v4, vcc, 0x1000, v4
	global_load_dwordx4 v[10:13], v[34:35], off offset:64
	s_nop 0
	v_addc_co_u32_e32 v5, vcc, 0, v5, vcc
	global_load_dwordx4 v[14:17], v[4:5], off offset:512
	v_ashrrev_i32_e32 v3, 31, v2
	v_lshlrev_b64 v[2:3], 8, v[2:3]
	v_lshl_add_u64 v[44:45], v[82:83], 0, v[2:3]
	global_load_dwordx4 v[18:21], v[44:45], off
	global_load_dwordx4 v[22:25], v[44:45], off offset:16
	global_load_dwordx4 v[26:29], v[44:45], off offset:32
	global_load_dwordx4 v[30:33], v[44:45], off offset:48
	global_load_dwordx4 v[6:9], v[34:35], off offset:32
	global_load_dwordx4 v[2:5], v[34:35], off offset:96
	s_movk_i32 s2, 0xf800
	v_and_b32_e32 v177, 0x7fe, v88
	v_or_b32_e32 v184, v88, v94
	v_mad_i64_i32 v[184:185], vcc, v184, s80, v[42:43]
	v_add_co_u32_e32 v184, vcc, 0x3300, v184
	s_nop 1
	v_addc_co_u32_e32 v185, vcc, 0, v185, vcc
	global_load_dwordx4 v[66:69], v[184:185], off
	global_load_dwordx4 v[180:183], v[184:185], off offset:16
	s_waitcnt vmcnt(7)
	v_lshlrev_b32_e32 v34, 16, v10
	v_and_b32_e32 v10, 0xffff0000, v10
	v_lshlrev_b32_e32 v36, 16, v11
	v_and_b32_e32 v38, 0xffff0000, v11
	v_lshlrev_b32_e32 v40, 16, v12
	v_and_b32_e32 v12, 0xffff0000, v12
	v_lshlrev_b32_e32 v46, 16, v13
	v_and_b32_e32 v48, 0xffff0000, v13
	s_waitcnt vmcnt(6)
	v_lshlrev_b32_e32 v35, 16, v14
	v_and_b32_e32 v11, 0xffff0000, v14
	v_lshlrev_b32_e32 v37, 16, v15
	v_and_b32_e32 v39, 0xffff0000, v15
	v_lshlrev_b32_e32 v41, 16, v16
	v_and_b32_e32 v13, 0xffff0000, v16
	v_lshlrev_b32_e32 v47, 16, v17
	v_and_b32_e32 v49, 0xffff0000, v17
	s_waitcnt vmcnt(5)
	v_pk_mul_f32 v[14:15], v[18:19], v[34:35] op_sel:[0,1] op_sel_hi:[1,0]
	v_pk_mul_f32 v[16:17], v[18:19], v[34:35]
	v_pk_mul_f32 v[18:19], v[20:21], v[10:11] op_sel:[0,1] op_sel_hi:[1,0]
	v_pk_mul_f32 v[10:11], v[20:21], v[10:11]
	s_waitcnt vmcnt(4)
	v_pk_mul_f32 v[20:21], v[22:23], v[36:37] op_sel:[0,1] op_sel_hi:[1,0]
	v_pk_mul_f32 v[22:23], v[22:23], v[36:37]
	v_pk_mul_f32 v[34:35], v[24:25], v[38:39] op_sel:[0,1] op_sel_hi:[1,0]
	v_pk_mul_f32 v[24:25], v[24:25], v[38:39]
	s_waitcnt vmcnt(3)
	v_pk_mul_f32 v[36:37], v[26:27], v[40:41] op_sel:[0,1] op_sel_hi:[1,0]
	v_pk_mul_f32 v[26:27], v[26:27], v[40:41]
	v_pk_mul_f32 v[38:39], v[28:29], v[12:13] op_sel:[0,1] op_sel_hi:[1,0]
	v_pk_mul_f32 v[12:13], v[28:29], v[12:13]
	s_waitcnt vmcnt(2)
	v_pk_mul_f32 v[28:29], v[30:31], v[46:47] op_sel:[0,1] op_sel_hi:[1,0]
	v_pk_mul_f32 v[30:31], v[30:31], v[46:47]
	v_pk_mul_f32 v[40:41], v[32:33], v[48:49] op_sel:[0,1] op_sel_hi:[1,0]
	v_pk_mul_f32 v[32:33], v[32:33], v[48:49]
	v_sub_f32_e32 v14, v14, v15
	v_add_f32_e32 v15, v17, v16
	v_sub_f32_e32 v16, v18, v19
	v_add_f32_e32 v10, v10, v11
	v_sub_f32_e32 v11, v20, v21
	v_add_f32_e32 v17, v22, v23
	v_sub_f32_e32 v18, v34, v35
	v_add_f32_e32 v19, v24, v25
	v_sub_f32_e32 v20, v36, v37
	v_add_f32_e32 v21, v26, v27
	v_sub_f32_e32 v22, v38, v39
	v_add_f32_e32 v12, v12, v13
	v_sub_f32_e32 v13, v28, v29
	v_add_f32_e32 v23, v30, v31
	v_sub_f32_e32 v24, v40, v41
	v_add_f32_e32 v25, v32, v33
	v_cvt_pk_bf16_f32 v38, v14, v16
	v_cvt_pk_bf16_f32 v39, v11, v18
	v_cvt_pk_bf16_f32 v40, v20, v22
	v_cvt_pk_bf16_f32 v41, v13, v24
	v_cvt_pk_bf16_f32 v34, v15, v10
	v_cvt_pk_bf16_f32 v35, v17, v19
	v_cvt_pk_bf16_f32 v36, v21, v12
	v_cvt_pk_bf16_f32 v37, v23, v25
	global_load_dwordx4 v[10:13], v[44:45], off offset:128
	global_load_dwordx4 v[14:17], v[44:45], off offset:144
	global_load_dwordx4 v[18:21], v[44:45], off offset:160
	global_load_dwordx4 v[22:25], v[44:45], off offset:176
	v_or_b32_e32 v26, v88, v94
	v_and_or_b32 v28, v88, s2, v93
	v_mad_i64_i32 v[26:27], s[74:75], v26, s80, v[42:43]
	s_movk_i32 s2, 0x3000
	v_mad_i64_i32 v[28:29], s[74:75], v28, s80, v[42:43]
	v_add_co_u32_e32 v32, vcc, s2, v26
	v_lshl_add_u64 v[30:31], v[28:29], 0, v[86:87]
	s_nop 0
	v_addc_co_u32_e32 v33, vcc, 0, v27, vcc
	s_waitcnt vmcnt(5)
	v_lshlrev_b32_e32 v27, 16, v6
	v_and_b32_e32 v29, 0xffff0000, v6
	v_lshlrev_b32_e32 v43, 16, v7
	v_and_b32_e32 v7, 0xffff0000, v7
	v_lshlrev_b32_e32 v45, 16, v8
	v_and_b32_e32 v47, 0xffff0000, v8
	v_lshlrev_b32_e32 v49, 16, v9
	v_and_b32_e32 v9, 0xffff0000, v9
	s_waitcnt vmcnt(4)
	v_lshlrev_b32_e32 v26, 16, v2
	v_and_b32_e32 v28, 0xffff0000, v2
	v_lshlrev_b32_e32 v42, 16, v3
	v_and_b32_e32 v6, 0xffff0000, v3
	v_lshlrev_b32_e32 v44, 16, v4
	v_and_b32_e32 v46, 0xffff0000, v4
	v_and_b32_e32 v8, 0xffff0000, v5
	s_mov_b64 s[74:75], 0x3200
	v_lshlrev_b32_e32 v48, 16, v5
	v_lshl_add_u64 v[90:91], v[30:31], 0, s[74:75]
	v_add_co_u32_e32 v30, vcc, 0x3000, v30
	v_cmp_lt_u32_e64 s[74:75], 31, v177
	s_nop 0
	v_addc_co_u32_e32 v31, vcc, 0, v31, vcc
	s_waitcnt vmcnt(3)
	v_pk_mul_f32 v[2:3], v[10:11], v[26:27] op_sel:[0,1] op_sel_hi:[1,0]
	v_pk_mul_f32 v[4:5], v[10:11], v[26:27]
	v_pk_mul_f32 v[10:11], v[12:13], v[28:29] op_sel:[0,1] op_sel_hi:[1,0]
	v_pk_mul_f32 v[12:13], v[12:13], v[28:29]
	s_waitcnt vmcnt(2)
	v_pk_mul_f32 v[26:27], v[14:15], v[42:43] op_sel:[0,1] op_sel_hi:[1,0]
	v_pk_mul_f32 v[14:15], v[14:15], v[42:43]
	v_pk_mul_f32 v[28:29], v[16:17], v[6:7] op_sel:[0,1] op_sel_hi:[1,0]
	v_pk_mul_f32 v[6:7], v[16:17], v[6:7]
	s_waitcnt vmcnt(1)
	v_pk_mul_f32 v[16:17], v[18:19], v[44:45] op_sel:[0,1] op_sel_hi:[1,0]
	v_pk_mul_f32 v[18:19], v[18:19], v[44:45]
	v_pk_mul_f32 v[42:43], v[20:21], v[46:47] op_sel:[0,1] op_sel_hi:[1,0]
	v_pk_mul_f32 v[20:21], v[20:21], v[46:47]
	s_waitcnt vmcnt(0)
	v_pk_mul_f32 v[46:47], v[24:25], v[8:9] op_sel:[0,1] op_sel_hi:[1,0]
	v_pk_mul_f32 v[44:45], v[22:23], v[48:49] op_sel:[0,1] op_sel_hi:[1,0]
	v_pk_mul_f32 v[22:23], v[22:23], v[48:49]
	v_pk_mul_f32 v[8:9], v[24:25], v[8:9]
	v_sub_f32_e32 v2, v2, v3
	v_add_f32_e32 v3, v4, v5
	v_sub_f32_e32 v4, v10, v11
	v_add_f32_e32 v5, v12, v13
	v_add_f32_e32 v13, v18, v19
	v_sub_f32_e32 v18, v46, v47
	v_sub_f32_e32 v10, v26, v27
	v_add_f32_e32 v11, v14, v15
	v_sub_f32_e32 v12, v28, v29
	v_add_f32_e32 v6, v6, v7
	v_sub_f32_e32 v7, v16, v17
	v_sub_f32_e32 v14, v42, v43
	v_add_f32_e32 v15, v20, v21
	v_sub_f32_e32 v16, v44, v45
	v_add_f32_e32 v17, v22, v23
	v_add_f32_e32 v8, v8, v9
	v_cvt_pk_bf16_f32 v46, v2, v4
	v_cvt_pk_bf16_f32 v47, v10, v12
	v_cvt_pk_bf16_f32 v48, v7, v14
	v_cvt_pk_bf16_f32 v49, v16, v18
	v_cvt_pk_bf16_f32 v42, v3, v5
	v_cvt_pk_bf16_f32 v43, v11, v6
	v_cvt_pk_bf16_f32 v44, v13, v15
	v_cvt_pk_bf16_f32 v45, v17, v8
	s_waitcnt vmcnt(0)
	s_barrier
	v_add_u32_e32 v78, 0x10000, v74
	ds_read_b128 v[6:9], v78
	ds_read_b128 v[58:61], v78 offset:4096
	v_add_u32_e32 v78, 0x10000, v75
	ds_read_b128 v[26:29], v78
	ds_read_b128 v[54:57], v78 offset:4096
	v_add_u32_e32 v78, 0x10000, v76
	ds_read_b128 v[18:21], v78
	ds_read_b128 v[50:53], v78 offset:4096
	v_add_u32_e32 v78, 0x10000, v77
	ds_read_b128 v[22:25], v78
	ds_read_b128 v[62:65], v78 offset:4096
	v_mov_b64_e32 v[2:3], v[66:67]
	v_mov_b64_e32 v[4:5], v[68:69]
	v_mov_b64_e32 v[10:11], v[180:181]
	v_mov_b64_e32 v[12:13], v[182:183]
	v_lshlrev_b32_e32 v174, 16, v2
	v_lshlrev_b32_e32 v166, 16, v10
	v_and_b32_e32 v173, 0xffff0000, v2
	v_and_b32_e32 v165, 0xffff0000, v10
	v_lshlrev_b32_e32 v172, 16, v3
	v_lshlrev_b32_e32 v164, 16, v11
	v_and_b32_e32 v171, 0xffff0000, v3
	v_and_b32_e32 v163, 0xffff0000, v11
	v_lshlrev_b32_e32 v170, 16, v4
	v_lshlrev_b32_e32 v162, 16, v12
	v_and_b32_e32 v169, 0xffff0000, v4
	v_and_b32_e32 v161, 0xffff0000, v12
	v_lshlrev_b32_e32 v168, 16, v5
	v_lshlrev_b32_e32 v160, 16, v13
	v_and_b32_e32 v167, 0xffff0000, v5
	v_and_b32_e32 v89, 0xffff0000, v13
	s_waitcnt lgkmcnt(0)
	v_mfma_f32_32x32x16_bf16 v[2:17], v[38:41], v[6:9], 0
	v_or_b32_e32 v87, v177, v94
	v_mov_b32_e32 v175, 0
	v_mfma_f32_32x32x16_bf16 v[2:17], v[46:49], v[26:29], v[2:17]
	v_mfma_f32_32x32x16_bf16 v[2:17], v[34:37], v[18:21], v[2:17]
	v_mfma_f32_32x32x16_bf16 v[2:17], v[42:45], v[22:25], v[2:17]
	v_readfirstlane_b32 s2, v177
	s_cmp_gt_u32 s2, 0x1f
	s_cbranch_scc0 .Lidxp_e1
	s_waitcnt lgkmcnt(0)
	v_mfma_f32_32x32x16_bf16 v[18:33], v[38:41], v[58:61], 0
	v_mfma_f32_32x32x16_bf16 v[18:33], v[46:49], v[54:57], v[18:33]
	v_mfma_f32_32x32x16_bf16 v[18:33], v[34:37], v[50:53], v[18:33]
	v_mfma_f32_32x32x16_bf16 v[18:33], v[42:45], v[62:65], v[18:33]
	ds_read_b128 v[58:61], v74 offset:0
	ds_read_b128 v[54:57], v75 offset:0
	ds_read_b128 v[50:53], v76 offset:0
	ds_read_b128 v[62:65], v77 offset:0
	s_nop 3
	v_max_f32_e32 v2, 0, v2
	v_fma_f32 v2, v174, v2, 0
	v_max_f32_e32 v3, 0, v3
	v_fmac_f32_e32 v2, v173, v3
	v_max_f32_e32 v3, 0, v4
	v_fmac_f32_e32 v2, v172, v3
	v_max_f32_e32 v3, 0, v5
	v_fmac_f32_e32 v2, v171, v3
	v_max_f32_e32 v3, 0, v6
	v_fmac_f32_e32 v2, v170, v3
	v_max_f32_e32 v3, 0, v7
	v_fmac_f32_e32 v2, v169, v3
	v_max_f32_e32 v3, 0, v8
	v_fmac_f32_e32 v2, v168, v3
	v_max_f32_e32 v3, 0, v9
	v_fmac_f32_e32 v2, v167, v3
	v_max_f32_e32 v3, 0, v10
	v_fmac_f32_e32 v2, v166, v3
	v_max_f32_e32 v3, 0, v11
	v_fmac_f32_e32 v2, v165, v3
	v_max_f32_e32 v3, 0, v12
	v_fmac_f32_e32 v2, v164, v3
	v_max_f32_e32 v3, 0, v13
	v_fmac_f32_e32 v2, v163, v3
	v_max_f32_e32 v3, 0, v14
	v_fmac_f32_e32 v2, v162, v3
	v_max_f32_e32 v3, 0, v15
	v_fmac_f32_e32 v2, v161, v3
	v_max_f32_e32 v3, 0, v16
	v_fmac_f32_e32 v2, v160, v3
	v_max_f32_e32 v3, 0, v17
	v_fmac_f32_e32 v2, v89, v3
	v_cmp_gt_i32_e32 vcc, 0, v2
	v_not_b32_e32 v3, v2
	v_or_b32_e32 v4, 0x80000000, v2
	v_cndmask_b32_e32 v2, v4, v3, vcc
	v_cmp_le_u32_e32 vcc, v93, v87
	s_nop 1
	v_cndmask_b32_e32 v81, 0, v2, vcc
.LBB0_405:
	s_xor_b64 s[80:81], s[82:83], -1
	v_mov_b32_e32 v176, 0
	s_cmp_gt_u32 s2, 0x3f
	s_cbranch_scc0 .Lidxp_e2
	s_waitcnt lgkmcnt(0)
	v_mfma_f32_32x32x16_bf16 v[2:17], v[38:41], v[58:61], 0
	v_max_f32_e32 v18, 0, v18
	v_max_f32_e32 v19, 0, v19
	v_fma_f32 v18, v174, v18, 0
	v_max_f32_e32 v20, 0, v20
	v_fmac_f32_e32 v18, v173, v19
	v_max_f32_e32 v21, 0, v21
	v_fmac_f32_e32 v18, v172, v20
	v_max_f32_e32 v22, 0, v22
	v_fmac_f32_e32 v18, v171, v21
	v_max_f32_e32 v23, 0, v23
	v_mfma_f32_32x32x16_bf16 v[2:17], v[46:49], v[54:57], v[2:17]
	v_fmac_f32_e32 v18, v170, v22
	v_max_f32_e32 v24, 0, v24
	v_fmac_f32_e32 v18, v169, v23
	v_max_f32_e32 v25, 0, v25
	v_fmac_f32_e32 v18, v168, v24
	v_max_f32_e32 v26, 0, v26
	v_fmac_f32_e32 v18, v167, v25
	v_max_f32_e32 v27, 0, v27
	v_fmac_f32_e32 v18, v166, v26
	v_max_f32_e32 v28, 0, v28
	v_mfma_f32_32x32x16_bf16 v[2:17], v[34:37], v[50:53], v[2:17]
	v_fmac_f32_e32 v18, v165, v27
	v_max_f32_e32 v29, 0, v29
	v_fmac_f32_e32 v18, v164, v28
	v_max_f32_e32 v30, 0, v30
	v_fmac_f32_e32 v18, v163, v29
	v_fmac_f32_e32 v18, v162, v30
	v_max_f32_e32 v19, 0, v31
	v_fmac_f32_e32 v18, v161, v19
	v_max_f32_e32 v19, 0, v32
	v_fmac_f32_e32 v18, v160, v19
	v_mfma_f32_32x32x16_bf16 v[2:17], v[42:45], v[62:65], v[2:17]
	ds_read_b128 v[58:61], v74 offset:4096
	ds_read_b128 v[54:57], v75 offset:4096
	ds_read_b128 v[50:53], v76 offset:4096
	ds_read_b128 v[62:65], v77 offset:4096
	v_max_f32_e32 v19, 0, v33
	v_fmac_f32_e32 v18, v89, v19
	v_cmp_gt_i32_e32 vcc, 0, v18
	v_not_b32_e32 v19, v18
	v_or_b32_e32 v20, 0x80000000, v18
	v_cndmask_b32_e32 v18, v20, v19, vcc
	v_cmp_le_u32_e32 vcc, v96, v87
	s_nop 1
	v_cndmask_b32_e32 v175, 0, v18, vcc
.LBB0_409:
	v_mov_b32_e32 v179, 0
	s_cmp_gt_u32 s2, 0x5f
	s_cbranch_scc0 .Lidxp_e3
	s_waitcnt lgkmcnt(0)
	v_mfma_f32_32x32x16_bf16 v[18:33], v[38:41], v[58:61], 0
	v_max_f32_e32 v2, 0, v2
	v_max_f32_e32 v3, 0, v3
	v_fma_f32 v2, v174, v2, 0
	v_max_f32_e32 v4, 0, v4
	v_fmac_f32_e32 v2, v173, v3
	v_max_f32_e32 v5, 0, v5
	v_fmac_f32_e32 v2, v172, v4
	v_max_f32_e32 v6, 0, v6
	v_fmac_f32_e32 v2, v171, v5
	v_max_f32_e32 v7, 0, v7
	v_mfma_f32_32x32x16_bf16 v[18:33], v[46:49], v[54:57], v[18:33]
	v_fmac_f32_e32 v2, v170, v6
	v_max_f32_e32 v8, 0, v8
	v_fmac_f32_e32 v2, v169, v7
	v_max_f32_e32 v9, 0, v9
	v_fmac_f32_e32 v2, v168, v8
	v_max_f32_e32 v10, 0, v10
	v_fmac_f32_e32 v2, v167, v9
	v_max_f32_e32 v11, 0, v11
	v_fmac_f32_e32 v2, v166, v10
	v_max_f32_e32 v12, 0, v12
	v_mfma_f32_32x32x16_bf16 v[18:33], v[34:37], v[50:53], v[18:33]
	v_fmac_f32_e32 v2, v165, v11
	v_max_f32_e32 v13, 0, v13
	v_fmac_f32_e32 v2, v164, v12
	v_max_f32_e32 v14, 0, v14
	v_fmac_f32_e32 v2, v163, v13
	v_fmac_f32_e32 v2, v162, v14
	v_max_f32_e32 v3, 0, v15
	v_fmac_f32_e32 v2, v161, v3
	v_max_f32_e32 v3, 0, v16
	v_fmac_f32_e32 v2, v160, v3
	v_mfma_f32_32x32x16_bf16 v[18:33], v[42:45], v[62:65], v[18:33]
	ds_read_b128 v[58:61], v74 offset:8192
	ds_read_b128 v[54:57], v75 offset:8192
	ds_read_b128 v[50:53], v76 offset:8192
	ds_read_b128 v[62:65], v77 offset:8192
	v_max_f32_e32 v3, 0, v17
	v_fmac_f32_e32 v2, v89, v3
	v_cmp_gt_i32_e32 vcc, 0, v2
	v_not_b32_e32 v3, v2
	v_or_b32_e32 v4, 0x80000000, v2
	v_cndmask_b32_e32 v2, v4, v3, vcc
	v_cmp_le_u32_e32 vcc, v97, v87
	s_nop 1
	v_cndmask_b32_e32 v176, 0, v2, vcc
.LBB0_413:
	v_mov_b32_e32 v180, 0
	s_cmp_gt_u32 s2, 0x7f
	s_cbranch_scc0 .Lidxp_e4
	s_waitcnt lgkmcnt(0)
	v_mfma_f32_32x32x16_bf16 v[2:17], v[38:41], v[58:61], 0
	v_max_f32_e32 v18, 0, v18
	v_max_f32_e32 v19, 0, v19
	v_fma_f32 v18, v174, v18, 0
	v_max_f32_e32 v20, 0, v20
	v_fmac_f32_e32 v18, v173, v19
	v_max_f32_e32 v21, 0, v21
	v_fmac_f32_e32 v18, v172, v20
	v_max_f32_e32 v22, 0, v22
	v_fmac_f32_e32 v18, v171, v21
	v_max_f32_e32 v23, 0, v23
	v_mfma_f32_32x32x16_bf16 v[2:17], v[46:49], v[54:57], v[2:17]
	v_fmac_f32_e32 v18, v170, v22
	v_max_f32_e32 v24, 0, v24
	v_fmac_f32_e32 v18, v169, v23
	v_max_f32_e32 v25, 0, v25
	v_fmac_f32_e32 v18, v168, v24
	v_max_f32_e32 v26, 0, v26
	v_fmac_f32_e32 v18, v167, v25
	v_max_f32_e32 v27, 0, v27
	v_fmac_f32_e32 v18, v166, v26
	v_max_f32_e32 v28, 0, v28
	v_mfma_f32_32x32x16_bf16 v[2:17], v[34:37], v[50:53], v[2:17]
	v_fmac_f32_e32 v18, v165, v27
	v_max_f32_e32 v29, 0, v29
	v_fmac_f32_e32 v18, v164, v28
	v_max_f32_e32 v30, 0, v30
	v_fmac_f32_e32 v18, v163, v29
	v_fmac_f32_e32 v18, v162, v30
	v_max_f32_e32 v19, 0, v31
	v_fmac_f32_e32 v18, v161, v19
	v_max_f32_e32 v19, 0, v32
	v_fmac_f32_e32 v18, v160, v19
	v_mfma_f32_32x32x16_bf16 v[2:17], v[42:45], v[62:65], v[2:17]
	ds_read_b128 v[58:61], v74 offset:12288
	ds_read_b128 v[54:57], v75 offset:12288
	ds_read_b128 v[50:53], v76 offset:12288
	ds_read_b128 v[62:65], v77 offset:12288
	v_max_f32_e32 v19, 0, v33
	v_fmac_f32_e32 v18, v89, v19
	v_cmp_gt_i32_e32 vcc, 0, v18
	v_not_b32_e32 v19, v18
	v_or_b32_e32 v20, 0x80000000, v18
	v_cndmask_b32_e32 v18, v20, v19, vcc
	v_cmp_le_u32_e32 vcc, v98, v87
	s_nop 1
	v_cndmask_b32_e32 v179, 0, v18, vcc
.LBB0_417:
	v_mov_b32_e32 v181, 0
	s_cmp_gt_u32 s2, 0x9f
	s_cbranch_scc0 .Lidxp_e5
	s_waitcnt lgkmcnt(0)
	v_mfma_f32_32x32x16_bf16 v[18:33], v[38:41], v[58:61], 0
	v_max_f32_e32 v2, 0, v2
	v_max_f32_e32 v3, 0, v3
	v_fma_f32 v2, v174, v2, 0
	v_max_f32_e32 v4, 0, v4
	v_fmac_f32_e32 v2, v173, v3
	v_max_f32_e32 v5, 0, v5
	v_fmac_f32_e32 v2, v172, v4
	v_max_f32_e32 v6, 0, v6
	v_fmac_f32_e32 v2, v171, v5
	v_max_f32_e32 v7, 0, v7
	v_mfma_f32_32x32x16_bf16 v[18:33], v[46:49], v[54:57], v[18:33]
	v_fmac_f32_e32 v2, v170, v6
	v_max_f32_e32 v8, 0, v8
	v_fmac_f32_e32 v2, v169, v7
	v_max_f32_e32 v9, 0, v9
	v_fmac_f32_e32 v2, v168, v8
	v_max_f32_e32 v10, 0, v10
	v_fmac_f32_e32 v2, v167, v9
	v_max_f32_e32 v11, 0, v11
	v_fmac_f32_e32 v2, v166, v10
	v_max_f32_e32 v12, 0, v12
	v_mfma_f32_32x32x16_bf16 v[18:33], v[34:37], v[50:53], v[18:33]
	v_fmac_f32_e32 v2, v165, v11
	v_max_f32_e32 v13, 0, v13
	v_fmac_f32_e32 v2, v164, v12
	v_max_f32_e32 v14, 0, v14
	v_fmac_f32_e32 v2, v163, v13
	v_fmac_f32_e32 v2, v162, v14
	v_max_f32_e32 v3, 0, v15
	v_fmac_f32_e32 v2, v161, v3
	v_max_f32_e32 v3, 0, v16
	v_fmac_f32_e32 v2, v160, v3
	v_mfma_f32_32x32x16_bf16 v[18:33], v[42:45], v[62:65], v[18:33]
	ds_read_b128 v[58:61], v74 offset:16384
	ds_read_b128 v[54:57], v75 offset:16384
	ds_read_b128 v[50:53], v76 offset:16384
	ds_read_b128 v[62:65], v77 offset:16384
	v_max_f32_e32 v3, 0, v17
	v_fmac_f32_e32 v2, v89, v3
	v_cmp_gt_i32_e32 vcc, 0, v2
	v_not_b32_e32 v3, v2
	v_or_b32_e32 v4, 0x80000000, v2
	v_cndmask_b32_e32 v2, v4, v3, vcc
	v_cmp_le_u32_e32 vcc, v99, v87
	s_nop 1
	v_cndmask_b32_e32 v180, 0, v2, vcc
.LBB0_421:
	v_mov_b32_e32 v182, 0
	s_cmp_gt_u32 s2, 0xbf
	s_cbranch_scc0 .Lidxp_e6
	s_waitcnt lgkmcnt(0)
	v_mfma_f32_32x32x16_bf16 v[2:17], v[38:41], v[58:61], 0
	v_max_f32_e32 v18, 0, v18
	v_max_f32_e32 v19, 0, v19
	v_fma_f32 v18, v174, v18, 0
	v_max_f32_e32 v20, 0, v20
	v_fmac_f32_e32 v18, v173, v19
	v_max_f32_e32 v21, 0, v21
	v_fmac_f32_e32 v18, v172, v20
	v_max_f32_e32 v22, 0, v22
	v_fmac_f32_e32 v18, v171, v21
	v_max_f32_e32 v23, 0, v23
	v_mfma_f32_32x32x16_bf16 v[2:17], v[46:49], v[54:57], v[2:17]
	v_fmac_f32_e32 v18, v170, v22
	v_max_f32_e32 v24, 0, v24
	v_fmac_f32_e32 v18, v169, v23
	v_max_f32_e32 v25, 0, v25
	v_fmac_f32_e32 v18, v168, v24
	v_max_f32_e32 v26, 0, v26
	v_fmac_f32_e32 v18, v167, v25
	v_max_f32_e32 v27, 0, v27
	v_fmac_f32_e32 v18, v166, v26
	v_max_f32_e32 v28, 0, v28
	v_mfma_f32_32x32x16_bf16 v[2:17], v[34:37], v[50:53], v[2:17]
	v_fmac_f32_e32 v18, v165, v27
	v_max_f32_e32 v29, 0, v29
	v_fmac_f32_e32 v18, v164, v28
	v_max_f32_e32 v30, 0, v30
	v_fmac_f32_e32 v18, v163, v29
	v_fmac_f32_e32 v18, v162, v30
	v_max_f32_e32 v19, 0, v31
	v_fmac_f32_e32 v18, v161, v19
	v_max_f32_e32 v19, 0, v32
	v_fmac_f32_e32 v18, v160, v19
	v_mfma_f32_32x32x16_bf16 v[2:17], v[42:45], v[62:65], v[2:17]
	ds_read_b128 v[58:61], v74 offset:20480
	ds_read_b128 v[54:57], v75 offset:20480
	ds_read_b128 v[50:53], v76 offset:20480
	ds_read_b128 v[62:65], v77 offset:20480
	v_max_f32_e32 v19, 0, v33
	v_fmac_f32_e32 v18, v89, v19
	v_cmp_gt_i32_e32 vcc, 0, v18
	v_not_b32_e32 v19, v18
	v_or_b32_e32 v20, 0x80000000, v18
	v_cndmask_b32_e32 v18, v20, v19, vcc
	v_cmp_le_u32_e32 vcc, v100, v87
	s_nop 1
	v_cndmask_b32_e32 v181, 0, v18, vcc
.LBB0_425:
	v_mov_b32_e32 v183, 0
	s_cmp_gt_u32 s2, 0xdf
	s_cbranch_scc0 .Lidxp_e7
	s_waitcnt lgkmcnt(0)
	v_mfma_f32_32x32x16_bf16 v[18:33], v[38:41], v[58:61], 0
	v_max_f32_e32 v2, 0, v2
	v_max_f32_e32 v3, 0, v3
	v_fma_f32 v2, v174, v2, 0
	v_max_f32_e32 v4, 0, v4
	v_fmac_f32_e32 v2, v173, v3
	v_max_f32_e32 v5, 0, v5
	v_fmac_f32_e32 v2, v172, v4
	v_max_f32_e32 v6, 0, v6
	v_fmac_f32_e32 v2, v171, v5
	v_max_f32_e32 v7, 0, v7
	v_mfma_f32_32x32x16_bf16 v[18:33], v[46:49], v[54:57], v[18:33]
	v_fmac_f32_e32 v2, v170, v6
	v_max_f32_e32 v8, 0, v8
	v_fmac_f32_e32 v2, v169, v7
	v_max_f32_e32 v9, 0, v9
	v_fmac_f32_e32 v2, v168, v8
	v_max_f32_e32 v10, 0, v10
	v_fmac_f32_e32 v2, v167, v9
	v_max_f32_e32 v11, 0, v11
	v_fmac_f32_e32 v2, v166, v10
	v_max_f32_e32 v12, 0, v12
	v_mfma_f32_32x32x16_bf16 v[18:33], v[34:37], v[50:53], v[18:33]
	v_fmac_f32_e32 v2, v165, v11
	v_max_f32_e32 v13, 0, v13
	v_fmac_f32_e32 v2, v164, v12
	v_max_f32_e32 v14, 0, v14
	v_fmac_f32_e32 v2, v163, v13
	v_fmac_f32_e32 v2, v162, v14
	v_max_f32_e32 v3, 0, v15
	v_fmac_f32_e32 v2, v161, v3
	v_max_f32_e32 v3, 0, v16
	v_fmac_f32_e32 v2, v160, v3
	v_mfma_f32_32x32x16_bf16 v[18:33], v[42:45], v[62:65], v[18:33]
	ds_read_b128 v[58:61], v74 offset:24576
	ds_read_b128 v[54:57], v75 offset:24576
	ds_read_b128 v[50:53], v76 offset:24576
	ds_read_b128 v[62:65], v77 offset:24576
	v_max_f32_e32 v3, 0, v17
	v_fmac_f32_e32 v2, v89, v3
	v_cmp_gt_i32_e32 vcc, 0, v2
	v_not_b32_e32 v3, v2
	v_or_b32_e32 v4, 0x80000000, v2
	v_cndmask_b32_e32 v2, v4, v3, vcc
	v_cmp_le_u32_e32 vcc, v101, v87
	s_nop 1
	v_cndmask_b32_e32 v182, 0, v2, vcc
.LBB0_429:
	v_cmp_gt_u32_e64 s[74:75], s33, v177
	v_mov_b32_e32 v184, 0
	s_cmp_gt_u32 s2, 0xff
	s_cbranch_scc0 .Lidxp_e8
	s_waitcnt lgkmcnt(0)
	v_mfma_f32_32x32x16_bf16 v[2:17], v[38:41], v[58:61], 0
	v_max_f32_e32 v18, 0, v18
	v_max_f32_e32 v19, 0, v19
	v_fma_f32 v18, v174, v18, 0
	v_max_f32_e32 v20, 0, v20
	v_fmac_f32_e32 v18, v173, v19
	v_max_f32_e32 v21, 0, v21
	v_fmac_f32_e32 v18, v172, v20
	v_max_f32_e32 v22, 0, v22
	v_fmac_f32_e32 v18, v171, v21
	v_max_f32_e32 v23, 0, v23
	v_mfma_f32_32x32x16_bf16 v[2:17], v[46:49], v[54:57], v[2:17]
	v_fmac_f32_e32 v18, v170, v22
	v_max_f32_e32 v24, 0, v24
	v_fmac_f32_e32 v18, v169, v23
	v_max_f32_e32 v25, 0, v25
	v_fmac_f32_e32 v18, v168, v24
	v_max_f32_e32 v26, 0, v26
	v_fmac_f32_e32 v18, v167, v25
	v_max_f32_e32 v27, 0, v27
	v_fmac_f32_e32 v18, v166, v26
	v_max_f32_e32 v28, 0, v28
	v_mfma_f32_32x32x16_bf16 v[2:17], v[34:37], v[50:53], v[2:17]
	v_fmac_f32_e32 v18, v165, v27
	v_max_f32_e32 v29, 0, v29
	v_fmac_f32_e32 v18, v164, v28
	v_max_f32_e32 v30, 0, v30
	v_fmac_f32_e32 v18, v163, v29
	v_fmac_f32_e32 v18, v162, v30
	v_max_f32_e32 v19, 0, v31
	v_fmac_f32_e32 v18, v161, v19
	v_max_f32_e32 v19, 0, v32
	v_fmac_f32_e32 v18, v160, v19
	v_mfma_f32_32x32x16_bf16 v[2:17], v[42:45], v[62:65], v[2:17]
	ds_read_b128 v[58:61], v74 offset:28672
	ds_read_b128 v[54:57], v75 offset:28672
	ds_read_b128 v[50:53], v76 offset:28672
	ds_read_b128 v[62:65], v77 offset:28672
	v_max_f32_e32 v19, 0, v33
	v_fmac_f32_e32 v18, v89, v19
	v_cmp_gt_i32_e32 vcc, 0, v18
	v_not_b32_e32 v19, v18
	v_or_b32_e32 v20, 0x80000000, v18
	v_cndmask_b32_e32 v18, v20, v19, vcc
	v_cmp_le_u32_e32 vcc, v102, v87
	s_nop 1
	v_cndmask_b32_e32 v183, 0, v18, vcc

.Lidxd_s1:
	v_mfma_f32_32x32x16_bf16 v[18:33], v[38:41], v[58:61], 0
	v_max_f32_e32 v2, 0, v2
	v_max_f32_e32 v3, 0, v3
	v_fma_f32 v2, v174, v2, 0
	v_max_f32_e32 v4, 0, v4
	v_fmac_f32_e32 v2, v173, v3
	v_max_f32_e32 v5, 0, v5
	v_fmac_f32_e32 v2, v172, v4
	v_max_f32_e32 v6, 0, v6
	v_fmac_f32_e32 v2, v171, v5
	v_max_f32_e32 v7, 0, v7
	v_mfma_f32_32x32x16_bf16 v[18:33], v[46:49], v[54:57], v[18:33]
	v_fmac_f32_e32 v2, v170, v6
	v_max_f32_e32 v8, 0, v8
	v_fmac_f32_e32 v2, v169, v7
	v_max_f32_e32 v9, 0, v9
	v_fmac_f32_e32 v2, v168, v8
	v_max_f32_e32 v10, 0, v10
	v_fmac_f32_e32 v2, v167, v9
	v_max_f32_e32 v11, 0, v11
	v_fmac_f32_e32 v2, v166, v10
	v_max_f32_e32 v12, 0, v12
	v_mfma_f32_32x32x16_bf16 v[18:33], v[34:37], v[50:53], v[18:33]
	v_fmac_f32_e32 v2, v165, v11
	v_max_f32_e32 v13, 0, v13
	v_fmac_f32_e32 v2, v164, v12
	v_max_f32_e32 v14, 0, v14
	v_fmac_f32_e32 v2, v163, v13
	v_fmac_f32_e32 v2, v162, v14
	v_max_f32_e32 v3, 0, v15
	v_fmac_f32_e32 v2, v161, v3
	v_max_f32_e32 v3, 0, v16
	v_fmac_f32_e32 v2, v160, v3
	v_mfma_f32_32x32x16_bf16 v[18:33], v[42:45], v[62:65], v[18:33]
	ds_read_b128 v[58:61], v74 offset:32768
	ds_read_b128 v[54:57], v75 offset:32768
	ds_read_b128 v[50:53], v76 offset:32768
	ds_read_b128 v[62:65], v77 offset:32768
	v_max_f32_e32 v3, 0, v17
	v_fmac_f32_e32 v2, v89, v3
	v_cmp_gt_i32_e32 vcc, 0, v2
	v_not_b32_e32 v3, v2
	v_or_b32_e32 v4, 0x80000000, v2
	v_cndmask_b32_e32 v2, v4, v3, vcc
	v_cmp_le_u32_e32 vcc, v103, v87
	s_nop 1
	v_cndmask_b32_e32 v184, 0, v2, vcc
.LBB0_437:
	v_mov_b32_e32 v186, 0
	s_cmp_gt_u32 s2, 0x13f
	s_cbranch_scc0 .Lidxp_e10
	s_waitcnt lgkmcnt(0)
	v_mfma_f32_32x32x16_bf16 v[2:17], v[38:41], v[58:61], 0
	v_max_f32_e32 v18, 0, v18
	v_max_f32_e32 v19, 0, v19
	v_fma_f32 v18, v174, v18, 0
	v_max_f32_e32 v20, 0, v20
	v_fmac_f32_e32 v18, v173, v19
	v_max_f32_e32 v21, 0, v21
	v_fmac_f32_e32 v18, v172, v20
	v_max_f32_e32 v22, 0, v22
	v_fmac_f32_e32 v18, v171, v21
	v_max_f32_e32 v23, 0, v23
	v_mfma_f32_32x32x16_bf16 v[2:17], v[46:49], v[54:57], v[2:17]
	v_fmac_f32_e32 v18, v170, v22
	v_max_f32_e32 v24, 0, v24
	v_fmac_f32_e32 v18, v169, v23
	v_max_f32_e32 v25, 0, v25
	v_fmac_f32_e32 v18, v168, v24
	v_max_f32_e32 v26, 0, v26
	v_fmac_f32_e32 v18, v167, v25
	v_max_f32_e32 v27, 0, v27
	v_fmac_f32_e32 v18, v166, v26
	v_max_f32_e32 v28, 0, v28
	v_mfma_f32_32x32x16_bf16 v[2:17], v[34:37], v[50:53], v[2:17]
	v_fmac_f32_e32 v18, v165, v27
	v_max_f32_e32 v29, 0, v29
	v_fmac_f32_e32 v18, v164, v28
	v_max_f32_e32 v30, 0, v30
	v_fmac_f32_e32 v18, v163, v29
	v_fmac_f32_e32 v18, v162, v30
	v_max_f32_e32 v19, 0, v31
	v_fmac_f32_e32 v18, v161, v19
	v_max_f32_e32 v19, 0, v32
	v_fmac_f32_e32 v18, v160, v19
	v_mfma_f32_32x32x16_bf16 v[2:17], v[42:45], v[62:65], v[2:17]
	ds_read_b128 v[58:61], v74 offset:36864
	ds_read_b128 v[54:57], v75 offset:36864
	ds_read_b128 v[50:53], v76 offset:36864
	ds_read_b128 v[62:65], v77 offset:36864
	v_max_f32_e32 v19, 0, v33
	v_fmac_f32_e32 v18, v89, v19
	v_cmp_gt_i32_e32 vcc, 0, v18
	v_not_b32_e32 v19, v18
	v_or_b32_e32 v20, 0x80000000, v18
	v_cndmask_b32_e32 v18, v20, v19, vcc
	v_cmp_le_u32_e32 vcc, v104, v87
	s_nop 1
	v_cndmask_b32_e32 v185, 0, v18, vcc
.LBB0_441:
	v_mov_b32_e32 v187, 0
	s_cmp_gt_u32 s2, 0x15f
	s_cbranch_scc0 .Lidxp_e11
	s_waitcnt lgkmcnt(0)
	v_mfma_f32_32x32x16_bf16 v[18:33], v[38:41], v[58:61], 0
	v_max_f32_e32 v2, 0, v2
	v_max_f32_e32 v3, 0, v3
	v_fma_f32 v2, v174, v2, 0
	v_max_f32_e32 v4, 0, v4
	v_fmac_f32_e32 v2, v173, v3
	v_max_f32_e32 v5, 0, v5
	v_fmac_f32_e32 v2, v172, v4
	v_max_f32_e32 v6, 0, v6
	v_fmac_f32_e32 v2, v171, v5
	v_max_f32_e32 v7, 0, v7
	v_mfma_f32_32x32x16_bf16 v[18:33], v[46:49], v[54:57], v[18:33]
	v_fmac_f32_e32 v2, v170, v6
	v_max_f32_e32 v8, 0, v8
	v_fmac_f32_e32 v2, v169, v7
	v_max_f32_e32 v9, 0, v9
	v_fmac_f32_e32 v2, v168, v8
	v_max_f32_e32 v10, 0, v10
	v_fmac_f32_e32 v2, v167, v9
	v_max_f32_e32 v11, 0, v11
	v_fmac_f32_e32 v2, v166, v10
	v_max_f32_e32 v12, 0, v12
	v_mfma_f32_32x32x16_bf16 v[18:33], v[34:37], v[50:53], v[18:33]
	v_fmac_f32_e32 v2, v165, v11
	v_max_f32_e32 v13, 0, v13
	v_fmac_f32_e32 v2, v164, v12
	v_max_f32_e32 v14, 0, v14
	v_fmac_f32_e32 v2, v163, v13
	v_fmac_f32_e32 v2, v162, v14
	v_max_f32_e32 v3, 0, v15
	v_fmac_f32_e32 v2, v161, v3
	v_max_f32_e32 v3, 0, v16
	v_fmac_f32_e32 v2, v160, v3
	v_mfma_f32_32x32x16_bf16 v[18:33], v[42:45], v[62:65], v[18:33]
	ds_read_b128 v[58:61], v74 offset:40960
	ds_read_b128 v[54:57], v75 offset:40960
	ds_read_b128 v[50:53], v76 offset:40960
	ds_read_b128 v[62:65], v77 offset:40960
	v_max_f32_e32 v3, 0, v17
	v_fmac_f32_e32 v2, v89, v3
	v_cmp_gt_i32_e32 vcc, 0, v2
	v_not_b32_e32 v3, v2
	v_or_b32_e32 v4, 0x80000000, v2
	v_cndmask_b32_e32 v2, v4, v3, vcc
	v_cmp_le_u32_e32 vcc, v105, v87
	s_nop 1
	v_cndmask_b32_e32 v186, 0, v2, vcc
.LBB0_445:
	v_mov_b32_e32 v188, 0
	s_cmp_gt_u32 s2, 0x17f
	s_cbranch_scc0 .Lidxp_e12
	s_waitcnt lgkmcnt(0)
	v_mfma_f32_32x32x16_bf16 v[2:17], v[38:41], v[58:61], 0
	v_max_f32_e32 v18, 0, v18
	v_max_f32_e32 v19, 0, v19
	v_fma_f32 v18, v174, v18, 0
	v_max_f32_e32 v20, 0, v20
	v_fmac_f32_e32 v18, v173, v19
	v_max_f32_e32 v21, 0, v21
	v_fmac_f32_e32 v18, v172, v20
	v_max_f32_e32 v22, 0, v22
	v_fmac_f32_e32 v18, v171, v21
	v_max_f32_e32 v23, 0, v23
	v_mfma_f32_32x32x16_bf16 v[2:17], v[46:49], v[54:57], v[2:17]
	v_fmac_f32_e32 v18, v170, v22
	v_max_f32_e32 v24, 0, v24
	v_fmac_f32_e32 v18, v169, v23
	v_max_f32_e32 v25, 0, v25
	v_fmac_f32_e32 v18, v168, v24
	v_max_f32_e32 v26, 0, v26
	v_fmac_f32_e32 v18, v167, v25
	v_max_f32_e32 v27, 0, v27
	v_fmac_f32_e32 v18, v166, v26
	v_max_f32_e32 v28, 0, v28
	v_mfma_f32_32x32x16_bf16 v[2:17], v[34:37], v[50:53], v[2:17]
	v_fmac_f32_e32 v18, v165, v27
	v_max_f32_e32 v29, 0, v29
	v_fmac_f32_e32 v18, v164, v28
	v_max_f32_e32 v30, 0, v30
	v_fmac_f32_e32 v18, v163, v29
	v_fmac_f32_e32 v18, v162, v30
	v_max_f32_e32 v19, 0, v31
	v_fmac_f32_e32 v18, v161, v19
	v_max_f32_e32 v19, 0, v32
	v_fmac_f32_e32 v18, v160, v19
	v_mfma_f32_32x32x16_bf16 v[2:17], v[42:45], v[62:65], v[2:17]
	ds_read_b128 v[58:61], v74 offset:45056
	ds_read_b128 v[54:57], v75 offset:45056
	ds_read_b128 v[50:53], v76 offset:45056
	ds_read_b128 v[62:65], v77 offset:45056
	v_max_f32_e32 v19, 0, v33
	v_fmac_f32_e32 v18, v89, v19
	v_cmp_gt_i32_e32 vcc, 0, v18
	v_not_b32_e32 v19, v18
	v_or_b32_e32 v20, 0x80000000, v18
	v_cndmask_b32_e32 v18, v20, v19, vcc
	v_cmp_le_u32_e32 vcc, v106, v87
	s_nop 1
	v_cndmask_b32_e32 v187, 0, v18, vcc
.LBB0_449:
	v_mov_b32_e32 v189, 0
	s_cmp_gt_u32 s2, 0x19f
	s_cbranch_scc0 .Lidxp_e13
	s_waitcnt lgkmcnt(0)
	v_mfma_f32_32x32x16_bf16 v[18:33], v[38:41], v[58:61], 0
	v_max_f32_e32 v2, 0, v2
	v_max_f32_e32 v3, 0, v3
	v_fma_f32 v2, v174, v2, 0
	v_max_f32_e32 v4, 0, v4
	v_fmac_f32_e32 v2, v173, v3
	v_max_f32_e32 v5, 0, v5
	v_fmac_f32_e32 v2, v172, v4
	v_max_f32_e32 v6, 0, v6
	v_fmac_f32_e32 v2, v171, v5
	v_max_f32_e32 v7, 0, v7
	v_mfma_f32_32x32x16_bf16 v[18:33], v[46:49], v[54:57], v[18:33]
	v_fmac_f32_e32 v2, v170, v6
	v_max_f32_e32 v8, 0, v8
	v_fmac_f32_e32 v2, v169, v7
	v_max_f32_e32 v9, 0, v9
	v_fmac_f32_e32 v2, v168, v8
	v_max_f32_e32 v10, 0, v10
	v_fmac_f32_e32 v2, v167, v9
	v_max_f32_e32 v11, 0, v11
	v_fmac_f32_e32 v2, v166, v10
	v_max_f32_e32 v12, 0, v12
	v_mfma_f32_32x32x16_bf16 v[18:33], v[34:37], v[50:53], v[18:33]
	v_fmac_f32_e32 v2, v165, v11
	v_max_f32_e32 v13, 0, v13
	v_fmac_f32_e32 v2, v164, v12
	v_max_f32_e32 v14, 0, v14
	v_fmac_f32_e32 v2, v163, v13
	v_fmac_f32_e32 v2, v162, v14
	v_max_f32_e32 v3, 0, v15
	v_fmac_f32_e32 v2, v161, v3
	v_max_f32_e32 v3, 0, v16
	v_fmac_f32_e32 v2, v160, v3
	v_mfma_f32_32x32x16_bf16 v[18:33], v[42:45], v[62:65], v[18:33]
	ds_read_b128 v[58:61], v74 offset:49152
	ds_read_b128 v[54:57], v75 offset:49152
	ds_read_b128 v[50:53], v76 offset:49152
	ds_read_b128 v[62:65], v77 offset:49152
	v_max_f32_e32 v3, 0, v17
	v_fmac_f32_e32 v2, v89, v3
	v_cmp_gt_i32_e32 vcc, 0, v2
	v_not_b32_e32 v3, v2
	v_or_b32_e32 v4, 0x80000000, v2
	v_cndmask_b32_e32 v2, v4, v3, vcc
	v_cmp_le_u32_e32 vcc, v107, v87
	s_nop 1
	v_cndmask_b32_e32 v188, 0, v2, vcc
.LBB0_453:
	v_mov_b32_e32 v190, 0
	s_cmp_gt_u32 s2, 0x1bf
	s_cbranch_scc0 .Lidxp_e14
	s_waitcnt lgkmcnt(0)
	v_mfma_f32_32x32x16_bf16 v[2:17], v[38:41], v[58:61], 0
	v_max_f32_e32 v18, 0, v18
	v_max_f32_e32 v19, 0, v19
	v_fma_f32 v18, v174, v18, 0
	v_max_f32_e32 v20, 0, v20
	v_fmac_f32_e32 v18, v173, v19
	v_max_f32_e32 v21, 0, v21
	v_fmac_f32_e32 v18, v172, v20
	v_max_f32_e32 v22, 0, v22
	v_fmac_f32_e32 v18, v171, v21
	v_max_f32_e32 v23, 0, v23
	v_mfma_f32_32x32x16_bf16 v[2:17], v[46:49], v[54:57], v[2:17]
	v_fmac_f32_e32 v18, v170, v22
	v_max_f32_e32 v24, 0, v24
	v_fmac_f32_e32 v18, v169, v23
	v_max_f32_e32 v25, 0, v25
	v_fmac_f32_e32 v18, v168, v24
	v_max_f32_e32 v26, 0, v26
	v_fmac_f32_e32 v18, v167, v25
	v_max_f32_e32 v27, 0, v27
	v_fmac_f32_e32 v18, v166, v26
	v_max_f32_e32 v28, 0, v28
	v_mfma_f32_32x32x16_bf16 v[2:17], v[34:37], v[50:53], v[2:17]
	v_fmac_f32_e32 v18, v165, v27
	v_max_f32_e32 v29, 0, v29
	v_fmac_f32_e32 v18, v164, v28
	v_max_f32_e32 v30, 0, v30
	v_fmac_f32_e32 v18, v163, v29
	v_fmac_f32_e32 v18, v162, v30
	v_max_f32_e32 v19, 0, v31
	v_fmac_f32_e32 v18, v161, v19
	v_max_f32_e32 v19, 0, v32
	v_fmac_f32_e32 v18, v160, v19
	v_mfma_f32_32x32x16_bf16 v[2:17], v[42:45], v[62:65], v[2:17]
	ds_read_b128 v[58:61], v74 offset:53248
	ds_read_b128 v[54:57], v75 offset:53248
	ds_read_b128 v[50:53], v76 offset:53248
	ds_read_b128 v[62:65], v77 offset:53248
	v_max_f32_e32 v19, 0, v33
	v_fmac_f32_e32 v18, v89, v19
	v_cmp_gt_i32_e32 vcc, 0, v18
	v_not_b32_e32 v19, v18
	v_or_b32_e32 v20, 0x80000000, v18
	v_cndmask_b32_e32 v18, v20, v19, vcc
	v_cmp_le_u32_e32 vcc, v108, v87
	s_nop 1
	v_cndmask_b32_e32 v189, 0, v18, vcc
.LBB0_457:
	v_mov_b32_e32 v191, 0
	s_cmp_gt_u32 s2, 0x1df
	s_cbranch_scc0 .Lidxp_e15
	s_waitcnt lgkmcnt(0)
	v_mfma_f32_32x32x16_bf16 v[18:33], v[38:41], v[58:61], 0
	v_max_f32_e32 v2, 0, v2
	v_max_f32_e32 v3, 0, v3
	v_fma_f32 v2, v174, v2, 0
	v_max_f32_e32 v4, 0, v4
	v_fmac_f32_e32 v2, v173, v3
	v_max_f32_e32 v5, 0, v5
	v_fmac_f32_e32 v2, v172, v4
	v_max_f32_e32 v6, 0, v6
	v_fmac_f32_e32 v2, v171, v5
	v_max_f32_e32 v7, 0, v7
	v_mfma_f32_32x32x16_bf16 v[18:33], v[46:49], v[54:57], v[18:33]
	v_fmac_f32_e32 v2, v170, v6
	v_max_f32_e32 v8, 0, v8
	v_fmac_f32_e32 v2, v169, v7
	v_max_f32_e32 v9, 0, v9
	v_fmac_f32_e32 v2, v168, v8
	v_max_f32_e32 v10, 0, v10
	v_fmac_f32_e32 v2, v167, v9
	v_max_f32_e32 v11, 0, v11
	v_fmac_f32_e32 v2, v166, v10
	v_max_f32_e32 v12, 0, v12
	v_mfma_f32_32x32x16_bf16 v[18:33], v[34:37], v[50:53], v[18:33]
	v_fmac_f32_e32 v2, v165, v11
	v_max_f32_e32 v13, 0, v13
	v_fmac_f32_e32 v2, v164, v12
	v_max_f32_e32 v14, 0, v14
	v_fmac_f32_e32 v2, v163, v13
	v_fmac_f32_e32 v2, v162, v14
	v_max_f32_e32 v3, 0, v15
	v_fmac_f32_e32 v2, v161, v3
	v_max_f32_e32 v3, 0, v16
	v_fmac_f32_e32 v2, v160, v3
	v_mfma_f32_32x32x16_bf16 v[18:33], v[42:45], v[62:65], v[18:33]
	ds_read_b128 v[58:61], v74 offset:57344
	ds_read_b128 v[54:57], v75 offset:57344
	ds_read_b128 v[50:53], v76 offset:57344
	ds_read_b128 v[62:65], v77 offset:57344
	v_max_f32_e32 v3, 0, v17
	v_fmac_f32_e32 v2, v89, v3
	v_cmp_gt_i32_e32 vcc, 0, v2
	v_not_b32_e32 v3, v2
	v_or_b32_e32 v4, 0x80000000, v2
	v_cndmask_b32_e32 v2, v4, v3, vcc
	v_cmp_le_u32_e32 vcc, v109, v87
	s_nop 1
	v_cndmask_b32_e32 v190, 0, v2, vcc
.LBB0_461:
	v_mov_b32_e32 v192, 0
	s_cmp_gt_u32 s2, 0x1ff
	s_cbranch_scc0 .Lidxp_e16
	s_waitcnt lgkmcnt(0)
	v_mfma_f32_32x32x16_bf16 v[2:17], v[38:41], v[58:61], 0
	v_max_f32_e32 v18, 0, v18
	v_max_f32_e32 v19, 0, v19
	v_fma_f32 v18, v174, v18, 0
	v_max_f32_e32 v20, 0, v20
	v_fmac_f32_e32 v18, v173, v19
	v_max_f32_e32 v21, 0, v21
	v_fmac_f32_e32 v18, v172, v20
	v_max_f32_e32 v22, 0, v22
	v_fmac_f32_e32 v18, v171, v21
	v_max_f32_e32 v23, 0, v23
	v_mfma_f32_32x32x16_bf16 v[2:17], v[46:49], v[54:57], v[2:17]
	v_fmac_f32_e32 v18, v170, v22
	v_max_f32_e32 v24, 0, v24
	v_fmac_f32_e32 v18, v169, v23
	v_max_f32_e32 v25, 0, v25
	v_fmac_f32_e32 v18, v168, v24
	v_max_f32_e32 v26, 0, v26
	v_fmac_f32_e32 v18, v167, v25
	v_max_f32_e32 v27, 0, v27
	v_fmac_f32_e32 v18, v166, v26
	v_max_f32_e32 v28, 0, v28
	v_mfma_f32_32x32x16_bf16 v[2:17], v[34:37], v[50:53], v[2:17]
	v_fmac_f32_e32 v18, v165, v27
	v_max_f32_e32 v29, 0, v29
	v_fmac_f32_e32 v18, v164, v28
	v_max_f32_e32 v30, 0, v30
	v_fmac_f32_e32 v18, v163, v29
	v_fmac_f32_e32 v18, v162, v30
	v_max_f32_e32 v19, 0, v31
	v_fmac_f32_e32 v18, v161, v19
	v_max_f32_e32 v19, 0, v32
	v_fmac_f32_e32 v18, v160, v19
	v_mfma_f32_32x32x16_bf16 v[2:17], v[42:45], v[62:65], v[2:17]
	ds_read_b128 v[58:61], v74 offset:61440
	ds_read_b128 v[54:57], v75 offset:61440
	ds_read_b128 v[50:53], v76 offset:61440
	ds_read_b128 v[62:65], v77 offset:61440
	v_max_f32_e32 v19, 0, v33
	v_fmac_f32_e32 v18, v89, v19
	v_cmp_gt_i32_e32 vcc, 0, v18
	v_not_b32_e32 v19, v18
	v_or_b32_e32 v20, 0x80000000, v18
	v_cndmask_b32_e32 v18, v20, v19, vcc
	v_cmp_le_u32_e32 vcc, v110, v87
	s_nop 1
	v_cndmask_b32_e32 v191, 0, v18, vcc

.Lidxd_s2:
	v_mfma_f32_32x32x16_bf16 v[18:33], v[38:41], v[58:61], 0
	v_max_f32_e32 v2, 0, v2
	v_max_f32_e32 v3, 0, v3
	v_fma_f32 v2, v174, v2, 0
	v_max_f32_e32 v4, 0, v4
	v_fmac_f32_e32 v2, v173, v3
	v_max_f32_e32 v5, 0, v5
	v_fmac_f32_e32 v2, v172, v4
	v_max_f32_e32 v6, 0, v6
	v_fmac_f32_e32 v2, v171, v5
	v_max_f32_e32 v7, 0, v7
	v_mfma_f32_32x32x16_bf16 v[18:33], v[46:49], v[54:57], v[18:33]
	v_fmac_f32_e32 v2, v170, v6
	v_max_f32_e32 v8, 0, v8
	v_fmac_f32_e32 v2, v169, v7
	v_max_f32_e32 v9, 0, v9
	v_fmac_f32_e32 v2, v168, v8
	v_max_f32_e32 v10, 0, v10
	v_fmac_f32_e32 v2, v167, v9
	v_max_f32_e32 v11, 0, v11
	v_fmac_f32_e32 v2, v166, v10
	v_max_f32_e32 v12, 0, v12
	v_mfma_f32_32x32x16_bf16 v[18:33], v[34:37], v[50:53], v[18:33]
	v_fmac_f32_e32 v2, v165, v11
	v_max_f32_e32 v13, 0, v13
	v_fmac_f32_e32 v2, v164, v12
	v_max_f32_e32 v14, 0, v14
	v_fmac_f32_e32 v2, v163, v13
	v_fmac_f32_e32 v2, v162, v14
	v_max_f32_e32 v3, 0, v15
	v_fmac_f32_e32 v2, v161, v3
	v_max_f32_e32 v3, 0, v16
	v_fmac_f32_e32 v2, v160, v3
	v_mfma_f32_32x32x16_bf16 v[18:33], v[42:45], v[62:65], v[18:33]
	ds_read_b128 v[58:61], v74 offset:0
	ds_read_b128 v[54:57], v75 offset:0
	ds_read_b128 v[50:53], v76 offset:0
	ds_read_b128 v[62:65], v77 offset:0
	v_max_f32_e32 v3, 0, v17
	v_fmac_f32_e32 v2, v89, v3
	v_cmp_gt_i32_e32 vcc, 0, v2
	v_not_b32_e32 v3, v2
	v_or_b32_e32 v4, 0x80000000, v2
	v_cndmask_b32_e32 v2, v4, v3, vcc
	v_cmp_le_u32_e32 vcc, v111, v87
	s_nop 1
	v_cndmask_b32_e32 v192, 0, v2, vcc
.LBB0_469:
	v_mov_b32_e32 v194, 0
	s_cmp_gt_u32 s2, 0x23f
	s_cbranch_scc0 .Lidxp_e18
	s_waitcnt lgkmcnt(0)
	v_mfma_f32_32x32x16_bf16 v[2:17], v[38:41], v[58:61], 0
	v_max_f32_e32 v18, 0, v18
	v_max_f32_e32 v19, 0, v19
	v_fma_f32 v18, v174, v18, 0
	v_max_f32_e32 v20, 0, v20
	v_fmac_f32_e32 v18, v173, v19
	v_max_f32_e32 v21, 0, v21
	v_fmac_f32_e32 v18, v172, v20
	v_max_f32_e32 v22, 0, v22
	v_fmac_f32_e32 v18, v171, v21
	v_max_f32_e32 v23, 0, v23
	v_mfma_f32_32x32x16_bf16 v[2:17], v[46:49], v[54:57], v[2:17]
	v_fmac_f32_e32 v18, v170, v22
	v_max_f32_e32 v24, 0, v24
	v_fmac_f32_e32 v18, v169, v23
	v_max_f32_e32 v25, 0, v25
	v_fmac_f32_e32 v18, v168, v24
	v_max_f32_e32 v26, 0, v26
	v_fmac_f32_e32 v18, v167, v25
	v_max_f32_e32 v27, 0, v27
	v_fmac_f32_e32 v18, v166, v26
	v_max_f32_e32 v28, 0, v28
	v_mfma_f32_32x32x16_bf16 v[2:17], v[34:37], v[50:53], v[2:17]
	v_fmac_f32_e32 v18, v165, v27
	v_max_f32_e32 v29, 0, v29
	v_fmac_f32_e32 v18, v164, v28
	v_max_f32_e32 v30, 0, v30
	v_fmac_f32_e32 v18, v163, v29
	v_fmac_f32_e32 v18, v162, v30
	v_max_f32_e32 v19, 0, v31
	v_fmac_f32_e32 v18, v161, v19
	v_max_f32_e32 v19, 0, v32
	v_fmac_f32_e32 v18, v160, v19
	v_mfma_f32_32x32x16_bf16 v[2:17], v[42:45], v[62:65], v[2:17]
	ds_read_b128 v[58:61], v74 offset:4096
	ds_read_b128 v[54:57], v75 offset:4096
	ds_read_b128 v[50:53], v76 offset:4096
	ds_read_b128 v[62:65], v77 offset:4096
	v_max_f32_e32 v19, 0, v33
	v_fmac_f32_e32 v18, v89, v19
	v_cmp_gt_i32_e32 vcc, 0, v18
	v_not_b32_e32 v19, v18
	v_or_b32_e32 v20, 0x80000000, v18
	v_cndmask_b32_e32 v18, v20, v19, vcc
	v_cmp_le_u32_e32 vcc, v112, v87
	s_nop 1
	v_cndmask_b32_e32 v193, 0, v18, vcc
.LBB0_473:
	v_mov_b32_e32 v195, 0
	s_cmp_gt_u32 s2, 0x25f
	s_cbranch_scc0 .Lidxp_e19
	s_waitcnt lgkmcnt(0)
	v_mfma_f32_32x32x16_bf16 v[18:33], v[38:41], v[58:61], 0
	v_max_f32_e32 v2, 0, v2
	v_max_f32_e32 v3, 0, v3
	v_fma_f32 v2, v174, v2, 0
	v_max_f32_e32 v4, 0, v4
	v_fmac_f32_e32 v2, v173, v3
	v_max_f32_e32 v5, 0, v5
	v_fmac_f32_e32 v2, v172, v4
	v_max_f32_e32 v6, 0, v6
	v_fmac_f32_e32 v2, v171, v5
	v_max_f32_e32 v7, 0, v7
	v_mfma_f32_32x32x16_bf16 v[18:33], v[46:49], v[54:57], v[18:33]
	v_fmac_f32_e32 v2, v170, v6
	v_max_f32_e32 v8, 0, v8
	v_fmac_f32_e32 v2, v169, v7
	v_max_f32_e32 v9, 0, v9
	v_fmac_f32_e32 v2, v168, v8
	v_max_f32_e32 v10, 0, v10
	v_fmac_f32_e32 v2, v167, v9
	v_max_f32_e32 v11, 0, v11
	v_fmac_f32_e32 v2, v166, v10
	v_max_f32_e32 v12, 0, v12
	v_mfma_f32_32x32x16_bf16 v[18:33], v[34:37], v[50:53], v[18:33]
	v_fmac_f32_e32 v2, v165, v11
	v_max_f32_e32 v13, 0, v13
	v_fmac_f32_e32 v2, v164, v12
	v_max_f32_e32 v14, 0, v14
	v_fmac_f32_e32 v2, v163, v13
	v_fmac_f32_e32 v2, v162, v14
	v_max_f32_e32 v3, 0, v15
	v_fmac_f32_e32 v2, v161, v3
	v_max_f32_e32 v3, 0, v16
	v_fmac_f32_e32 v2, v160, v3
	v_mfma_f32_32x32x16_bf16 v[18:33], v[42:45], v[62:65], v[18:33]
	ds_read_b128 v[58:61], v74 offset:8192
	ds_read_b128 v[54:57], v75 offset:8192
	ds_read_b128 v[50:53], v76 offset:8192
	ds_read_b128 v[62:65], v77 offset:8192
	v_max_f32_e32 v3, 0, v17
	v_fmac_f32_e32 v2, v89, v3
	v_cmp_gt_i32_e32 vcc, 0, v2
	v_not_b32_e32 v3, v2
	v_or_b32_e32 v4, 0x80000000, v2
	v_cndmask_b32_e32 v2, v4, v3, vcc
	v_cmp_le_u32_e32 vcc, v113, v87
	s_nop 1
	v_cndmask_b32_e32 v194, 0, v2, vcc
.LBB0_477:
	v_mov_b32_e32 v196, 0
	s_cmp_gt_u32 s2, 0x27f
	s_cbranch_scc0 .Lidxp_e20
	s_waitcnt lgkmcnt(0)
	v_mfma_f32_32x32x16_bf16 v[2:17], v[38:41], v[58:61], 0
	v_max_f32_e32 v18, 0, v18
	v_max_f32_e32 v19, 0, v19
	v_fma_f32 v18, v174, v18, 0
	v_max_f32_e32 v20, 0, v20
	v_fmac_f32_e32 v18, v173, v19
	v_max_f32_e32 v21, 0, v21
	v_fmac_f32_e32 v18, v172, v20
	v_max_f32_e32 v22, 0, v22
	v_fmac_f32_e32 v18, v171, v21
	v_max_f32_e32 v23, 0, v23
	v_mfma_f32_32x32x16_bf16 v[2:17], v[46:49], v[54:57], v[2:17]
	v_fmac_f32_e32 v18, v170, v22
	v_max_f32_e32 v24, 0, v24
	v_fmac_f32_e32 v18, v169, v23
	v_max_f32_e32 v25, 0, v25
	v_fmac_f32_e32 v18, v168, v24
	v_max_f32_e32 v26, 0, v26
	v_fmac_f32_e32 v18, v167, v25
	v_max_f32_e32 v27, 0, v27
	v_fmac_f32_e32 v18, v166, v26
	v_max_f32_e32 v28, 0, v28
	v_mfma_f32_32x32x16_bf16 v[2:17], v[34:37], v[50:53], v[2:17]
	v_fmac_f32_e32 v18, v165, v27
	v_max_f32_e32 v29, 0, v29
	v_fmac_f32_e32 v18, v164, v28
	v_max_f32_e32 v30, 0, v30
	v_fmac_f32_e32 v18, v163, v29
	v_fmac_f32_e32 v18, v162, v30
	v_max_f32_e32 v19, 0, v31
	v_fmac_f32_e32 v18, v161, v19
	v_max_f32_e32 v19, 0, v32
	v_fmac_f32_e32 v18, v160, v19
	v_mfma_f32_32x32x16_bf16 v[2:17], v[42:45], v[62:65], v[2:17]
	ds_read_b128 v[58:61], v74 offset:12288
	ds_read_b128 v[54:57], v75 offset:12288
	ds_read_b128 v[50:53], v76 offset:12288
	ds_read_b128 v[62:65], v77 offset:12288
	v_max_f32_e32 v19, 0, v33
	v_fmac_f32_e32 v18, v89, v19
	v_cmp_gt_i32_e32 vcc, 0, v18
	v_not_b32_e32 v19, v18
	v_or_b32_e32 v20, 0x80000000, v18
	v_cndmask_b32_e32 v18, v20, v19, vcc
	v_cmp_le_u32_e32 vcc, v114, v87
	s_nop 1
	v_cndmask_b32_e32 v195, 0, v18, vcc
.LBB0_481:
	v_mov_b32_e32 v197, 0
	s_cmp_gt_u32 s2, 0x29f
	s_cbranch_scc0 .Lidxp_e21
	s_waitcnt lgkmcnt(0)
	v_mfma_f32_32x32x16_bf16 v[18:33], v[38:41], v[58:61], 0
	v_max_f32_e32 v2, 0, v2
	v_max_f32_e32 v3, 0, v3
	v_fma_f32 v2, v174, v2, 0
	v_max_f32_e32 v4, 0, v4
	v_fmac_f32_e32 v2, v173, v3
	v_max_f32_e32 v5, 0, v5
	v_fmac_f32_e32 v2, v172, v4
	v_max_f32_e32 v6, 0, v6
	v_fmac_f32_e32 v2, v171, v5
	v_max_f32_e32 v7, 0, v7
	v_mfma_f32_32x32x16_bf16 v[18:33], v[46:49], v[54:57], v[18:33]
	v_fmac_f32_e32 v2, v170, v6
	v_max_f32_e32 v8, 0, v8
	v_fmac_f32_e32 v2, v169, v7
	v_max_f32_e32 v9, 0, v9
	v_fmac_f32_e32 v2, v168, v8
	v_max_f32_e32 v10, 0, v10
	v_fmac_f32_e32 v2, v167, v9
	v_max_f32_e32 v11, 0, v11
	v_fmac_f32_e32 v2, v166, v10
	v_max_f32_e32 v12, 0, v12
	v_mfma_f32_32x32x16_bf16 v[18:33], v[34:37], v[50:53], v[18:33]
	v_fmac_f32_e32 v2, v165, v11
	v_max_f32_e32 v13, 0, v13
	v_fmac_f32_e32 v2, v164, v12
	v_max_f32_e32 v14, 0, v14
	v_fmac_f32_e32 v2, v163, v13
	v_fmac_f32_e32 v2, v162, v14
	v_max_f32_e32 v3, 0, v15
	v_fmac_f32_e32 v2, v161, v3
	v_max_f32_e32 v3, 0, v16
	v_fmac_f32_e32 v2, v160, v3
	v_mfma_f32_32x32x16_bf16 v[18:33], v[42:45], v[62:65], v[18:33]
	ds_read_b128 v[58:61], v74 offset:16384
	ds_read_b128 v[54:57], v75 offset:16384
	ds_read_b128 v[50:53], v76 offset:16384
	ds_read_b128 v[62:65], v77 offset:16384
	v_max_f32_e32 v3, 0, v17
	v_fmac_f32_e32 v2, v89, v3
	v_cmp_gt_i32_e32 vcc, 0, v2
	v_not_b32_e32 v3, v2
	v_or_b32_e32 v4, 0x80000000, v2
	v_cndmask_b32_e32 v2, v4, v3, vcc
	v_cmp_le_u32_e32 vcc, v115, v87
	s_nop 1
	v_cndmask_b32_e32 v196, 0, v2, vcc
.LBB0_485:
	v_mov_b32_e32 v216, 0
	s_cmp_gt_u32 s2, 0x2bf
	s_cbranch_scc0 .Lidxp_e22
	s_waitcnt lgkmcnt(0)
	v_mfma_f32_32x32x16_bf16 v[2:17], v[38:41], v[58:61], 0
	v_max_f32_e32 v18, 0, v18
	v_max_f32_e32 v19, 0, v19
	v_fma_f32 v18, v174, v18, 0
	v_max_f32_e32 v20, 0, v20
	v_fmac_f32_e32 v18, v173, v19
	v_max_f32_e32 v21, 0, v21
	v_fmac_f32_e32 v18, v172, v20
	v_max_f32_e32 v22, 0, v22
	v_fmac_f32_e32 v18, v171, v21
	v_max_f32_e32 v23, 0, v23
	v_mfma_f32_32x32x16_bf16 v[2:17], v[46:49], v[54:57], v[2:17]
	v_fmac_f32_e32 v18, v170, v22
	v_max_f32_e32 v24, 0, v24
	v_fmac_f32_e32 v18, v169, v23
	v_max_f32_e32 v25, 0, v25
	v_fmac_f32_e32 v18, v168, v24
	v_max_f32_e32 v26, 0, v26
	v_fmac_f32_e32 v18, v167, v25
	v_max_f32_e32 v27, 0, v27
	v_fmac_f32_e32 v18, v166, v26
	v_max_f32_e32 v28, 0, v28
	v_mfma_f32_32x32x16_bf16 v[2:17], v[34:37], v[50:53], v[2:17]
	v_fmac_f32_e32 v18, v165, v27
	v_max_f32_e32 v29, 0, v29
	v_fmac_f32_e32 v18, v164, v28
	v_max_f32_e32 v30, 0, v30
	v_fmac_f32_e32 v18, v163, v29
	v_fmac_f32_e32 v18, v162, v30
	v_max_f32_e32 v19, 0, v31
	v_fmac_f32_e32 v18, v161, v19
	v_max_f32_e32 v19, 0, v32
	v_fmac_f32_e32 v18, v160, v19
	v_mfma_f32_32x32x16_bf16 v[2:17], v[42:45], v[62:65], v[2:17]
	ds_read_b128 v[58:61], v74 offset:20480
	ds_read_b128 v[54:57], v75 offset:20480
	ds_read_b128 v[50:53], v76 offset:20480
	ds_read_b128 v[62:65], v77 offset:20480
	v_max_f32_e32 v19, 0, v33
	v_fmac_f32_e32 v18, v89, v19
	v_cmp_gt_i32_e32 vcc, 0, v18
	v_not_b32_e32 v19, v18
	v_or_b32_e32 v20, 0x80000000, v18
	v_cndmask_b32_e32 v18, v20, v19, vcc
	v_cmp_le_u32_e32 vcc, v116, v87
	s_nop 1
	v_cndmask_b32_e32 v197, 0, v18, vcc
.LBB0_489:
	v_mov_b32_e32 v217, 0
	s_cmp_gt_u32 s2, 0x2df
	s_cbranch_scc0 .Lidxp_e23
	s_waitcnt lgkmcnt(0)
	v_mfma_f32_32x32x16_bf16 v[18:33], v[38:41], v[58:61], 0
	v_max_f32_e32 v2, 0, v2
	v_max_f32_e32 v3, 0, v3
	v_fma_f32 v2, v174, v2, 0
	v_max_f32_e32 v4, 0, v4
	v_fmac_f32_e32 v2, v173, v3
	v_max_f32_e32 v5, 0, v5
	v_fmac_f32_e32 v2, v172, v4
	v_max_f32_e32 v6, 0, v6
	v_fmac_f32_e32 v2, v171, v5
	v_max_f32_e32 v7, 0, v7
	v_mfma_f32_32x32x16_bf16 v[18:33], v[46:49], v[54:57], v[18:33]
	v_fmac_f32_e32 v2, v170, v6
	v_max_f32_e32 v8, 0, v8
	v_fmac_f32_e32 v2, v169, v7
	v_max_f32_e32 v9, 0, v9
	v_fmac_f32_e32 v2, v168, v8
	v_max_f32_e32 v10, 0, v10
	v_fmac_f32_e32 v2, v167, v9
	v_max_f32_e32 v11, 0, v11
	v_fmac_f32_e32 v2, v166, v10
	v_max_f32_e32 v12, 0, v12
	v_mfma_f32_32x32x16_bf16 v[18:33], v[34:37], v[50:53], v[18:33]
	v_fmac_f32_e32 v2, v165, v11
	v_max_f32_e32 v13, 0, v13
	v_fmac_f32_e32 v2, v164, v12
	v_max_f32_e32 v14, 0, v14
	v_fmac_f32_e32 v2, v163, v13
	v_fmac_f32_e32 v2, v162, v14
	v_max_f32_e32 v3, 0, v15
	v_fmac_f32_e32 v2, v161, v3
	v_max_f32_e32 v3, 0, v16
	v_fmac_f32_e32 v2, v160, v3
	v_mfma_f32_32x32x16_bf16 v[18:33], v[42:45], v[62:65], v[18:33]
	ds_read_b128 v[58:61], v74 offset:24576
	ds_read_b128 v[54:57], v75 offset:24576
	ds_read_b128 v[50:53], v76 offset:24576
	ds_read_b128 v[62:65], v77 offset:24576
	v_max_f32_e32 v3, 0, v17
	v_fmac_f32_e32 v2, v89, v3
	v_cmp_gt_i32_e32 vcc, 0, v2
	v_not_b32_e32 v3, v2
	v_or_b32_e32 v4, 0x80000000, v2
	v_cndmask_b32_e32 v2, v4, v3, vcc
	v_cmp_le_u32_e32 vcc, v117, v87
	s_nop 1
	v_cndmask_b32_e32 v216, 0, v2, vcc
.LBB0_493:
	v_mov_b32_e32 v218, 0
	s_cmp_gt_u32 s2, 0x2ff
	s_cbranch_scc0 .Lidxp_e24
	s_waitcnt lgkmcnt(0)
	v_mfma_f32_32x32x16_bf16 v[2:17], v[38:41], v[58:61], 0
	v_max_f32_e32 v18, 0, v18
	v_max_f32_e32 v19, 0, v19
	v_fma_f32 v18, v174, v18, 0
	v_max_f32_e32 v20, 0, v20
	v_fmac_f32_e32 v18, v173, v19
	v_max_f32_e32 v21, 0, v21
	v_fmac_f32_e32 v18, v172, v20
	v_max_f32_e32 v22, 0, v22
	v_fmac_f32_e32 v18, v171, v21
	v_max_f32_e32 v23, 0, v23
	v_mfma_f32_32x32x16_bf16 v[2:17], v[46:49], v[54:57], v[2:17]
	v_fmac_f32_e32 v18, v170, v22
	v_max_f32_e32 v24, 0, v24
	v_fmac_f32_e32 v18, v169, v23
	v_max_f32_e32 v25, 0, v25
	v_fmac_f32_e32 v18, v168, v24
	v_max_f32_e32 v26, 0, v26
	v_fmac_f32_e32 v18, v167, v25
	v_max_f32_e32 v27, 0, v27
	v_fmac_f32_e32 v18, v166, v26
	v_max_f32_e32 v28, 0, v28
	v_mfma_f32_32x32x16_bf16 v[2:17], v[34:37], v[50:53], v[2:17]
	v_fmac_f32_e32 v18, v165, v27
	v_max_f32_e32 v29, 0, v29
	v_fmac_f32_e32 v18, v164, v28
	v_max_f32_e32 v30, 0, v30
	v_fmac_f32_e32 v18, v163, v29
	v_fmac_f32_e32 v18, v162, v30
	v_max_f32_e32 v19, 0, v31
	v_fmac_f32_e32 v18, v161, v19
	v_max_f32_e32 v19, 0, v32
	v_fmac_f32_e32 v18, v160, v19
	v_mfma_f32_32x32x16_bf16 v[2:17], v[42:45], v[62:65], v[2:17]
	ds_read_b128 v[58:61], v74 offset:28672
	ds_read_b128 v[54:57], v75 offset:28672
	ds_read_b128 v[50:53], v76 offset:28672
	ds_read_b128 v[62:65], v77 offset:28672
	v_max_f32_e32 v19, 0, v33
	v_fmac_f32_e32 v18, v89, v19
	v_cmp_gt_i32_e32 vcc, 0, v18
	v_not_b32_e32 v19, v18
	v_or_b32_e32 v20, 0x80000000, v18
	v_cndmask_b32_e32 v18, v20, v19, vcc
	v_cmp_le_u32_e32 vcc, v118, v87
	s_nop 1
	v_cndmask_b32_e32 v217, 0, v18, vcc

.Lidxd_s3:
	v_mfma_f32_32x32x16_bf16 v[18:33], v[38:41], v[58:61], 0
	v_max_f32_e32 v2, 0, v2
	v_max_f32_e32 v3, 0, v3
	v_fma_f32 v2, v174, v2, 0
	v_max_f32_e32 v4, 0, v4
	v_fmac_f32_e32 v2, v173, v3
	v_max_f32_e32 v5, 0, v5
	v_fmac_f32_e32 v2, v172, v4
	v_max_f32_e32 v6, 0, v6
	v_fmac_f32_e32 v2, v171, v5
	v_max_f32_e32 v7, 0, v7
	v_mfma_f32_32x32x16_bf16 v[18:33], v[46:49], v[54:57], v[18:33]
	v_fmac_f32_e32 v2, v170, v6
	v_max_f32_e32 v8, 0, v8
	v_fmac_f32_e32 v2, v169, v7
	v_max_f32_e32 v9, 0, v9
	v_fmac_f32_e32 v2, v168, v8
	v_max_f32_e32 v10, 0, v10
	v_fmac_f32_e32 v2, v167, v9
	v_max_f32_e32 v11, 0, v11
	v_fmac_f32_e32 v2, v166, v10
	v_max_f32_e32 v12, 0, v12
	v_mfma_f32_32x32x16_bf16 v[18:33], v[34:37], v[50:53], v[18:33]
	v_fmac_f32_e32 v2, v165, v11
	v_max_f32_e32 v13, 0, v13
	v_fmac_f32_e32 v2, v164, v12
	v_max_f32_e32 v14, 0, v14
	v_fmac_f32_e32 v2, v163, v13
	v_fmac_f32_e32 v2, v162, v14
	v_max_f32_e32 v3, 0, v15
	v_fmac_f32_e32 v2, v161, v3
	v_max_f32_e32 v3, 0, v16
	v_fmac_f32_e32 v2, v160, v3
	v_mfma_f32_32x32x16_bf16 v[18:33], v[42:45], v[62:65], v[18:33]
	ds_read_b128 v[58:61], v74 offset:32768
	ds_read_b128 v[54:57], v75 offset:32768
	ds_read_b128 v[50:53], v76 offset:32768
	ds_read_b128 v[62:65], v77 offset:32768
	v_max_f32_e32 v3, 0, v17
	v_fmac_f32_e32 v2, v89, v3
	v_cmp_gt_i32_e32 vcc, 0, v2
	v_not_b32_e32 v3, v2
	v_or_b32_e32 v4, 0x80000000, v2
	v_cndmask_b32_e32 v2, v4, v3, vcc
	v_cmp_le_u32_e32 vcc, v119, v87
	s_nop 1
	v_cndmask_b32_e32 v218, 0, v2, vcc
.LBB0_501:
	v_mov_b32_e32 v220, 0
	s_cmp_gt_u32 s2, 0x33f
	s_cbranch_scc0 .Lidxp_e26
	s_waitcnt lgkmcnt(0)
	v_mfma_f32_32x32x16_bf16 v[2:17], v[38:41], v[58:61], 0
	v_max_f32_e32 v18, 0, v18
	v_max_f32_e32 v19, 0, v19
	v_fma_f32 v18, v174, v18, 0
	v_max_f32_e32 v20, 0, v20
	v_fmac_f32_e32 v18, v173, v19
	v_max_f32_e32 v21, 0, v21
	v_fmac_f32_e32 v18, v172, v20
	v_max_f32_e32 v22, 0, v22
	v_fmac_f32_e32 v18, v171, v21
	v_max_f32_e32 v23, 0, v23
	v_mfma_f32_32x32x16_bf16 v[2:17], v[46:49], v[54:57], v[2:17]
	v_fmac_f32_e32 v18, v170, v22
	v_max_f32_e32 v24, 0, v24
	v_fmac_f32_e32 v18, v169, v23
	v_max_f32_e32 v25, 0, v25
	v_fmac_f32_e32 v18, v168, v24
	v_max_f32_e32 v26, 0, v26
	v_fmac_f32_e32 v18, v167, v25
	v_max_f32_e32 v27, 0, v27
	v_fmac_f32_e32 v18, v166, v26
	v_max_f32_e32 v28, 0, v28
	v_mfma_f32_32x32x16_bf16 v[2:17], v[34:37], v[50:53], v[2:17]
	v_fmac_f32_e32 v18, v165, v27
	v_max_f32_e32 v29, 0, v29
	v_fmac_f32_e32 v18, v164, v28
	v_max_f32_e32 v30, 0, v30
	v_fmac_f32_e32 v18, v163, v29
	v_fmac_f32_e32 v18, v162, v30
	v_max_f32_e32 v19, 0, v31
	v_fmac_f32_e32 v18, v161, v19
	v_max_f32_e32 v19, 0, v32
	v_fmac_f32_e32 v18, v160, v19
	v_mfma_f32_32x32x16_bf16 v[2:17], v[42:45], v[62:65], v[2:17]
	ds_read_b128 v[58:61], v74 offset:36864
	ds_read_b128 v[54:57], v75 offset:36864
	ds_read_b128 v[50:53], v76 offset:36864
	ds_read_b128 v[62:65], v77 offset:36864
	v_max_f32_e32 v19, 0, v33
	v_fmac_f32_e32 v18, v89, v19
	v_cmp_gt_i32_e32 vcc, 0, v18
	v_not_b32_e32 v19, v18
	v_or_b32_e32 v20, 0x80000000, v18
	v_cndmask_b32_e32 v18, v20, v19, vcc
	v_cmp_le_u32_e32 vcc, v120, v87
	s_nop 1
	v_cndmask_b32_e32 v219, 0, v18, vcc
.LBB0_505:
	v_mov_b32_e32 v221, 0
	s_cmp_gt_u32 s2, 0x35f
	s_cbranch_scc0 .Lidxp_e27
	s_waitcnt lgkmcnt(0)
	v_mfma_f32_32x32x16_bf16 v[18:33], v[38:41], v[58:61], 0
	v_max_f32_e32 v2, 0, v2
	v_max_f32_e32 v3, 0, v3
	v_fma_f32 v2, v174, v2, 0
	v_max_f32_e32 v4, 0, v4
	v_fmac_f32_e32 v2, v173, v3
	v_max_f32_e32 v5, 0, v5
	v_fmac_f32_e32 v2, v172, v4
	v_max_f32_e32 v6, 0, v6
	v_fmac_f32_e32 v2, v171, v5
	v_max_f32_e32 v7, 0, v7
	v_mfma_f32_32x32x16_bf16 v[18:33], v[46:49], v[54:57], v[18:33]
	v_fmac_f32_e32 v2, v170, v6
	v_max_f32_e32 v8, 0, v8
	v_fmac_f32_e32 v2, v169, v7
	v_max_f32_e32 v9, 0, v9
	v_fmac_f32_e32 v2, v168, v8
	v_max_f32_e32 v10, 0, v10
	v_fmac_f32_e32 v2, v167, v9
	v_max_f32_e32 v11, 0, v11
	v_fmac_f32_e32 v2, v166, v10
	v_max_f32_e32 v12, 0, v12
	v_mfma_f32_32x32x16_bf16 v[18:33], v[34:37], v[50:53], v[18:33]
	v_fmac_f32_e32 v2, v165, v11
	v_max_f32_e32 v13, 0, v13
	v_fmac_f32_e32 v2, v164, v12
	v_max_f32_e32 v14, 0, v14
	v_fmac_f32_e32 v2, v163, v13
	v_fmac_f32_e32 v2, v162, v14
	v_max_f32_e32 v3, 0, v15
	v_fmac_f32_e32 v2, v161, v3
	v_max_f32_e32 v3, 0, v16
	v_fmac_f32_e32 v2, v160, v3
	v_mfma_f32_32x32x16_bf16 v[18:33], v[42:45], v[62:65], v[18:33]
	ds_read_b128 v[58:61], v74 offset:40960
	ds_read_b128 v[54:57], v75 offset:40960
	ds_read_b128 v[50:53], v76 offset:40960
	ds_read_b128 v[62:65], v77 offset:40960
	v_max_f32_e32 v3, 0, v17
	v_fmac_f32_e32 v2, v89, v3
	v_cmp_gt_i32_e32 vcc, 0, v2
	v_not_b32_e32 v3, v2
	v_or_b32_e32 v4, 0x80000000, v2
	v_cndmask_b32_e32 v2, v4, v3, vcc
	v_cmp_le_u32_e32 vcc, v121, v87
	s_nop 1
	v_cndmask_b32_e32 v220, 0, v2, vcc
.LBB0_509:
	v_mov_b32_e32 v222, 0
	s_cmp_gt_u32 s2, 0x37f
	s_cbranch_scc0 .Lidxp_e28
	s_waitcnt lgkmcnt(0)
	v_mfma_f32_32x32x16_bf16 v[2:17], v[38:41], v[58:61], 0
	v_max_f32_e32 v18, 0, v18
	v_max_f32_e32 v19, 0, v19
	v_fma_f32 v18, v174, v18, 0
	v_max_f32_e32 v20, 0, v20
	v_fmac_f32_e32 v18, v173, v19
	v_max_f32_e32 v21, 0, v21
	v_fmac_f32_e32 v18, v172, v20
	v_max_f32_e32 v22, 0, v22
	v_fmac_f32_e32 v18, v171, v21
	v_max_f32_e32 v23, 0, v23
	v_mfma_f32_32x32x16_bf16 v[2:17], v[46:49], v[54:57], v[2:17]
	v_fmac_f32_e32 v18, v170, v22
	v_max_f32_e32 v24, 0, v24
	v_fmac_f32_e32 v18, v169, v23
	v_max_f32_e32 v25, 0, v25
	v_fmac_f32_e32 v18, v168, v24
	v_max_f32_e32 v26, 0, v26
	v_fmac_f32_e32 v18, v167, v25
	v_max_f32_e32 v27, 0, v27
	v_fmac_f32_e32 v18, v166, v26
	v_max_f32_e32 v28, 0, v28
	v_mfma_f32_32x32x16_bf16 v[2:17], v[34:37], v[50:53], v[2:17]
	v_fmac_f32_e32 v18, v165, v27
	v_max_f32_e32 v29, 0, v29
	v_fmac_f32_e32 v18, v164, v28
	v_max_f32_e32 v30, 0, v30
	v_fmac_f32_e32 v18, v163, v29
	v_fmac_f32_e32 v18, v162, v30
	v_max_f32_e32 v19, 0, v31
	v_fmac_f32_e32 v18, v161, v19
	v_max_f32_e32 v19, 0, v32
	v_fmac_f32_e32 v18, v160, v19
	v_mfma_f32_32x32x16_bf16 v[2:17], v[42:45], v[62:65], v[2:17]
	ds_read_b128 v[58:61], v74 offset:45056
	ds_read_b128 v[54:57], v75 offset:45056
	ds_read_b128 v[50:53], v76 offset:45056
	ds_read_b128 v[62:65], v77 offset:45056
	v_max_f32_e32 v19, 0, v33
	v_fmac_f32_e32 v18, v89, v19
	v_cmp_gt_i32_e32 vcc, 0, v18
	v_not_b32_e32 v19, v18
	v_or_b32_e32 v20, 0x80000000, v18
	v_cndmask_b32_e32 v18, v20, v19, vcc
	v_cmp_le_u32_e32 vcc, v122, v87
	s_nop 1
	v_cndmask_b32_e32 v221, 0, v18, vcc
.LBB0_513:
	v_mov_b32_e32 v223, 0
	s_cmp_gt_u32 s2, 0x39f
	s_cbranch_scc0 .Lidxp_e29
	s_waitcnt lgkmcnt(0)
	v_mfma_f32_32x32x16_bf16 v[18:33], v[38:41], v[58:61], 0
	v_max_f32_e32 v2, 0, v2
	v_max_f32_e32 v3, 0, v3
	v_fma_f32 v2, v174, v2, 0
	v_max_f32_e32 v4, 0, v4
	v_fmac_f32_e32 v2, v173, v3
	v_max_f32_e32 v5, 0, v5
	v_fmac_f32_e32 v2, v172, v4
	v_max_f32_e32 v6, 0, v6
	v_fmac_f32_e32 v2, v171, v5
	v_max_f32_e32 v7, 0, v7
	v_mfma_f32_32x32x16_bf16 v[18:33], v[46:49], v[54:57], v[18:33]
	v_fmac_f32_e32 v2, v170, v6
	v_max_f32_e32 v8, 0, v8
	v_fmac_f32_e32 v2, v169, v7
	v_max_f32_e32 v9, 0, v9
	v_fmac_f32_e32 v2, v168, v8
	v_max_f32_e32 v10, 0, v10
	v_fmac_f32_e32 v2, v167, v9
	v_max_f32_e32 v11, 0, v11
	v_fmac_f32_e32 v2, v166, v10
	v_max_f32_e32 v12, 0, v12
	v_mfma_f32_32x32x16_bf16 v[18:33], v[34:37], v[50:53], v[18:33]
	v_fmac_f32_e32 v2, v165, v11
	v_max_f32_e32 v13, 0, v13
	v_fmac_f32_e32 v2, v164, v12
	v_max_f32_e32 v14, 0, v14
	v_fmac_f32_e32 v2, v163, v13
	v_fmac_f32_e32 v2, v162, v14
	v_max_f32_e32 v3, 0, v15
	v_fmac_f32_e32 v2, v161, v3
	v_max_f32_e32 v3, 0, v16
	v_fmac_f32_e32 v2, v160, v3
	v_mfma_f32_32x32x16_bf16 v[18:33], v[42:45], v[62:65], v[18:33]
	ds_read_b128 v[58:61], v74 offset:49152
	ds_read_b128 v[54:57], v75 offset:49152
	ds_read_b128 v[50:53], v76 offset:49152
	ds_read_b128 v[62:65], v77 offset:49152
	v_max_f32_e32 v3, 0, v17
	v_fmac_f32_e32 v2, v89, v3
	v_cmp_gt_i32_e32 vcc, 0, v2
	v_not_b32_e32 v3, v2
	v_or_b32_e32 v4, 0x80000000, v2
	v_cndmask_b32_e32 v2, v4, v3, vcc
	v_cmp_le_u32_e32 vcc, v123, v87
	s_nop 1
	v_cndmask_b32_e32 v222, 0, v2, vcc
.LBB0_517:
	v_mov_b32_e32 v224, 0
	s_cmp_gt_u32 s2, 0x3bf
	s_cbranch_scc0 .Lidxp_e30
	s_waitcnt lgkmcnt(0)
	v_mfma_f32_32x32x16_bf16 v[2:17], v[38:41], v[58:61], 0
	v_max_f32_e32 v18, 0, v18
	v_max_f32_e32 v19, 0, v19
	v_fma_f32 v18, v174, v18, 0
	v_max_f32_e32 v20, 0, v20
	v_fmac_f32_e32 v18, v173, v19
	v_max_f32_e32 v21, 0, v21
	v_fmac_f32_e32 v18, v172, v20
	v_max_f32_e32 v22, 0, v22
	v_fmac_f32_e32 v18, v171, v21
	v_max_f32_e32 v23, 0, v23
	v_mfma_f32_32x32x16_bf16 v[2:17], v[46:49], v[54:57], v[2:17]
	v_fmac_f32_e32 v18, v170, v22
	v_max_f32_e32 v24, 0, v24
	v_fmac_f32_e32 v18, v169, v23
	v_max_f32_e32 v25, 0, v25
	v_fmac_f32_e32 v18, v168, v24
	v_max_f32_e32 v26, 0, v26
	v_fmac_f32_e32 v18, v167, v25
	v_max_f32_e32 v27, 0, v27
	v_fmac_f32_e32 v18, v166, v26
	v_max_f32_e32 v28, 0, v28
	v_mfma_f32_32x32x16_bf16 v[2:17], v[34:37], v[50:53], v[2:17]
	v_fmac_f32_e32 v18, v165, v27
	v_max_f32_e32 v29, 0, v29
	v_fmac_f32_e32 v18, v164, v28
	v_max_f32_e32 v30, 0, v30
	v_fmac_f32_e32 v18, v163, v29
	v_fmac_f32_e32 v18, v162, v30
	v_max_f32_e32 v19, 0, v31
	v_fmac_f32_e32 v18, v161, v19
	v_max_f32_e32 v19, 0, v32
	v_fmac_f32_e32 v18, v160, v19
	v_mfma_f32_32x32x16_bf16 v[2:17], v[42:45], v[62:65], v[2:17]
	ds_read_b128 v[58:61], v74 offset:53248
	ds_read_b128 v[54:57], v75 offset:53248
	ds_read_b128 v[50:53], v76 offset:53248
	ds_read_b128 v[62:65], v77 offset:53248
	v_max_f32_e32 v19, 0, v33
	v_fmac_f32_e32 v18, v89, v19
	v_cmp_gt_i32_e32 vcc, 0, v18
	v_not_b32_e32 v19, v18
	v_or_b32_e32 v20, 0x80000000, v18
	v_cndmask_b32_e32 v18, v20, v19, vcc
	v_cmp_le_u32_e32 vcc, v124, v87
	s_nop 1
	v_cndmask_b32_e32 v223, 0, v18, vcc
.LBB0_521:
	v_mov_b32_e32 v225, 0
	s_cmp_gt_u32 s2, 0x3df
	s_cbranch_scc0 .Lidxp_e31
	s_waitcnt lgkmcnt(0)
	v_mfma_f32_32x32x16_bf16 v[18:33], v[38:41], v[58:61], 0
	v_max_f32_e32 v2, 0, v2
	v_max_f32_e32 v3, 0, v3
	v_fma_f32 v2, v174, v2, 0
	v_max_f32_e32 v4, 0, v4
	v_fmac_f32_e32 v2, v173, v3
	v_max_f32_e32 v5, 0, v5
	v_fmac_f32_e32 v2, v172, v4
	v_max_f32_e32 v6, 0, v6
	v_fmac_f32_e32 v2, v171, v5
	v_max_f32_e32 v7, 0, v7
	v_mfma_f32_32x32x16_bf16 v[18:33], v[46:49], v[54:57], v[18:33]
	v_fmac_f32_e32 v2, v170, v6
	v_max_f32_e32 v8, 0, v8
	v_fmac_f32_e32 v2, v169, v7
	v_max_f32_e32 v9, 0, v9
	v_fmac_f32_e32 v2, v168, v8
	v_max_f32_e32 v10, 0, v10
	v_fmac_f32_e32 v2, v167, v9
	v_max_f32_e32 v11, 0, v11
	v_fmac_f32_e32 v2, v166, v10
	v_max_f32_e32 v12, 0, v12
	v_mfma_f32_32x32x16_bf16 v[18:33], v[34:37], v[50:53], v[18:33]
	v_fmac_f32_e32 v2, v165, v11
	v_max_f32_e32 v13, 0, v13
	v_fmac_f32_e32 v2, v164, v12
	v_max_f32_e32 v14, 0, v14
	v_fmac_f32_e32 v2, v163, v13
	v_fmac_f32_e32 v2, v162, v14
	v_max_f32_e32 v3, 0, v15
	v_fmac_f32_e32 v2, v161, v3
	v_max_f32_e32 v3, 0, v16
	v_fmac_f32_e32 v2, v160, v3
	v_mfma_f32_32x32x16_bf16 v[18:33], v[42:45], v[62:65], v[18:33]
	ds_read_b128 v[58:61], v74 offset:57344
	ds_read_b128 v[54:57], v75 offset:57344
	ds_read_b128 v[50:53], v76 offset:57344
	ds_read_b128 v[62:65], v77 offset:57344
	v_max_f32_e32 v3, 0, v17
	v_fmac_f32_e32 v2, v89, v3
	v_cmp_gt_i32_e32 vcc, 0, v2
	v_not_b32_e32 v3, v2
	v_or_b32_e32 v4, 0x80000000, v2
	v_cndmask_b32_e32 v2, v4, v3, vcc
	v_cmp_le_u32_e32 vcc, v125, v87
	s_nop 1
	v_cndmask_b32_e32 v224, 0, v2, vcc
.LBB0_525:
	v_mov_b32_e32 v226, 0
	s_cmp_gt_u32 s2, 0x3ff
	s_cbranch_scc0 .Lidxp_e32
	s_waitcnt lgkmcnt(0)
	v_mfma_f32_32x32x16_bf16 v[2:17], v[38:41], v[58:61], 0
	v_max_f32_e32 v18, 0, v18
	v_max_f32_e32 v19, 0, v19
	v_fma_f32 v18, v174, v18, 0
	v_max_f32_e32 v20, 0, v20
	v_fmac_f32_e32 v18, v173, v19
	v_max_f32_e32 v21, 0, v21
	v_fmac_f32_e32 v18, v172, v20
	v_max_f32_e32 v22, 0, v22
	v_fmac_f32_e32 v18, v171, v21
	v_max_f32_e32 v23, 0, v23
	v_mfma_f32_32x32x16_bf16 v[2:17], v[46:49], v[54:57], v[2:17]
	v_fmac_f32_e32 v18, v170, v22
	v_max_f32_e32 v24, 0, v24
	v_fmac_f32_e32 v18, v169, v23
	v_max_f32_e32 v25, 0, v25
	v_fmac_f32_e32 v18, v168, v24
	v_max_f32_e32 v26, 0, v26
	v_fmac_f32_e32 v18, v167, v25
	v_max_f32_e32 v27, 0, v27
	v_fmac_f32_e32 v18, v166, v26
	v_max_f32_e32 v28, 0, v28
	v_mfma_f32_32x32x16_bf16 v[2:17], v[34:37], v[50:53], v[2:17]
	v_fmac_f32_e32 v18, v165, v27
	v_max_f32_e32 v29, 0, v29
	v_fmac_f32_e32 v18, v164, v28
	v_max_f32_e32 v30, 0, v30
	v_fmac_f32_e32 v18, v163, v29
	v_fmac_f32_e32 v18, v162, v30
	v_max_f32_e32 v19, 0, v31
	v_fmac_f32_e32 v18, v161, v19
	v_max_f32_e32 v19, 0, v32
	v_fmac_f32_e32 v18, v160, v19
	v_mfma_f32_32x32x16_bf16 v[2:17], v[42:45], v[62:65], v[2:17]
	ds_read_b128 v[58:61], v74 offset:61440
	ds_read_b128 v[54:57], v75 offset:61440
	ds_read_b128 v[50:53], v76 offset:61440
	ds_read_b128 v[62:65], v77 offset:61440
	v_max_f32_e32 v19, 0, v33
	v_fmac_f32_e32 v18, v89, v19
	v_cmp_gt_i32_e32 vcc, 0, v18
	v_not_b32_e32 v19, v18
	v_or_b32_e32 v20, 0x80000000, v18
	v_cndmask_b32_e32 v18, v20, v19, vcc
	v_cmp_le_u32_e32 vcc, v126, v87
	s_nop 1
	v_cndmask_b32_e32 v225, 0, v18, vcc

.Lidxd_s4:
	v_mfma_f32_32x32x16_bf16 v[18:33], v[38:41], v[58:61], 0
	v_max_f32_e32 v2, 0, v2
	v_max_f32_e32 v3, 0, v3
	v_fma_f32 v2, v174, v2, 0
	v_max_f32_e32 v4, 0, v4
	v_fmac_f32_e32 v2, v173, v3
	v_max_f32_e32 v5, 0, v5
	v_fmac_f32_e32 v2, v172, v4
	v_max_f32_e32 v6, 0, v6
	v_fmac_f32_e32 v2, v171, v5
	v_max_f32_e32 v7, 0, v7
	v_mfma_f32_32x32x16_bf16 v[18:33], v[46:49], v[54:57], v[18:33]
	v_fmac_f32_e32 v2, v170, v6
	v_max_f32_e32 v8, 0, v8
	v_fmac_f32_e32 v2, v169, v7
	v_max_f32_e32 v9, 0, v9
	v_fmac_f32_e32 v2, v168, v8
	v_max_f32_e32 v10, 0, v10
	v_fmac_f32_e32 v2, v167, v9
	v_max_f32_e32 v11, 0, v11
	v_fmac_f32_e32 v2, v166, v10
	v_max_f32_e32 v12, 0, v12
	v_mfma_f32_32x32x16_bf16 v[18:33], v[34:37], v[50:53], v[18:33]
	v_fmac_f32_e32 v2, v165, v11
	v_max_f32_e32 v13, 0, v13
	v_fmac_f32_e32 v2, v164, v12
	v_max_f32_e32 v14, 0, v14
	v_fmac_f32_e32 v2, v163, v13
	v_fmac_f32_e32 v2, v162, v14
	v_max_f32_e32 v3, 0, v15
	v_fmac_f32_e32 v2, v161, v3
	v_max_f32_e32 v3, 0, v16
	v_fmac_f32_e32 v2, v160, v3
	v_mfma_f32_32x32x16_bf16 v[18:33], v[42:45], v[62:65], v[18:33]
	ds_read_b128 v[58:61], v74 offset:0
	ds_read_b128 v[54:57], v75 offset:0
	ds_read_b128 v[50:53], v76 offset:0
	ds_read_b128 v[62:65], v77 offset:0
	v_max_f32_e32 v3, 0, v17
	v_fmac_f32_e32 v2, v89, v3
	v_cmp_gt_i32_e32 vcc, 0, v2
	v_not_b32_e32 v3, v2
	v_or_b32_e32 v4, 0x80000000, v2
	v_cndmask_b32_e32 v2, v4, v3, vcc
	v_cmp_le_u32_e32 vcc, v127, v87
	s_nop 1
	v_cndmask_b32_e32 v226, 0, v2, vcc
.LBB0_533:
	v_mov_b32_e32 v228, 0
	s_cmp_gt_u32 s2, 0x43f
	s_cbranch_scc0 .Lidxp_e34
	s_waitcnt lgkmcnt(0)
	v_mfma_f32_32x32x16_bf16 v[2:17], v[38:41], v[58:61], 0
	v_max_f32_e32 v18, 0, v18
	v_max_f32_e32 v19, 0, v19
	v_fma_f32 v18, v174, v18, 0
	v_max_f32_e32 v20, 0, v20
	v_fmac_f32_e32 v18, v173, v19
	v_max_f32_e32 v21, 0, v21
	v_fmac_f32_e32 v18, v172, v20
	v_max_f32_e32 v22, 0, v22
	v_fmac_f32_e32 v18, v171, v21
	v_max_f32_e32 v23, 0, v23
	v_mfma_f32_32x32x16_bf16 v[2:17], v[46:49], v[54:57], v[2:17]
	v_fmac_f32_e32 v18, v170, v22
	v_max_f32_e32 v24, 0, v24
	v_fmac_f32_e32 v18, v169, v23
	v_max_f32_e32 v25, 0, v25
	v_fmac_f32_e32 v18, v168, v24
	v_max_f32_e32 v26, 0, v26
	v_fmac_f32_e32 v18, v167, v25
	v_max_f32_e32 v27, 0, v27
	v_fmac_f32_e32 v18, v166, v26
	v_max_f32_e32 v28, 0, v28
	v_mfma_f32_32x32x16_bf16 v[2:17], v[34:37], v[50:53], v[2:17]
	v_fmac_f32_e32 v18, v165, v27
	v_max_f32_e32 v29, 0, v29
	v_fmac_f32_e32 v18, v164, v28
	v_max_f32_e32 v30, 0, v30
	v_fmac_f32_e32 v18, v163, v29
	v_fmac_f32_e32 v18, v162, v30
	v_max_f32_e32 v19, 0, v31
	v_fmac_f32_e32 v18, v161, v19
	v_max_f32_e32 v19, 0, v32
	v_fmac_f32_e32 v18, v160, v19
	v_mfma_f32_32x32x16_bf16 v[2:17], v[42:45], v[62:65], v[2:17]
	ds_read_b128 v[58:61], v74 offset:4096
	ds_read_b128 v[54:57], v75 offset:4096
	ds_read_b128 v[50:53], v76 offset:4096
	ds_read_b128 v[62:65], v77 offset:4096
	v_max_f32_e32 v19, 0, v33
	v_fmac_f32_e32 v18, v89, v19
	v_cmp_gt_i32_e32 vcc, 0, v18
	v_not_b32_e32 v19, v18
	v_or_b32_e32 v20, 0x80000000, v18
	v_cndmask_b32_e32 v18, v20, v19, vcc
	v_cmp_le_u32_e32 vcc, v128, v87
	s_nop 1
	v_cndmask_b32_e32 v227, 0, v18, vcc
.LBB0_537:
	v_mov_b32_e32 v229, 0
	s_cmp_gt_u32 s2, 0x45f
	s_cbranch_scc0 .Lidxp_e35
	s_waitcnt lgkmcnt(0)
	v_mfma_f32_32x32x16_bf16 v[18:33], v[38:41], v[58:61], 0
	v_max_f32_e32 v2, 0, v2
	v_max_f32_e32 v3, 0, v3
	v_fma_f32 v2, v174, v2, 0
	v_max_f32_e32 v4, 0, v4
	v_fmac_f32_e32 v2, v173, v3
	v_max_f32_e32 v5, 0, v5
	v_fmac_f32_e32 v2, v172, v4
	v_max_f32_e32 v6, 0, v6
	v_fmac_f32_e32 v2, v171, v5
	v_max_f32_e32 v7, 0, v7
	v_mfma_f32_32x32x16_bf16 v[18:33], v[46:49], v[54:57], v[18:33]
	v_fmac_f32_e32 v2, v170, v6
	v_max_f32_e32 v8, 0, v8
	v_fmac_f32_e32 v2, v169, v7
	v_max_f32_e32 v9, 0, v9
	v_fmac_f32_e32 v2, v168, v8
	v_max_f32_e32 v10, 0, v10
	v_fmac_f32_e32 v2, v167, v9
	v_max_f32_e32 v11, 0, v11
	v_fmac_f32_e32 v2, v166, v10
	v_max_f32_e32 v12, 0, v12
	v_mfma_f32_32x32x16_bf16 v[18:33], v[34:37], v[50:53], v[18:33]
	v_fmac_f32_e32 v2, v165, v11
	v_max_f32_e32 v13, 0, v13
	v_fmac_f32_e32 v2, v164, v12
	v_max_f32_e32 v14, 0, v14
	v_fmac_f32_e32 v2, v163, v13
	v_fmac_f32_e32 v2, v162, v14
	v_max_f32_e32 v3, 0, v15
	v_fmac_f32_e32 v2, v161, v3
	v_max_f32_e32 v3, 0, v16
	v_fmac_f32_e32 v2, v160, v3
	v_mfma_f32_32x32x16_bf16 v[18:33], v[42:45], v[62:65], v[18:33]
	ds_read_b128 v[58:61], v74 offset:8192
	ds_read_b128 v[54:57], v75 offset:8192
	ds_read_b128 v[50:53], v76 offset:8192
	ds_read_b128 v[62:65], v77 offset:8192
	v_max_f32_e32 v3, 0, v17
	v_fmac_f32_e32 v2, v89, v3
	v_cmp_gt_i32_e32 vcc, 0, v2
	v_not_b32_e32 v3, v2
	v_or_b32_e32 v4, 0x80000000, v2
	v_cndmask_b32_e32 v2, v4, v3, vcc
	v_cmp_le_u32_e32 vcc, v129, v87
	s_nop 1
	v_cndmask_b32_e32 v228, 0, v2, vcc
.LBB0_541:
	v_mov_b32_e32 v230, 0
	s_cmp_gt_u32 s2, 0x47f
	s_cbranch_scc0 .Lidxp_e36
	s_waitcnt lgkmcnt(0)
	v_mfma_f32_32x32x16_bf16 v[2:17], v[38:41], v[58:61], 0
	v_max_f32_e32 v18, 0, v18
	v_max_f32_e32 v19, 0, v19
	v_fma_f32 v18, v174, v18, 0
	v_max_f32_e32 v20, 0, v20
	v_fmac_f32_e32 v18, v173, v19
	v_max_f32_e32 v21, 0, v21
	v_fmac_f32_e32 v18, v172, v20
	v_max_f32_e32 v22, 0, v22
	v_fmac_f32_e32 v18, v171, v21
	v_max_f32_e32 v23, 0, v23
	v_mfma_f32_32x32x16_bf16 v[2:17], v[46:49], v[54:57], v[2:17]
	v_fmac_f32_e32 v18, v170, v22
	v_max_f32_e32 v24, 0, v24
	v_fmac_f32_e32 v18, v169, v23
	v_max_f32_e32 v25, 0, v25
	v_fmac_f32_e32 v18, v168, v24
	v_max_f32_e32 v26, 0, v26
	v_fmac_f32_e32 v18, v167, v25
	v_max_f32_e32 v27, 0, v27
	v_fmac_f32_e32 v18, v166, v26
	v_max_f32_e32 v28, 0, v28
	v_mfma_f32_32x32x16_bf16 v[2:17], v[34:37], v[50:53], v[2:17]
	v_fmac_f32_e32 v18, v165, v27
	v_max_f32_e32 v29, 0, v29
	v_fmac_f32_e32 v18, v164, v28
	v_max_f32_e32 v30, 0, v30
	v_fmac_f32_e32 v18, v163, v29
	v_fmac_f32_e32 v18, v162, v30
	v_max_f32_e32 v19, 0, v31
	v_fmac_f32_e32 v18, v161, v19
	v_max_f32_e32 v19, 0, v32
	v_fmac_f32_e32 v18, v160, v19
	v_mfma_f32_32x32x16_bf16 v[2:17], v[42:45], v[62:65], v[2:17]
	ds_read_b128 v[58:61], v74 offset:12288
	ds_read_b128 v[54:57], v75 offset:12288
	ds_read_b128 v[50:53], v76 offset:12288
	ds_read_b128 v[62:65], v77 offset:12288
	v_max_f32_e32 v19, 0, v33
	v_fmac_f32_e32 v18, v89, v19
	v_cmp_gt_i32_e32 vcc, 0, v18
	v_not_b32_e32 v19, v18
	v_or_b32_e32 v20, 0x80000000, v18
	v_cndmask_b32_e32 v18, v20, v19, vcc
	v_cmp_le_u32_e32 vcc, v130, v87
	s_nop 1
	v_cndmask_b32_e32 v229, 0, v18, vcc
.LBB0_545:
	v_mov_b32_e32 v231, 0
	s_cmp_gt_u32 s2, 0x49f
	s_cbranch_scc0 .Lidxp_e37
	s_waitcnt lgkmcnt(0)
	v_mfma_f32_32x32x16_bf16 v[18:33], v[38:41], v[58:61], 0
	v_max_f32_e32 v2, 0, v2
	v_max_f32_e32 v3, 0, v3
	v_fma_f32 v2, v174, v2, 0
	v_max_f32_e32 v4, 0, v4
	v_fmac_f32_e32 v2, v173, v3
	v_max_f32_e32 v5, 0, v5
	v_fmac_f32_e32 v2, v172, v4
	v_max_f32_e32 v6, 0, v6
	v_fmac_f32_e32 v2, v171, v5
	v_max_f32_e32 v7, 0, v7
	v_mfma_f32_32x32x16_bf16 v[18:33], v[46:49], v[54:57], v[18:33]
	v_fmac_f32_e32 v2, v170, v6
	v_max_f32_e32 v8, 0, v8
	v_fmac_f32_e32 v2, v169, v7
	v_max_f32_e32 v9, 0, v9
	v_fmac_f32_e32 v2, v168, v8
	v_max_f32_e32 v10, 0, v10
	v_fmac_f32_e32 v2, v167, v9
	v_max_f32_e32 v11, 0, v11
	v_fmac_f32_e32 v2, v166, v10
	v_max_f32_e32 v12, 0, v12
	v_mfma_f32_32x32x16_bf16 v[18:33], v[34:37], v[50:53], v[18:33]
	v_fmac_f32_e32 v2, v165, v11
	v_max_f32_e32 v13, 0, v13
	v_fmac_f32_e32 v2, v164, v12
	v_max_f32_e32 v14, 0, v14
	v_fmac_f32_e32 v2, v163, v13
	v_fmac_f32_e32 v2, v162, v14
	v_max_f32_e32 v3, 0, v15
	v_fmac_f32_e32 v2, v161, v3
	v_max_f32_e32 v3, 0, v16
	v_fmac_f32_e32 v2, v160, v3
	v_mfma_f32_32x32x16_bf16 v[18:33], v[42:45], v[62:65], v[18:33]
	ds_read_b128 v[58:61], v74 offset:16384
	ds_read_b128 v[54:57], v75 offset:16384
	ds_read_b128 v[50:53], v76 offset:16384
	ds_read_b128 v[62:65], v77 offset:16384
	v_max_f32_e32 v3, 0, v17
	v_fmac_f32_e32 v2, v89, v3
	v_cmp_gt_i32_e32 vcc, 0, v2
	v_not_b32_e32 v3, v2
	v_or_b32_e32 v4, 0x80000000, v2
	v_cndmask_b32_e32 v2, v4, v3, vcc
	v_cmp_le_u32_e32 vcc, v131, v87
	s_nop 1
	v_cndmask_b32_e32 v230, 0, v2, vcc
.LBB0_549:
	v_mov_b32_e32 v232, 0
	s_cmp_gt_u32 s2, 0x4bf
	s_cbranch_scc0 .Lidxp_e38
	s_waitcnt lgkmcnt(0)
	v_mfma_f32_32x32x16_bf16 v[2:17], v[38:41], v[58:61], 0
	v_max_f32_e32 v18, 0, v18
	v_max_f32_e32 v19, 0, v19
	v_fma_f32 v18, v174, v18, 0
	v_max_f32_e32 v20, 0, v20
	v_fmac_f32_e32 v18, v173, v19
	v_max_f32_e32 v21, 0, v21
	v_fmac_f32_e32 v18, v172, v20
	v_max_f32_e32 v22, 0, v22
	v_fmac_f32_e32 v18, v171, v21
	v_max_f32_e32 v23, 0, v23
	v_mfma_f32_32x32x16_bf16 v[2:17], v[46:49], v[54:57], v[2:17]
	v_fmac_f32_e32 v18, v170, v22
	v_max_f32_e32 v24, 0, v24
	v_fmac_f32_e32 v18, v169, v23
	v_max_f32_e32 v25, 0, v25
	v_fmac_f32_e32 v18, v168, v24
	v_max_f32_e32 v26, 0, v26
	v_fmac_f32_e32 v18, v167, v25
	v_max_f32_e32 v27, 0, v27
	v_fmac_f32_e32 v18, v166, v26
	v_max_f32_e32 v28, 0, v28
	v_mfma_f32_32x32x16_bf16 v[2:17], v[34:37], v[50:53], v[2:17]
	v_fmac_f32_e32 v18, v165, v27
	v_max_f32_e32 v29, 0, v29
	v_fmac_f32_e32 v18, v164, v28
	v_max_f32_e32 v30, 0, v30
	v_fmac_f32_e32 v18, v163, v29
	v_fmac_f32_e32 v18, v162, v30
	v_max_f32_e32 v19, 0, v31
	v_fmac_f32_e32 v18, v161, v19
	v_max_f32_e32 v19, 0, v32
	v_fmac_f32_e32 v18, v160, v19
	v_mfma_f32_32x32x16_bf16 v[2:17], v[42:45], v[62:65], v[2:17]
	ds_read_b128 v[58:61], v74 offset:20480
	ds_read_b128 v[54:57], v75 offset:20480
	ds_read_b128 v[50:53], v76 offset:20480
	ds_read_b128 v[62:65], v77 offset:20480
	v_max_f32_e32 v19, 0, v33
	v_fmac_f32_e32 v18, v89, v19
	v_cmp_gt_i32_e32 vcc, 0, v18
	v_not_b32_e32 v19, v18
	v_or_b32_e32 v20, 0x80000000, v18
	v_cndmask_b32_e32 v18, v20, v19, vcc
	v_cmp_le_u32_e32 vcc, v132, v87
	s_nop 1
	v_cndmask_b32_e32 v231, 0, v18, vcc
.LBB0_553:
	v_mov_b32_e32 v233, 0
	s_cmp_gt_u32 s2, 0x4df
	s_cbranch_scc0 .Lidxp_e39
	s_waitcnt lgkmcnt(0)
	v_mfma_f32_32x32x16_bf16 v[18:33], v[38:41], v[58:61], 0
	v_max_f32_e32 v2, 0, v2
	v_max_f32_e32 v3, 0, v3
	v_fma_f32 v2, v174, v2, 0
	v_max_f32_e32 v4, 0, v4
	v_fmac_f32_e32 v2, v173, v3
	v_max_f32_e32 v5, 0, v5
	v_fmac_f32_e32 v2, v172, v4
	v_max_f32_e32 v6, 0, v6
	v_fmac_f32_e32 v2, v171, v5
	v_max_f32_e32 v7, 0, v7
	v_mfma_f32_32x32x16_bf16 v[18:33], v[46:49], v[54:57], v[18:33]
	v_fmac_f32_e32 v2, v170, v6
	v_max_f32_e32 v8, 0, v8
	v_fmac_f32_e32 v2, v169, v7
	v_max_f32_e32 v9, 0, v9
	v_fmac_f32_e32 v2, v168, v8
	v_max_f32_e32 v10, 0, v10
	v_fmac_f32_e32 v2, v167, v9
	v_max_f32_e32 v11, 0, v11
	v_fmac_f32_e32 v2, v166, v10
	v_max_f32_e32 v12, 0, v12
	v_mfma_f32_32x32x16_bf16 v[18:33], v[34:37], v[50:53], v[18:33]
	v_fmac_f32_e32 v2, v165, v11
	v_max_f32_e32 v13, 0, v13
	v_fmac_f32_e32 v2, v164, v12
	v_max_f32_e32 v14, 0, v14
	v_fmac_f32_e32 v2, v163, v13
	v_fmac_f32_e32 v2, v162, v14
	v_max_f32_e32 v3, 0, v15
	v_fmac_f32_e32 v2, v161, v3
	v_max_f32_e32 v3, 0, v16
	v_fmac_f32_e32 v2, v160, v3
	v_mfma_f32_32x32x16_bf16 v[18:33], v[42:45], v[62:65], v[18:33]
	ds_read_b128 v[58:61], v74 offset:24576
	ds_read_b128 v[54:57], v75 offset:24576
	ds_read_b128 v[50:53], v76 offset:24576
	ds_read_b128 v[62:65], v77 offset:24576
	v_max_f32_e32 v3, 0, v17
	v_fmac_f32_e32 v2, v89, v3
	v_cmp_gt_i32_e32 vcc, 0, v2
	v_not_b32_e32 v3, v2
	v_or_b32_e32 v4, 0x80000000, v2
	v_cndmask_b32_e32 v2, v4, v3, vcc
	v_cmp_le_u32_e32 vcc, v133, v87
	s_nop 1
	v_cndmask_b32_e32 v232, 0, v2, vcc
.LBB0_557:
	v_mov_b32_e32 v234, 0
	s_cmp_gt_u32 s2, 0x4ff
	s_cbranch_scc0 .Lidxp_e40
	s_waitcnt lgkmcnt(0)
	v_mfma_f32_32x32x16_bf16 v[2:17], v[38:41], v[58:61], 0
	v_max_f32_e32 v18, 0, v18
	v_max_f32_e32 v19, 0, v19
	v_fma_f32 v18, v174, v18, 0
	v_max_f32_e32 v20, 0, v20
	v_fmac_f32_e32 v18, v173, v19
	v_max_f32_e32 v21, 0, v21
	v_fmac_f32_e32 v18, v172, v20
	v_max_f32_e32 v22, 0, v22
	v_fmac_f32_e32 v18, v171, v21
	v_max_f32_e32 v23, 0, v23
	v_mfma_f32_32x32x16_bf16 v[2:17], v[46:49], v[54:57], v[2:17]
	v_fmac_f32_e32 v18, v170, v22
	v_max_f32_e32 v24, 0, v24
	v_fmac_f32_e32 v18, v169, v23
	v_max_f32_e32 v25, 0, v25
	v_fmac_f32_e32 v18, v168, v24
	v_max_f32_e32 v26, 0, v26
	v_fmac_f32_e32 v18, v167, v25
	v_max_f32_e32 v27, 0, v27
	v_fmac_f32_e32 v18, v166, v26
	v_max_f32_e32 v28, 0, v28
	v_mfma_f32_32x32x16_bf16 v[2:17], v[34:37], v[50:53], v[2:17]
	v_fmac_f32_e32 v18, v165, v27
	v_max_f32_e32 v29, 0, v29
	v_fmac_f32_e32 v18, v164, v28
	v_max_f32_e32 v30, 0, v30
	v_fmac_f32_e32 v18, v163, v29
	v_fmac_f32_e32 v18, v162, v30
	v_max_f32_e32 v19, 0, v31
	v_fmac_f32_e32 v18, v161, v19
	v_max_f32_e32 v19, 0, v32
	v_fmac_f32_e32 v18, v160, v19
	v_mfma_f32_32x32x16_bf16 v[2:17], v[42:45], v[62:65], v[2:17]
	ds_read_b128 v[58:61], v74 offset:28672
	ds_read_b128 v[54:57], v75 offset:28672
	ds_read_b128 v[50:53], v76 offset:28672
	ds_read_b128 v[62:65], v77 offset:28672
	v_max_f32_e32 v19, 0, v33
	v_fmac_f32_e32 v18, v89, v19
	v_cmp_gt_i32_e32 vcc, 0, v18
	v_not_b32_e32 v19, v18
	v_or_b32_e32 v20, 0x80000000, v18
	v_cndmask_b32_e32 v18, v20, v19, vcc
	v_cmp_le_u32_e32 vcc, v134, v87
	s_nop 1
	v_cndmask_b32_e32 v233, 0, v18, vcc

.Lidxd_s5:
	v_mfma_f32_32x32x16_bf16 v[18:33], v[38:41], v[58:61], 0
	v_max_f32_e32 v2, 0, v2
	v_max_f32_e32 v3, 0, v3
	v_fma_f32 v2, v174, v2, 0
	v_max_f32_e32 v4, 0, v4
	v_fmac_f32_e32 v2, v173, v3
	v_max_f32_e32 v5, 0, v5
	v_fmac_f32_e32 v2, v172, v4
	v_max_f32_e32 v6, 0, v6
	v_fmac_f32_e32 v2, v171, v5
	v_max_f32_e32 v7, 0, v7
	v_mfma_f32_32x32x16_bf16 v[18:33], v[46:49], v[54:57], v[18:33]
	v_fmac_f32_e32 v2, v170, v6
	v_max_f32_e32 v8, 0, v8
	v_fmac_f32_e32 v2, v169, v7
	v_max_f32_e32 v9, 0, v9
	v_fmac_f32_e32 v2, v168, v8
	v_max_f32_e32 v10, 0, v10
	v_fmac_f32_e32 v2, v167, v9
	v_max_f32_e32 v11, 0, v11
	v_fmac_f32_e32 v2, v166, v10
	v_max_f32_e32 v12, 0, v12
	v_mfma_f32_32x32x16_bf16 v[18:33], v[34:37], v[50:53], v[18:33]
	v_fmac_f32_e32 v2, v165, v11
	v_max_f32_e32 v13, 0, v13
	v_fmac_f32_e32 v2, v164, v12
	v_max_f32_e32 v14, 0, v14
	v_fmac_f32_e32 v2, v163, v13
	v_fmac_f32_e32 v2, v162, v14
	v_max_f32_e32 v3, 0, v15
	v_fmac_f32_e32 v2, v161, v3
	v_max_f32_e32 v3, 0, v16
	v_fmac_f32_e32 v2, v160, v3
	v_mfma_f32_32x32x16_bf16 v[18:33], v[42:45], v[62:65], v[18:33]
	ds_read_b128 v[58:61], v74 offset:32768
	ds_read_b128 v[54:57], v75 offset:32768
	ds_read_b128 v[50:53], v76 offset:32768
	ds_read_b128 v[62:65], v77 offset:32768
	v_max_f32_e32 v3, 0, v17
	v_fmac_f32_e32 v2, v89, v3
	v_cmp_gt_i32_e32 vcc, 0, v2
	v_not_b32_e32 v3, v2
	v_or_b32_e32 v4, 0x80000000, v2
	v_cndmask_b32_e32 v2, v4, v3, vcc
	v_cmp_le_u32_e32 vcc, v135, v87
	s_nop 1
	v_cndmask_b32_e32 v234, 0, v2, vcc
.LBB0_565:
	v_mov_b32_e32 v236, 0
	s_cmp_gt_u32 s2, 0x53f
	s_cbranch_scc0 .Lidxp_e42
	s_waitcnt lgkmcnt(0)
	v_mfma_f32_32x32x16_bf16 v[2:17], v[38:41], v[58:61], 0
	v_max_f32_e32 v18, 0, v18
	v_max_f32_e32 v19, 0, v19
	v_fma_f32 v18, v174, v18, 0
	v_max_f32_e32 v20, 0, v20
	v_fmac_f32_e32 v18, v173, v19
	v_max_f32_e32 v21, 0, v21
	v_fmac_f32_e32 v18, v172, v20
	v_max_f32_e32 v22, 0, v22
	v_fmac_f32_e32 v18, v171, v21
	v_max_f32_e32 v23, 0, v23
	v_mfma_f32_32x32x16_bf16 v[2:17], v[46:49], v[54:57], v[2:17]
	v_fmac_f32_e32 v18, v170, v22
	v_max_f32_e32 v24, 0, v24
	v_fmac_f32_e32 v18, v169, v23
	v_max_f32_e32 v25, 0, v25
	v_fmac_f32_e32 v18, v168, v24
	v_max_f32_e32 v26, 0, v26
	v_fmac_f32_e32 v18, v167, v25
	v_max_f32_e32 v27, 0, v27
	v_fmac_f32_e32 v18, v166, v26
	v_max_f32_e32 v28, 0, v28
	v_mfma_f32_32x32x16_bf16 v[2:17], v[34:37], v[50:53], v[2:17]
	v_fmac_f32_e32 v18, v165, v27
	v_max_f32_e32 v29, 0, v29
	v_fmac_f32_e32 v18, v164, v28
	v_max_f32_e32 v30, 0, v30
	v_fmac_f32_e32 v18, v163, v29
	v_fmac_f32_e32 v18, v162, v30
	v_max_f32_e32 v19, 0, v31
	v_fmac_f32_e32 v18, v161, v19
	v_max_f32_e32 v19, 0, v32
	v_fmac_f32_e32 v18, v160, v19
	v_mfma_f32_32x32x16_bf16 v[2:17], v[42:45], v[62:65], v[2:17]
	ds_read_b128 v[58:61], v74 offset:36864
	ds_read_b128 v[54:57], v75 offset:36864
	ds_read_b128 v[50:53], v76 offset:36864
	ds_read_b128 v[62:65], v77 offset:36864
	v_max_f32_e32 v19, 0, v33
	v_fmac_f32_e32 v18, v89, v19
	v_cmp_gt_i32_e32 vcc, 0, v18
	v_not_b32_e32 v19, v18
	v_or_b32_e32 v20, 0x80000000, v18
	v_cndmask_b32_e32 v18, v20, v19, vcc
	v_cmp_le_u32_e32 vcc, v136, v87
	s_nop 1
	v_cndmask_b32_e32 v235, 0, v18, vcc
.LBB0_569:
	v_mov_b32_e32 v237, 0
	s_cmp_gt_u32 s2, 0x55f
	s_cbranch_scc0 .Lidxp_e43
	s_waitcnt lgkmcnt(0)
	v_mfma_f32_32x32x16_bf16 v[18:33], v[38:41], v[58:61], 0
	v_max_f32_e32 v2, 0, v2
	v_max_f32_e32 v3, 0, v3
	v_fma_f32 v2, v174, v2, 0
	v_max_f32_e32 v4, 0, v4
	v_fmac_f32_e32 v2, v173, v3
	v_max_f32_e32 v5, 0, v5
	v_fmac_f32_e32 v2, v172, v4
	v_max_f32_e32 v6, 0, v6
	v_fmac_f32_e32 v2, v171, v5
	v_max_f32_e32 v7, 0, v7
	v_mfma_f32_32x32x16_bf16 v[18:33], v[46:49], v[54:57], v[18:33]
	v_fmac_f32_e32 v2, v170, v6
	v_max_f32_e32 v8, 0, v8
	v_fmac_f32_e32 v2, v169, v7
	v_max_f32_e32 v9, 0, v9
	v_fmac_f32_e32 v2, v168, v8
	v_max_f32_e32 v10, 0, v10
	v_fmac_f32_e32 v2, v167, v9
	v_max_f32_e32 v11, 0, v11
	v_fmac_f32_e32 v2, v166, v10
	v_max_f32_e32 v12, 0, v12
	v_mfma_f32_32x32x16_bf16 v[18:33], v[34:37], v[50:53], v[18:33]
	v_fmac_f32_e32 v2, v165, v11
	v_max_f32_e32 v13, 0, v13
	v_fmac_f32_e32 v2, v164, v12
	v_max_f32_e32 v14, 0, v14
	v_fmac_f32_e32 v2, v163, v13
	v_fmac_f32_e32 v2, v162, v14
	v_max_f32_e32 v3, 0, v15
	v_fmac_f32_e32 v2, v161, v3
	v_max_f32_e32 v3, 0, v16
	v_fmac_f32_e32 v2, v160, v3
	v_mfma_f32_32x32x16_bf16 v[18:33], v[42:45], v[62:65], v[18:33]
	ds_read_b128 v[58:61], v74 offset:40960
	ds_read_b128 v[54:57], v75 offset:40960
	ds_read_b128 v[50:53], v76 offset:40960
	ds_read_b128 v[62:65], v77 offset:40960
	v_max_f32_e32 v3, 0, v17
	v_fmac_f32_e32 v2, v89, v3
	v_cmp_gt_i32_e32 vcc, 0, v2
	v_not_b32_e32 v3, v2
	v_or_b32_e32 v4, 0x80000000, v2
	v_cndmask_b32_e32 v2, v4, v3, vcc
	v_cmp_le_u32_e32 vcc, v137, v87
	s_nop 1
	v_cndmask_b32_e32 v236, 0, v2, vcc
.LBB0_573:
	v_mov_b32_e32 v238, 0
	s_cmp_gt_u32 s2, 0x57f
	s_cbranch_scc0 .Lidxp_e44
	s_waitcnt lgkmcnt(0)
	v_mfma_f32_32x32x16_bf16 v[2:17], v[38:41], v[58:61], 0
	v_max_f32_e32 v18, 0, v18
	v_max_f32_e32 v19, 0, v19
	v_fma_f32 v18, v174, v18, 0
	v_max_f32_e32 v20, 0, v20
	v_fmac_f32_e32 v18, v173, v19
	v_max_f32_e32 v21, 0, v21
	v_fmac_f32_e32 v18, v172, v20
	v_max_f32_e32 v22, 0, v22
	v_fmac_f32_e32 v18, v171, v21
	v_max_f32_e32 v23, 0, v23
	v_mfma_f32_32x32x16_bf16 v[2:17], v[46:49], v[54:57], v[2:17]
	v_fmac_f32_e32 v18, v170, v22
	v_max_f32_e32 v24, 0, v24
	v_fmac_f32_e32 v18, v169, v23
	v_max_f32_e32 v25, 0, v25
	v_fmac_f32_e32 v18, v168, v24
	v_max_f32_e32 v26, 0, v26
	v_fmac_f32_e32 v18, v167, v25
	v_max_f32_e32 v27, 0, v27
	v_fmac_f32_e32 v18, v166, v26
	v_max_f32_e32 v28, 0, v28
	v_mfma_f32_32x32x16_bf16 v[2:17], v[34:37], v[50:53], v[2:17]
	v_fmac_f32_e32 v18, v165, v27
	v_max_f32_e32 v29, 0, v29
	v_fmac_f32_e32 v18, v164, v28
	v_max_f32_e32 v30, 0, v30
	v_fmac_f32_e32 v18, v163, v29
	v_fmac_f32_e32 v18, v162, v30
	v_max_f32_e32 v19, 0, v31
	v_fmac_f32_e32 v18, v161, v19
	v_max_f32_e32 v19, 0, v32
	v_fmac_f32_e32 v18, v160, v19
	v_mfma_f32_32x32x16_bf16 v[2:17], v[42:45], v[62:65], v[2:17]
	ds_read_b128 v[58:61], v74 offset:45056
	ds_read_b128 v[54:57], v75 offset:45056
	ds_read_b128 v[50:53], v76 offset:45056
	ds_read_b128 v[62:65], v77 offset:45056
	v_max_f32_e32 v19, 0, v33
	v_fmac_f32_e32 v18, v89, v19
	v_cmp_gt_i32_e32 vcc, 0, v18
	v_not_b32_e32 v19, v18
	v_or_b32_e32 v20, 0x80000000, v18
	v_cndmask_b32_e32 v18, v20, v19, vcc
	v_cmp_le_u32_e32 vcc, v138, v87
	s_nop 1
	v_cndmask_b32_e32 v237, 0, v18, vcc
.LBB0_577:
	v_mov_b32_e32 v239, 0
	s_cmp_gt_u32 s2, 0x59f
	s_cbranch_scc0 .Lidxp_e45
	s_waitcnt lgkmcnt(0)
	v_mfma_f32_32x32x16_bf16 v[18:33], v[38:41], v[58:61], 0
	v_max_f32_e32 v2, 0, v2
	v_max_f32_e32 v3, 0, v3
	v_fma_f32 v2, v174, v2, 0
	v_max_f32_e32 v4, 0, v4
	v_fmac_f32_e32 v2, v173, v3
	v_max_f32_e32 v5, 0, v5
	v_fmac_f32_e32 v2, v172, v4
	v_max_f32_e32 v6, 0, v6
	v_fmac_f32_e32 v2, v171, v5
	v_max_f32_e32 v7, 0, v7
	v_mfma_f32_32x32x16_bf16 v[18:33], v[46:49], v[54:57], v[18:33]
	v_fmac_f32_e32 v2, v170, v6
	v_max_f32_e32 v8, 0, v8
	v_fmac_f32_e32 v2, v169, v7
	v_max_f32_e32 v9, 0, v9
	v_fmac_f32_e32 v2, v168, v8
	v_max_f32_e32 v10, 0, v10
	v_fmac_f32_e32 v2, v167, v9
	v_max_f32_e32 v11, 0, v11
	v_fmac_f32_e32 v2, v166, v10
	v_max_f32_e32 v12, 0, v12
	v_mfma_f32_32x32x16_bf16 v[18:33], v[34:37], v[50:53], v[18:33]
	v_fmac_f32_e32 v2, v165, v11
	v_max_f32_e32 v13, 0, v13
	v_fmac_f32_e32 v2, v164, v12
	v_max_f32_e32 v14, 0, v14
	v_fmac_f32_e32 v2, v163, v13
	v_fmac_f32_e32 v2, v162, v14
	v_max_f32_e32 v3, 0, v15
	v_fmac_f32_e32 v2, v161, v3
	v_max_f32_e32 v3, 0, v16
	v_fmac_f32_e32 v2, v160, v3
	v_mfma_f32_32x32x16_bf16 v[18:33], v[42:45], v[62:65], v[18:33]
	ds_read_b128 v[58:61], v74 offset:49152
	ds_read_b128 v[54:57], v75 offset:49152
	ds_read_b128 v[50:53], v76 offset:49152
	ds_read_b128 v[62:65], v77 offset:49152
	v_max_f32_e32 v3, 0, v17
	v_fmac_f32_e32 v2, v89, v3
	v_cmp_gt_i32_e32 vcc, 0, v2
	v_not_b32_e32 v3, v2
	v_or_b32_e32 v4, 0x80000000, v2
	v_cndmask_b32_e32 v2, v4, v3, vcc
	v_cmp_le_u32_e32 vcc, v139, v87
	s_nop 1
	v_cndmask_b32_e32 v238, 0, v2, vcc
.LBB0_581:
	v_mov_b32_e32 v240, 0
	s_cmp_gt_u32 s2, 0x5bf
	s_cbranch_scc0 .Lidxp_e46
	s_waitcnt lgkmcnt(0)
	v_mfma_f32_32x32x16_bf16 v[2:17], v[38:41], v[58:61], 0
	v_max_f32_e32 v18, 0, v18
	v_max_f32_e32 v19, 0, v19
	v_fma_f32 v18, v174, v18, 0
	v_max_f32_e32 v20, 0, v20
	v_fmac_f32_e32 v18, v173, v19
	v_max_f32_e32 v21, 0, v21
	v_fmac_f32_e32 v18, v172, v20
	v_max_f32_e32 v22, 0, v22
	v_fmac_f32_e32 v18, v171, v21
	v_max_f32_e32 v23, 0, v23
	v_mfma_f32_32x32x16_bf16 v[2:17], v[46:49], v[54:57], v[2:17]
	v_fmac_f32_e32 v18, v170, v22
	v_max_f32_e32 v24, 0, v24
	v_fmac_f32_e32 v18, v169, v23
	v_max_f32_e32 v25, 0, v25
	v_fmac_f32_e32 v18, v168, v24
	v_max_f32_e32 v26, 0, v26
	v_fmac_f32_e32 v18, v167, v25
	v_max_f32_e32 v27, 0, v27
	v_fmac_f32_e32 v18, v166, v26
	v_max_f32_e32 v28, 0, v28
	v_mfma_f32_32x32x16_bf16 v[2:17], v[34:37], v[50:53], v[2:17]
	v_fmac_f32_e32 v18, v165, v27
	v_max_f32_e32 v29, 0, v29
	v_fmac_f32_e32 v18, v164, v28
	v_max_f32_e32 v30, 0, v30
	v_fmac_f32_e32 v18, v163, v29
	v_fmac_f32_e32 v18, v162, v30
	v_max_f32_e32 v19, 0, v31
	v_fmac_f32_e32 v18, v161, v19
	v_max_f32_e32 v19, 0, v32
	v_fmac_f32_e32 v18, v160, v19
	v_mfma_f32_32x32x16_bf16 v[2:17], v[42:45], v[62:65], v[2:17]
	ds_read_b128 v[58:61], v74 offset:53248
	ds_read_b128 v[54:57], v75 offset:53248
	ds_read_b128 v[50:53], v76 offset:53248
	ds_read_b128 v[62:65], v77 offset:53248
	v_max_f32_e32 v19, 0, v33
	v_fmac_f32_e32 v18, v89, v19
	v_cmp_gt_i32_e32 vcc, 0, v18
	v_not_b32_e32 v19, v18
	v_or_b32_e32 v20, 0x80000000, v18
	v_cndmask_b32_e32 v18, v20, v19, vcc
	v_cmp_le_u32_e32 vcc, v140, v87
	s_nop 1
	v_cndmask_b32_e32 v239, 0, v18, vcc
.LBB0_585:
	v_mov_b32_e32 v241, 0
	s_cmp_gt_u32 s2, 0x5df
	s_cbranch_scc0 .Lidxp_e47
	s_waitcnt lgkmcnt(0)
	v_mfma_f32_32x32x16_bf16 v[18:33], v[38:41], v[58:61], 0
	v_max_f32_e32 v2, 0, v2
	v_max_f32_e32 v3, 0, v3
	v_fma_f32 v2, v174, v2, 0
	v_max_f32_e32 v4, 0, v4
	v_fmac_f32_e32 v2, v173, v3
	v_max_f32_e32 v5, 0, v5
	v_fmac_f32_e32 v2, v172, v4
	v_max_f32_e32 v6, 0, v6
	v_fmac_f32_e32 v2, v171, v5
	v_max_f32_e32 v7, 0, v7
	v_mfma_f32_32x32x16_bf16 v[18:33], v[46:49], v[54:57], v[18:33]
	v_fmac_f32_e32 v2, v170, v6
	v_max_f32_e32 v8, 0, v8
	v_fmac_f32_e32 v2, v169, v7
	v_max_f32_e32 v9, 0, v9
	v_fmac_f32_e32 v2, v168, v8
	v_max_f32_e32 v10, 0, v10
	v_fmac_f32_e32 v2, v167, v9
	v_max_f32_e32 v11, 0, v11
	v_fmac_f32_e32 v2, v166, v10
	v_max_f32_e32 v12, 0, v12
	v_mfma_f32_32x32x16_bf16 v[18:33], v[34:37], v[50:53], v[18:33]
	v_fmac_f32_e32 v2, v165, v11
	v_max_f32_e32 v13, 0, v13
	v_fmac_f32_e32 v2, v164, v12
	v_max_f32_e32 v14, 0, v14
	v_fmac_f32_e32 v2, v163, v13
	v_fmac_f32_e32 v2, v162, v14
	v_max_f32_e32 v3, 0, v15
	v_fmac_f32_e32 v2, v161, v3
	v_max_f32_e32 v3, 0, v16
	v_fmac_f32_e32 v2, v160, v3
	v_mfma_f32_32x32x16_bf16 v[18:33], v[42:45], v[62:65], v[18:33]
	ds_read_b128 v[58:61], v74 offset:57344
	ds_read_b128 v[54:57], v75 offset:57344
	ds_read_b128 v[50:53], v76 offset:57344
	ds_read_b128 v[62:65], v77 offset:57344
	v_max_f32_e32 v3, 0, v17
	v_fmac_f32_e32 v2, v89, v3
	v_cmp_gt_i32_e32 vcc, 0, v2
	v_not_b32_e32 v3, v2
	v_or_b32_e32 v4, 0x80000000, v2
	v_cndmask_b32_e32 v2, v4, v3, vcc
	v_cmp_le_u32_e32 vcc, v141, v87
	s_nop 1
	v_cndmask_b32_e32 v240, 0, v2, vcc
.LBB0_589:
	v_mov_b32_e32 v242, 0
	s_cmp_gt_u32 s2, 0x5ff
	s_cbranch_scc0 .Lidxp_e48
	s_waitcnt lgkmcnt(0)
	v_mfma_f32_32x32x16_bf16 v[2:17], v[38:41], v[58:61], 0
	v_max_f32_e32 v18, 0, v18
	v_max_f32_e32 v19, 0, v19
	v_fma_f32 v18, v174, v18, 0
	v_max_f32_e32 v20, 0, v20
	v_fmac_f32_e32 v18, v173, v19
	v_max_f32_e32 v21, 0, v21
	v_fmac_f32_e32 v18, v172, v20
	v_max_f32_e32 v22, 0, v22
	v_fmac_f32_e32 v18, v171, v21
	v_max_f32_e32 v23, 0, v23
	v_mfma_f32_32x32x16_bf16 v[2:17], v[46:49], v[54:57], v[2:17]
	v_fmac_f32_e32 v18, v170, v22
	v_max_f32_e32 v24, 0, v24
	v_fmac_f32_e32 v18, v169, v23
	v_max_f32_e32 v25, 0, v25
	v_fmac_f32_e32 v18, v168, v24
	v_max_f32_e32 v26, 0, v26
	v_fmac_f32_e32 v18, v167, v25
	v_max_f32_e32 v27, 0, v27
	v_fmac_f32_e32 v18, v166, v26
	v_max_f32_e32 v28, 0, v28
	v_mfma_f32_32x32x16_bf16 v[2:17], v[34:37], v[50:53], v[2:17]
	v_fmac_f32_e32 v18, v165, v27
	v_max_f32_e32 v29, 0, v29
	v_fmac_f32_e32 v18, v164, v28
	v_max_f32_e32 v30, 0, v30
	v_fmac_f32_e32 v18, v163, v29
	v_fmac_f32_e32 v18, v162, v30
	v_max_f32_e32 v19, 0, v31
	v_fmac_f32_e32 v18, v161, v19
	v_max_f32_e32 v19, 0, v32
	v_fmac_f32_e32 v18, v160, v19
	v_mfma_f32_32x32x16_bf16 v[2:17], v[42:45], v[62:65], v[2:17]
	ds_read_b128 v[58:61], v74 offset:61440
	ds_read_b128 v[54:57], v75 offset:61440
	ds_read_b128 v[50:53], v76 offset:61440
	ds_read_b128 v[62:65], v77 offset:61440
	v_max_f32_e32 v19, 0, v33
	v_fmac_f32_e32 v18, v89, v19
	v_cmp_gt_i32_e32 vcc, 0, v18
	v_not_b32_e32 v19, v18
	v_or_b32_e32 v20, 0x80000000, v18
	v_cndmask_b32_e32 v18, v20, v19, vcc
	v_cmp_le_u32_e32 vcc, v142, v87
	s_nop 1
	v_cndmask_b32_e32 v241, 0, v18, vcc

.Lidxd_s6:
	v_mfma_f32_32x32x16_bf16 v[18:33], v[38:41], v[58:61], 0
	v_max_f32_e32 v2, 0, v2
	v_max_f32_e32 v3, 0, v3
	v_fma_f32 v2, v174, v2, 0
	v_max_f32_e32 v4, 0, v4
	v_fmac_f32_e32 v2, v173, v3
	v_max_f32_e32 v5, 0, v5
	v_fmac_f32_e32 v2, v172, v4
	v_max_f32_e32 v6, 0, v6
	v_fmac_f32_e32 v2, v171, v5
	v_max_f32_e32 v7, 0, v7
	v_mfma_f32_32x32x16_bf16 v[18:33], v[46:49], v[54:57], v[18:33]
	v_fmac_f32_e32 v2, v170, v6
	v_max_f32_e32 v8, 0, v8
	v_fmac_f32_e32 v2, v169, v7
	v_max_f32_e32 v9, 0, v9
	v_fmac_f32_e32 v2, v168, v8
	v_max_f32_e32 v10, 0, v10
	v_fmac_f32_e32 v2, v167, v9
	v_max_f32_e32 v11, 0, v11
	v_fmac_f32_e32 v2, v166, v10
	v_max_f32_e32 v12, 0, v12
	v_mfma_f32_32x32x16_bf16 v[18:33], v[34:37], v[50:53], v[18:33]
	v_fmac_f32_e32 v2, v165, v11
	v_max_f32_e32 v13, 0, v13
	v_fmac_f32_e32 v2, v164, v12
	v_max_f32_e32 v14, 0, v14
	v_fmac_f32_e32 v2, v163, v13
	v_fmac_f32_e32 v2, v162, v14
	v_max_f32_e32 v3, 0, v15
	v_fmac_f32_e32 v2, v161, v3
	v_max_f32_e32 v3, 0, v16
	v_fmac_f32_e32 v2, v160, v3
	v_mfma_f32_32x32x16_bf16 v[18:33], v[42:45], v[62:65], v[18:33]
	ds_read_b128 v[58:61], v74 offset:0
	ds_read_b128 v[54:57], v75 offset:0
	ds_read_b128 v[50:53], v76 offset:0
	ds_read_b128 v[62:65], v77 offset:0
	v_max_f32_e32 v3, 0, v17
	v_fmac_f32_e32 v2, v89, v3
	v_cmp_gt_i32_e32 vcc, 0, v2
	v_not_b32_e32 v3, v2
	v_or_b32_e32 v4, 0x80000000, v2
	v_cndmask_b32_e32 v2, v4, v3, vcc
	v_cmp_le_u32_e32 vcc, v143, v87
	s_nop 1
	v_cndmask_b32_e32 v242, 0, v2, vcc
.LBB0_597:
	v_mov_b32_e32 v244, 0
	s_cmp_gt_u32 s2, 0x63f
	s_cbranch_scc0 .Lidxp_e50
	s_waitcnt lgkmcnt(0)
	v_mfma_f32_32x32x16_bf16 v[2:17], v[38:41], v[58:61], 0
	v_max_f32_e32 v18, 0, v18
	v_max_f32_e32 v19, 0, v19
	v_fma_f32 v18, v174, v18, 0
	v_max_f32_e32 v20, 0, v20
	v_fmac_f32_e32 v18, v173, v19
	v_max_f32_e32 v21, 0, v21
	v_fmac_f32_e32 v18, v172, v20
	v_max_f32_e32 v22, 0, v22
	v_fmac_f32_e32 v18, v171, v21
	v_max_f32_e32 v23, 0, v23
	v_mfma_f32_32x32x16_bf16 v[2:17], v[46:49], v[54:57], v[2:17]
	v_fmac_f32_e32 v18, v170, v22
	v_max_f32_e32 v24, 0, v24
	v_fmac_f32_e32 v18, v169, v23
	v_max_f32_e32 v25, 0, v25
	v_fmac_f32_e32 v18, v168, v24
	v_max_f32_e32 v26, 0, v26
	v_fmac_f32_e32 v18, v167, v25
	v_max_f32_e32 v27, 0, v27
	v_fmac_f32_e32 v18, v166, v26
	v_max_f32_e32 v28, 0, v28
	v_mfma_f32_32x32x16_bf16 v[2:17], v[34:37], v[50:53], v[2:17]
	v_fmac_f32_e32 v18, v165, v27
	v_max_f32_e32 v29, 0, v29
	v_fmac_f32_e32 v18, v164, v28
	v_max_f32_e32 v30, 0, v30
	v_fmac_f32_e32 v18, v163, v29
	v_fmac_f32_e32 v18, v162, v30
	v_max_f32_e32 v19, 0, v31
	v_fmac_f32_e32 v18, v161, v19
	v_max_f32_e32 v19, 0, v32
	v_fmac_f32_e32 v18, v160, v19
	v_mfma_f32_32x32x16_bf16 v[2:17], v[42:45], v[62:65], v[2:17]
	ds_read_b128 v[58:61], v74 offset:4096
	ds_read_b128 v[54:57], v75 offset:4096
	ds_read_b128 v[50:53], v76 offset:4096
	ds_read_b128 v[62:65], v77 offset:4096
	v_max_f32_e32 v19, 0, v33
	v_fmac_f32_e32 v18, v89, v19
	v_cmp_gt_i32_e32 vcc, 0, v18
	v_not_b32_e32 v19, v18
	v_or_b32_e32 v20, 0x80000000, v18
	v_cndmask_b32_e32 v18, v20, v19, vcc
	v_cmp_le_u32_e32 vcc, v144, v87
	s_nop 1
	v_cndmask_b32_e32 v243, 0, v18, vcc
.LBB0_601:
	v_mov_b32_e32 v245, 0
	s_cmp_gt_u32 s2, 0x65f
	s_cbranch_scc0 .Lidxp_e51
	s_waitcnt lgkmcnt(0)
	v_mfma_f32_32x32x16_bf16 v[18:33], v[38:41], v[58:61], 0
	v_max_f32_e32 v2, 0, v2
	v_max_f32_e32 v3, 0, v3
	v_fma_f32 v2, v174, v2, 0
	v_max_f32_e32 v4, 0, v4
	v_fmac_f32_e32 v2, v173, v3
	v_max_f32_e32 v5, 0, v5
	v_fmac_f32_e32 v2, v172, v4
	v_max_f32_e32 v6, 0, v6
	v_fmac_f32_e32 v2, v171, v5
	v_max_f32_e32 v7, 0, v7
	v_mfma_f32_32x32x16_bf16 v[18:33], v[46:49], v[54:57], v[18:33]
	v_fmac_f32_e32 v2, v170, v6
	v_max_f32_e32 v8, 0, v8
	v_fmac_f32_e32 v2, v169, v7
	v_max_f32_e32 v9, 0, v9
	v_fmac_f32_e32 v2, v168, v8
	v_max_f32_e32 v10, 0, v10
	v_fmac_f32_e32 v2, v167, v9
	v_max_f32_e32 v11, 0, v11
	v_fmac_f32_e32 v2, v166, v10
	v_max_f32_e32 v12, 0, v12
	v_mfma_f32_32x32x16_bf16 v[18:33], v[34:37], v[50:53], v[18:33]
	v_fmac_f32_e32 v2, v165, v11
	v_max_f32_e32 v13, 0, v13
	v_fmac_f32_e32 v2, v164, v12
	v_max_f32_e32 v14, 0, v14
	v_fmac_f32_e32 v2, v163, v13
	v_fmac_f32_e32 v2, v162, v14
	v_max_f32_e32 v3, 0, v15
	v_fmac_f32_e32 v2, v161, v3
	v_max_f32_e32 v3, 0, v16
	v_fmac_f32_e32 v2, v160, v3
	v_mfma_f32_32x32x16_bf16 v[18:33], v[42:45], v[62:65], v[18:33]
	ds_read_b128 v[58:61], v74 offset:8192
	ds_read_b128 v[54:57], v75 offset:8192
	ds_read_b128 v[50:53], v76 offset:8192
	ds_read_b128 v[62:65], v77 offset:8192
	v_max_f32_e32 v3, 0, v17
	v_fmac_f32_e32 v2, v89, v3
	v_cmp_gt_i32_e32 vcc, 0, v2
	v_not_b32_e32 v3, v2
	v_or_b32_e32 v4, 0x80000000, v2
	v_cndmask_b32_e32 v2, v4, v3, vcc
	v_cmp_le_u32_e32 vcc, v145, v87
	s_nop 1
	v_cndmask_b32_e32 v244, 0, v2, vcc
.LBB0_605:
	v_mov_b32_e32 v246, 0
	s_cmp_gt_u32 s2, 0x67f
	s_cbranch_scc0 .Lidxp_e52
	s_waitcnt lgkmcnt(0)
	v_mfma_f32_32x32x16_bf16 v[2:17], v[38:41], v[58:61], 0
	v_max_f32_e32 v18, 0, v18
	v_max_f32_e32 v19, 0, v19
	v_fma_f32 v18, v174, v18, 0
	v_max_f32_e32 v20, 0, v20
	v_fmac_f32_e32 v18, v173, v19
	v_max_f32_e32 v21, 0, v21
	v_fmac_f32_e32 v18, v172, v20
	v_max_f32_e32 v22, 0, v22
	v_fmac_f32_e32 v18, v171, v21
	v_max_f32_e32 v23, 0, v23
	v_mfma_f32_32x32x16_bf16 v[2:17], v[46:49], v[54:57], v[2:17]
	v_fmac_f32_e32 v18, v170, v22
	v_max_f32_e32 v24, 0, v24
	v_fmac_f32_e32 v18, v169, v23
	v_max_f32_e32 v25, 0, v25
	v_fmac_f32_e32 v18, v168, v24
	v_max_f32_e32 v26, 0, v26
	v_fmac_f32_e32 v18, v167, v25
	v_max_f32_e32 v27, 0, v27
	v_fmac_f32_e32 v18, v166, v26
	v_max_f32_e32 v28, 0, v28
	v_mfma_f32_32x32x16_bf16 v[2:17], v[34:37], v[50:53], v[2:17]
	v_fmac_f32_e32 v18, v165, v27
	v_max_f32_e32 v29, 0, v29
	v_fmac_f32_e32 v18, v164, v28
	v_max_f32_e32 v30, 0, v30
	v_fmac_f32_e32 v18, v163, v29
	v_fmac_f32_e32 v18, v162, v30
	v_max_f32_e32 v19, 0, v31
	v_fmac_f32_e32 v18, v161, v19
	v_max_f32_e32 v19, 0, v32
	v_fmac_f32_e32 v18, v160, v19
	v_mfma_f32_32x32x16_bf16 v[2:17], v[42:45], v[62:65], v[2:17]
	ds_read_b128 v[58:61], v74 offset:12288
	ds_read_b128 v[54:57], v75 offset:12288
	ds_read_b128 v[50:53], v76 offset:12288
	ds_read_b128 v[62:65], v77 offset:12288
	v_max_f32_e32 v19, 0, v33
	v_fmac_f32_e32 v18, v89, v19
	v_cmp_gt_i32_e32 vcc, 0, v18
	v_not_b32_e32 v19, v18
	v_or_b32_e32 v20, 0x80000000, v18
	v_cndmask_b32_e32 v18, v20, v19, vcc
	v_cmp_le_u32_e32 vcc, v146, v87
	s_nop 1
	v_cndmask_b32_e32 v245, 0, v18, vcc
.LBB0_609:
	v_mov_b32_e32 v247, 0
	s_cmp_gt_u32 s2, 0x69f
	s_cbranch_scc0 .Lidxp_e53
	s_waitcnt lgkmcnt(0)
	v_mfma_f32_32x32x16_bf16 v[18:33], v[38:41], v[58:61], 0
	v_max_f32_e32 v2, 0, v2
	v_max_f32_e32 v3, 0, v3
	v_fma_f32 v2, v174, v2, 0
	v_max_f32_e32 v4, 0, v4
	v_fmac_f32_e32 v2, v173, v3
	v_max_f32_e32 v5, 0, v5
	v_fmac_f32_e32 v2, v172, v4
	v_max_f32_e32 v6, 0, v6
	v_fmac_f32_e32 v2, v171, v5
	v_max_f32_e32 v7, 0, v7
	v_mfma_f32_32x32x16_bf16 v[18:33], v[46:49], v[54:57], v[18:33]
	v_fmac_f32_e32 v2, v170, v6
	v_max_f32_e32 v8, 0, v8
	v_fmac_f32_e32 v2, v169, v7
	v_max_f32_e32 v9, 0, v9
	v_fmac_f32_e32 v2, v168, v8
	v_max_f32_e32 v10, 0, v10
	v_fmac_f32_e32 v2, v167, v9
	v_max_f32_e32 v11, 0, v11
	v_fmac_f32_e32 v2, v166, v10
	v_max_f32_e32 v12, 0, v12
	v_mfma_f32_32x32x16_bf16 v[18:33], v[34:37], v[50:53], v[18:33]
	v_fmac_f32_e32 v2, v165, v11
	v_max_f32_e32 v13, 0, v13
	v_fmac_f32_e32 v2, v164, v12
	v_max_f32_e32 v14, 0, v14
	v_fmac_f32_e32 v2, v163, v13
	v_fmac_f32_e32 v2, v162, v14
	v_max_f32_e32 v3, 0, v15
	v_fmac_f32_e32 v2, v161, v3
	v_max_f32_e32 v3, 0, v16
	v_fmac_f32_e32 v2, v160, v3
	v_mfma_f32_32x32x16_bf16 v[18:33], v[42:45], v[62:65], v[18:33]
	ds_read_b128 v[58:61], v74 offset:16384
	ds_read_b128 v[54:57], v75 offset:16384
	ds_read_b128 v[50:53], v76 offset:16384
	ds_read_b128 v[62:65], v77 offset:16384
	v_max_f32_e32 v3, 0, v17
	v_fmac_f32_e32 v2, v89, v3
	v_cmp_gt_i32_e32 vcc, 0, v2
	v_not_b32_e32 v3, v2
	v_or_b32_e32 v4, 0x80000000, v2
	v_cndmask_b32_e32 v2, v4, v3, vcc
	v_cmp_le_u32_e32 vcc, v147, v87
	s_nop 1
	v_cndmask_b32_e32 v246, 0, v2, vcc
.LBB0_613:
	v_mov_b32_e32 v248, 0
	s_cmp_gt_u32 s2, 0x6bf
	s_cbranch_scc0 .Lidxp_e54
	s_waitcnt lgkmcnt(0)
	v_mfma_f32_32x32x16_bf16 v[2:17], v[38:41], v[58:61], 0
	v_max_f32_e32 v18, 0, v18
	v_max_f32_e32 v19, 0, v19
	v_fma_f32 v18, v174, v18, 0
	v_max_f32_e32 v20, 0, v20
	v_fmac_f32_e32 v18, v173, v19
	v_max_f32_e32 v21, 0, v21
	v_fmac_f32_e32 v18, v172, v20
	v_max_f32_e32 v22, 0, v22
	v_fmac_f32_e32 v18, v171, v21
	v_max_f32_e32 v23, 0, v23
	v_mfma_f32_32x32x16_bf16 v[2:17], v[46:49], v[54:57], v[2:17]
	v_fmac_f32_e32 v18, v170, v22
	v_max_f32_e32 v24, 0, v24
	v_fmac_f32_e32 v18, v169, v23
	v_max_f32_e32 v25, 0, v25
	v_fmac_f32_e32 v18, v168, v24
	v_max_f32_e32 v26, 0, v26
	v_fmac_f32_e32 v18, v167, v25
	v_max_f32_e32 v27, 0, v27
	v_fmac_f32_e32 v18, v166, v26
	v_max_f32_e32 v28, 0, v28
	v_mfma_f32_32x32x16_bf16 v[2:17], v[34:37], v[50:53], v[2:17]
	v_fmac_f32_e32 v18, v165, v27
	v_max_f32_e32 v29, 0, v29
	v_fmac_f32_e32 v18, v164, v28
	v_max_f32_e32 v30, 0, v30
	v_fmac_f32_e32 v18, v163, v29
	v_fmac_f32_e32 v18, v162, v30
	v_max_f32_e32 v19, 0, v31
	v_fmac_f32_e32 v18, v161, v19
	v_max_f32_e32 v19, 0, v32
	v_fmac_f32_e32 v18, v160, v19
	v_mfma_f32_32x32x16_bf16 v[2:17], v[42:45], v[62:65], v[2:17]
	ds_read_b128 v[58:61], v74 offset:20480
	ds_read_b128 v[54:57], v75 offset:20480
	ds_read_b128 v[50:53], v76 offset:20480
	ds_read_b128 v[62:65], v77 offset:20480
	v_max_f32_e32 v19, 0, v33
	v_fmac_f32_e32 v18, v89, v19
	v_cmp_gt_i32_e32 vcc, 0, v18
	v_not_b32_e32 v19, v18
	v_or_b32_e32 v20, 0x80000000, v18
	v_cndmask_b32_e32 v18, v20, v19, vcc
	v_cmp_le_u32_e32 vcc, v148, v87
	s_nop 1
	v_cndmask_b32_e32 v247, 0, v18, vcc
.LBB0_617:
	v_mov_b32_e32 v249, 0
	s_cmp_gt_u32 s2, 0x6df
	s_cbranch_scc0 .Lidxp_e55
	s_waitcnt lgkmcnt(0)
	v_mfma_f32_32x32x16_bf16 v[18:33], v[38:41], v[58:61], 0
	v_max_f32_e32 v2, 0, v2
	v_max_f32_e32 v3, 0, v3
	v_fma_f32 v2, v174, v2, 0
	v_max_f32_e32 v4, 0, v4
	v_fmac_f32_e32 v2, v173, v3
	v_max_f32_e32 v5, 0, v5
	v_fmac_f32_e32 v2, v172, v4
	v_max_f32_e32 v6, 0, v6
	v_fmac_f32_e32 v2, v171, v5
	v_max_f32_e32 v7, 0, v7
	v_mfma_f32_32x32x16_bf16 v[18:33], v[46:49], v[54:57], v[18:33]
	v_fmac_f32_e32 v2, v170, v6
	v_max_f32_e32 v8, 0, v8
	v_fmac_f32_e32 v2, v169, v7
	v_max_f32_e32 v9, 0, v9
	v_fmac_f32_e32 v2, v168, v8
	v_max_f32_e32 v10, 0, v10
	v_fmac_f32_e32 v2, v167, v9
	v_max_f32_e32 v11, 0, v11
	v_fmac_f32_e32 v2, v166, v10
	v_max_f32_e32 v12, 0, v12
	v_mfma_f32_32x32x16_bf16 v[18:33], v[34:37], v[50:53], v[18:33]
	v_fmac_f32_e32 v2, v165, v11
	v_max_f32_e32 v13, 0, v13
	v_fmac_f32_e32 v2, v164, v12
	v_max_f32_e32 v14, 0, v14
	v_fmac_f32_e32 v2, v163, v13
	v_fmac_f32_e32 v2, v162, v14
	v_max_f32_e32 v3, 0, v15
	v_fmac_f32_e32 v2, v161, v3
	v_max_f32_e32 v3, 0, v16
	v_fmac_f32_e32 v2, v160, v3
	v_mfma_f32_32x32x16_bf16 v[18:33], v[42:45], v[62:65], v[18:33]
	ds_read_b128 v[58:61], v74 offset:24576
	ds_read_b128 v[54:57], v75 offset:24576
	ds_read_b128 v[50:53], v76 offset:24576
	ds_read_b128 v[62:65], v77 offset:24576
	v_max_f32_e32 v3, 0, v17
	v_fmac_f32_e32 v2, v89, v3
	v_cmp_gt_i32_e32 vcc, 0, v2
	v_not_b32_e32 v3, v2
	v_or_b32_e32 v4, 0x80000000, v2
	v_cndmask_b32_e32 v2, v4, v3, vcc
	v_cmp_le_u32_e32 vcc, v149, v87
	s_nop 1
	v_cndmask_b32_e32 v248, 0, v2, vcc
.LBB0_621:
	v_mov_b32_e32 v250, 0
	s_cmp_gt_u32 s2, 0x6ff
	s_cbranch_scc0 .Lidxp_e56
	s_waitcnt lgkmcnt(0)
	v_mfma_f32_32x32x16_bf16 v[2:17], v[38:41], v[58:61], 0
	v_max_f32_e32 v18, 0, v18
	v_max_f32_e32 v19, 0, v19
	v_fma_f32 v18, v174, v18, 0
	v_max_f32_e32 v20, 0, v20
	v_fmac_f32_e32 v18, v173, v19
	v_max_f32_e32 v21, 0, v21
	v_fmac_f32_e32 v18, v172, v20
	v_max_f32_e32 v22, 0, v22
	v_fmac_f32_e32 v18, v171, v21
	v_max_f32_e32 v23, 0, v23
	v_mfma_f32_32x32x16_bf16 v[2:17], v[46:49], v[54:57], v[2:17]
	v_fmac_f32_e32 v18, v170, v22
	v_max_f32_e32 v24, 0, v24
	v_fmac_f32_e32 v18, v169, v23
	v_max_f32_e32 v25, 0, v25
	v_fmac_f32_e32 v18, v168, v24
	v_max_f32_e32 v26, 0, v26
	v_fmac_f32_e32 v18, v167, v25
	v_max_f32_e32 v27, 0, v27
	v_fmac_f32_e32 v18, v166, v26
	v_max_f32_e32 v28, 0, v28
	v_mfma_f32_32x32x16_bf16 v[2:17], v[34:37], v[50:53], v[2:17]
	v_fmac_f32_e32 v18, v165, v27
	v_max_f32_e32 v29, 0, v29
	v_fmac_f32_e32 v18, v164, v28
	v_max_f32_e32 v30, 0, v30
	v_fmac_f32_e32 v18, v163, v29
	v_fmac_f32_e32 v18, v162, v30
	v_max_f32_e32 v19, 0, v31
	v_fmac_f32_e32 v18, v161, v19
	v_max_f32_e32 v19, 0, v32
	v_fmac_f32_e32 v18, v160, v19
	v_mfma_f32_32x32x16_bf16 v[2:17], v[42:45], v[62:65], v[2:17]
	ds_read_b128 v[58:61], v74 offset:28672
	ds_read_b128 v[54:57], v75 offset:28672
	ds_read_b128 v[50:53], v76 offset:28672
	ds_read_b128 v[62:65], v77 offset:28672
	v_max_f32_e32 v19, 0, v33
	v_fmac_f32_e32 v18, v89, v19
	v_cmp_gt_i32_e32 vcc, 0, v18
	v_not_b32_e32 v19, v18
	v_or_b32_e32 v20, 0x80000000, v18
	v_cndmask_b32_e32 v18, v20, v19, vcc
	v_cmp_le_u32_e32 vcc, v150, v87
	s_nop 1
	v_cndmask_b32_e32 v249, 0, v18, vcc
.LBB0_625:
	v_mov_b32_e32 v199, 0
	s_cmp_gt_u32 s2, 0x71f
	s_cbranch_scc0 .Lidxp_e57
	s_waitcnt lgkmcnt(0)
	s_waitcnt vmcnt(0)
	s_barrier
	v_mfma_f32_32x32x16_bf16 v[18:33], v[38:41], v[58:61], 0
	v_max_f32_e32 v2, 0, v2
	v_max_f32_e32 v3, 0, v3
	v_fma_f32 v2, v174, v2, 0
	v_max_f32_e32 v4, 0, v4
	v_fmac_f32_e32 v2, v173, v3
	v_max_f32_e32 v5, 0, v5
	v_fmac_f32_e32 v2, v172, v4
	v_max_f32_e32 v6, 0, v6
	v_fmac_f32_e32 v2, v171, v5
	v_max_f32_e32 v7, 0, v7
	v_mfma_f32_32x32x16_bf16 v[18:33], v[46:49], v[54:57], v[18:33]
	v_fmac_f32_e32 v2, v170, v6
	v_max_f32_e32 v8, 0, v8
	v_fmac_f32_e32 v2, v169, v7
	v_max_f32_e32 v9, 0, v9
	v_fmac_f32_e32 v2, v168, v8
	v_max_f32_e32 v10, 0, v10
	v_fmac_f32_e32 v2, v167, v9
	v_max_f32_e32 v11, 0, v11
	v_fmac_f32_e32 v2, v166, v10
	v_max_f32_e32 v12, 0, v12
	v_mfma_f32_32x32x16_bf16 v[18:33], v[34:37], v[50:53], v[18:33]
	v_fmac_f32_e32 v2, v165, v11
	v_max_f32_e32 v13, 0, v13
	v_fmac_f32_e32 v2, v164, v12
	v_max_f32_e32 v14, 0, v14
	v_fmac_f32_e32 v2, v163, v13
	v_fmac_f32_e32 v2, v162, v14
	v_max_f32_e32 v3, 0, v15
	v_fmac_f32_e32 v2, v161, v3
	v_max_f32_e32 v3, 0, v16
	v_fmac_f32_e32 v2, v160, v3
	v_mfma_f32_32x32x16_bf16 v[18:33], v[42:45], v[62:65], v[18:33]
	ds_read_b128 v[58:61], v74 offset:32768
	ds_read_b128 v[54:57], v75 offset:32768
	ds_read_b128 v[50:53], v76 offset:32768
	ds_read_b128 v[62:65], v77 offset:32768
	v_max_f32_e32 v3, 0, v17
	v_fmac_f32_e32 v2, v89, v3
	v_cmp_gt_i32_e32 vcc, 0, v2
	v_not_b32_e32 v3, v2
	v_or_b32_e32 v4, 0x80000000, v2
	v_cndmask_b32_e32 v2, v4, v3, vcc
	v_cmp_le_u32_e32 vcc, v151, v87
	s_nop 1
	v_cndmask_b32_e32 v250, 0, v2, vcc
.LBB0_629:
	v_mov_b32_e32 v200, 0
	s_cmp_gt_u32 s2, 0x73f
	s_cbranch_scc0 .Lidxp_e58
	s_waitcnt lgkmcnt(0)
	v_mfma_f32_32x32x16_bf16 v[2:17], v[38:41], v[58:61], 0
	v_max_f32_e32 v18, 0, v18
	v_max_f32_e32 v19, 0, v19
	v_fma_f32 v18, v174, v18, 0
	v_max_f32_e32 v20, 0, v20
	v_fmac_f32_e32 v18, v173, v19
	v_max_f32_e32 v21, 0, v21
	v_fmac_f32_e32 v18, v172, v20
	v_max_f32_e32 v22, 0, v22
	v_fmac_f32_e32 v18, v171, v21
	v_max_f32_e32 v23, 0, v23
	v_mfma_f32_32x32x16_bf16 v[2:17], v[46:49], v[54:57], v[2:17]
	v_fmac_f32_e32 v18, v170, v22
	v_max_f32_e32 v24, 0, v24
	v_fmac_f32_e32 v18, v169, v23
	v_max_f32_e32 v25, 0, v25
	v_fmac_f32_e32 v18, v168, v24
	v_max_f32_e32 v26, 0, v26
	v_fmac_f32_e32 v18, v167, v25
	v_max_f32_e32 v27, 0, v27
	v_fmac_f32_e32 v18, v166, v26
	v_max_f32_e32 v28, 0, v28
	v_mfma_f32_32x32x16_bf16 v[2:17], v[34:37], v[50:53], v[2:17]
	v_fmac_f32_e32 v18, v165, v27
	v_max_f32_e32 v29, 0, v29
	v_fmac_f32_e32 v18, v164, v28
	v_max_f32_e32 v30, 0, v30
	v_fmac_f32_e32 v18, v163, v29
	v_fmac_f32_e32 v18, v162, v30
	v_max_f32_e32 v19, 0, v31
	v_fmac_f32_e32 v18, v161, v19
	v_max_f32_e32 v19, 0, v32
	v_fmac_f32_e32 v18, v160, v19
	v_mfma_f32_32x32x16_bf16 v[2:17], v[42:45], v[62:65], v[2:17]
	ds_read_b128 v[58:61], v74 offset:36864
	ds_read_b128 v[54:57], v75 offset:36864
	ds_read_b128 v[50:53], v76 offset:36864
	ds_read_b128 v[62:65], v77 offset:36864
	v_max_f32_e32 v19, 0, v33
	v_fmac_f32_e32 v18, v89, v19
	v_cmp_gt_i32_e32 vcc, 0, v18
	v_not_b32_e32 v19, v18
	v_or_b32_e32 v20, 0x80000000, v18
	v_cndmask_b32_e32 v18, v20, v19, vcc
	v_cmp_le_u32_e32 vcc, v152, v87
	s_nop 1
	v_cndmask_b32_e32 v199, 0, v18, vcc
.LBB0_633:
	v_mov_b32_e32 v207, 0
	s_cmp_gt_u32 s2, 0x75f
	s_cbranch_scc0 .Lidxp_e59
	s_waitcnt lgkmcnt(0)
	v_mfma_f32_32x32x16_bf16 v[18:33], v[38:41], v[58:61], 0
	v_max_f32_e32 v2, 0, v2
	v_max_f32_e32 v3, 0, v3
	v_fma_f32 v2, v174, v2, 0
	v_max_f32_e32 v4, 0, v4
	v_fmac_f32_e32 v2, v173, v3
	v_max_f32_e32 v5, 0, v5
	v_fmac_f32_e32 v2, v172, v4
	v_max_f32_e32 v6, 0, v6
	v_fmac_f32_e32 v2, v171, v5
	v_max_f32_e32 v7, 0, v7
	v_mfma_f32_32x32x16_bf16 v[18:33], v[46:49], v[54:57], v[18:33]
	v_fmac_f32_e32 v2, v170, v6
	v_max_f32_e32 v8, 0, v8
	v_fmac_f32_e32 v2, v169, v7
	v_max_f32_e32 v9, 0, v9
	v_fmac_f32_e32 v2, v168, v8
	v_max_f32_e32 v10, 0, v10
	v_fmac_f32_e32 v2, v167, v9
	v_max_f32_e32 v11, 0, v11
	v_fmac_f32_e32 v2, v166, v10
	v_max_f32_e32 v12, 0, v12
	v_mfma_f32_32x32x16_bf16 v[18:33], v[34:37], v[50:53], v[18:33]
	v_fmac_f32_e32 v2, v165, v11
	v_max_f32_e32 v13, 0, v13
	v_fmac_f32_e32 v2, v164, v12
	v_max_f32_e32 v14, 0, v14
	v_fmac_f32_e32 v2, v163, v13
	v_fmac_f32_e32 v2, v162, v14
	v_max_f32_e32 v3, 0, v15
	v_fmac_f32_e32 v2, v161, v3
	v_max_f32_e32 v3, 0, v16
	v_fmac_f32_e32 v2, v160, v3
	v_mfma_f32_32x32x16_bf16 v[18:33], v[42:45], v[62:65], v[18:33]
	ds_read_b128 v[58:61], v74 offset:40960
	ds_read_b128 v[54:57], v75 offset:40960
	ds_read_b128 v[50:53], v76 offset:40960
	ds_read_b128 v[62:65], v77 offset:40960
	v_max_f32_e32 v3, 0, v17
	v_fmac_f32_e32 v2, v89, v3
	v_cmp_gt_i32_e32 vcc, 0, v2
	v_not_b32_e32 v3, v2
	v_or_b32_e32 v4, 0x80000000, v2
	v_cndmask_b32_e32 v2, v4, v3, vcc
	v_cmp_le_u32_e32 vcc, v153, v87
	s_nop 1
	v_cndmask_b32_e32 v200, 0, v2, vcc
.LBB0_637:
	v_mov_b32_e32 v208, 0
	s_cmp_gt_u32 s2, 0x77f
	s_cbranch_scc0 .Lidxp_e60
	s_waitcnt lgkmcnt(0)
	v_mfma_f32_32x32x16_bf16 v[2:17], v[38:41], v[58:61], 0
	v_max_f32_e32 v18, 0, v18
	v_max_f32_e32 v19, 0, v19
	v_fma_f32 v18, v174, v18, 0
	v_max_f32_e32 v20, 0, v20
	v_fmac_f32_e32 v18, v173, v19
	v_max_f32_e32 v21, 0, v21
	v_fmac_f32_e32 v18, v172, v20
	v_max_f32_e32 v22, 0, v22
	v_fmac_f32_e32 v18, v171, v21
	v_max_f32_e32 v23, 0, v23
	v_mfma_f32_32x32x16_bf16 v[2:17], v[46:49], v[54:57], v[2:17]
	v_fmac_f32_e32 v18, v170, v22
	v_max_f32_e32 v24, 0, v24
	v_fmac_f32_e32 v18, v169, v23
	v_max_f32_e32 v25, 0, v25
	v_fmac_f32_e32 v18, v168, v24
	v_max_f32_e32 v26, 0, v26
	v_fmac_f32_e32 v18, v167, v25
	v_max_f32_e32 v27, 0, v27
	v_fmac_f32_e32 v18, v166, v26
	v_max_f32_e32 v28, 0, v28
	v_mfma_f32_32x32x16_bf16 v[2:17], v[34:37], v[50:53], v[2:17]
	v_fmac_f32_e32 v18, v165, v27
	v_max_f32_e32 v29, 0, v29
	v_fmac_f32_e32 v18, v164, v28
	v_max_f32_e32 v30, 0, v30
	v_fmac_f32_e32 v18, v163, v29
	v_fmac_f32_e32 v18, v162, v30
	v_max_f32_e32 v19, 0, v31
	v_fmac_f32_e32 v18, v161, v19
	v_max_f32_e32 v19, 0, v32
	v_fmac_f32_e32 v18, v160, v19
	v_mfma_f32_32x32x16_bf16 v[2:17], v[42:45], v[62:65], v[2:17]
	ds_read_b128 v[58:61], v74 offset:45056
	ds_read_b128 v[54:57], v75 offset:45056
	ds_read_b128 v[50:53], v76 offset:45056
	ds_read_b128 v[62:65], v77 offset:45056
	v_max_f32_e32 v19, 0, v33
	v_fmac_f32_e32 v18, v89, v19
	v_cmp_gt_i32_e32 vcc, 0, v18
	v_not_b32_e32 v19, v18
	v_or_b32_e32 v20, 0x80000000, v18
	v_cndmask_b32_e32 v18, v20, v19, vcc
	v_cmp_le_u32_e32 vcc, v154, v87
	s_nop 1
	v_cndmask_b32_e32 v207, 0, v18, vcc
.LBB0_641:
	v_mov_b32_e32 v210, 0
	s_cmp_gt_u32 s2, 0x79f
	s_cbranch_scc0 .Lidxp_e61
	s_waitcnt lgkmcnt(0)
	v_mfma_f32_32x32x16_bf16 v[18:33], v[38:41], v[58:61], 0
	v_max_f32_e32 v2, 0, v2
	v_max_f32_e32 v3, 0, v3
	v_fma_f32 v2, v174, v2, 0
	v_max_f32_e32 v4, 0, v4
	v_fmac_f32_e32 v2, v173, v3
	v_max_f32_e32 v5, 0, v5
	v_fmac_f32_e32 v2, v172, v4
	v_max_f32_e32 v6, 0, v6
	v_fmac_f32_e32 v2, v171, v5
	v_max_f32_e32 v7, 0, v7
	v_mfma_f32_32x32x16_bf16 v[18:33], v[46:49], v[54:57], v[18:33]
	v_fmac_f32_e32 v2, v170, v6
	v_max_f32_e32 v8, 0, v8
	v_fmac_f32_e32 v2, v169, v7
	v_max_f32_e32 v9, 0, v9
	v_fmac_f32_e32 v2, v168, v8
	v_max_f32_e32 v10, 0, v10
	v_fmac_f32_e32 v2, v167, v9
	v_max_f32_e32 v11, 0, v11
	v_fmac_f32_e32 v2, v166, v10
	v_max_f32_e32 v12, 0, v12
	v_mfma_f32_32x32x16_bf16 v[18:33], v[34:37], v[50:53], v[18:33]
	v_fmac_f32_e32 v2, v165, v11
	v_max_f32_e32 v13, 0, v13
	v_fmac_f32_e32 v2, v164, v12
	v_max_f32_e32 v14, 0, v14
	v_fmac_f32_e32 v2, v163, v13
	v_fmac_f32_e32 v2, v162, v14
	v_max_f32_e32 v3, 0, v15
	v_fmac_f32_e32 v2, v161, v3
	v_max_f32_e32 v3, 0, v16
	v_fmac_f32_e32 v2, v160, v3
	v_mfma_f32_32x32x16_bf16 v[18:33], v[42:45], v[62:65], v[18:33]
	ds_read_b128 v[58:61], v74 offset:49152
	ds_read_b128 v[54:57], v75 offset:49152
	ds_read_b128 v[50:53], v76 offset:49152
	ds_read_b128 v[62:65], v77 offset:49152
	v_max_f32_e32 v3, 0, v17
	v_fmac_f32_e32 v2, v89, v3
	v_cmp_gt_i32_e32 vcc, 0, v2
	v_not_b32_e32 v3, v2
	v_or_b32_e32 v4, 0x80000000, v2
	v_cndmask_b32_e32 v2, v4, v3, vcc
	v_cmp_le_u32_e32 vcc, v155, v87
	s_nop 1
	v_cndmask_b32_e32 v208, 0, v2, vcc
.LBB0_645:
	v_lshrrev_b32_e32 v201, 5, v177
	v_mov_b32_e32 v70, 0
	s_cmp_gt_u32 s2, 0x7bf
	s_cbranch_scc0 .Lidxp_e62
	s_waitcnt lgkmcnt(0)
	v_mfma_f32_32x32x16_bf16 v[2:17], v[38:41], v[58:61], 0
	v_max_f32_e32 v18, 0, v18
	v_max_f32_e32 v19, 0, v19
	v_fma_f32 v18, v174, v18, 0
	v_max_f32_e32 v20, 0, v20
	v_fmac_f32_e32 v18, v173, v19
	v_max_f32_e32 v21, 0, v21
	v_fmac_f32_e32 v18, v172, v20
	v_max_f32_e32 v22, 0, v22
	v_fmac_f32_e32 v18, v171, v21
	v_max_f32_e32 v23, 0, v23
	v_mfma_f32_32x32x16_bf16 v[2:17], v[46:49], v[54:57], v[2:17]
	v_fmac_f32_e32 v18, v170, v22
	v_max_f32_e32 v24, 0, v24
	v_fmac_f32_e32 v18, v169, v23
	v_max_f32_e32 v25, 0, v25
	v_fmac_f32_e32 v18, v168, v24
	v_max_f32_e32 v26, 0, v26
	v_fmac_f32_e32 v18, v167, v25
	v_max_f32_e32 v27, 0, v27
	v_fmac_f32_e32 v18, v166, v26
	v_max_f32_e32 v28, 0, v28
	v_mfma_f32_32x32x16_bf16 v[2:17], v[34:37], v[50:53], v[2:17]
	v_fmac_f32_e32 v18, v165, v27
	v_max_f32_e32 v29, 0, v29
	v_fmac_f32_e32 v18, v164, v28
	v_max_f32_e32 v30, 0, v30
	v_fmac_f32_e32 v18, v163, v29
	v_fmac_f32_e32 v18, v162, v30
	v_max_f32_e32 v19, 0, v31
	v_fmac_f32_e32 v18, v161, v19
	v_max_f32_e32 v19, 0, v32
	v_fmac_f32_e32 v18, v160, v19
	v_mfma_f32_32x32x16_bf16 v[2:17], v[42:45], v[62:65], v[2:17]
	ds_read_b128 v[58:61], v74 offset:53248
	ds_read_b128 v[54:57], v75 offset:53248
	ds_read_b128 v[50:53], v76 offset:53248
	ds_read_b128 v[62:65], v77 offset:53248
	v_max_f32_e32 v19, 0, v33
	v_fmac_f32_e32 v18, v89, v19
	v_cmp_gt_i32_e32 vcc, 0, v18
	v_not_b32_e32 v19, v18
	v_or_b32_e32 v20, 0x80000000, v18
	v_cndmask_b32_e32 v18, v20, v19, vcc
	v_cmp_le_u32_e32 vcc, v156, v87
	s_nop 1
	v_cndmask_b32_e32 v210, 0, v18, vcc
.LBB0_649:
	v_mov_b32_e32 v66, 0
	v_mov_b32_e32 v18, 0
	s_cmp_gt_u32 s2, 0x7df
	s_cbranch_scc0 .Lidxp_e63
	s_waitcnt lgkmcnt(0)
	v_mfma_f32_32x32x16_bf16 v[18:33], v[38:41], v[58:61], 0
	v_max_f32_e32 v2, 0, v2
	v_max_f32_e32 v3, 0, v3
	v_fma_f32 v2, v174, v2, 0
	v_max_f32_e32 v4, 0, v4
	v_fmac_f32_e32 v2, v173, v3
	v_max_f32_e32 v5, 0, v5
	v_fmac_f32_e32 v2, v172, v4
	v_max_f32_e32 v6, 0, v6
	v_fmac_f32_e32 v2, v171, v5
	v_max_f32_e32 v7, 0, v7
	v_mfma_f32_32x32x16_bf16 v[18:33], v[46:49], v[54:57], v[18:33]
	v_fmac_f32_e32 v2, v170, v6
	v_max_f32_e32 v8, 0, v8
	v_fmac_f32_e32 v2, v169, v7
	v_max_f32_e32 v9, 0, v9
	v_fmac_f32_e32 v2, v168, v8
	v_max_f32_e32 v10, 0, v10
	v_fmac_f32_e32 v2, v167, v9
	v_max_f32_e32 v11, 0, v11
	v_fmac_f32_e32 v2, v166, v10
	v_max_f32_e32 v12, 0, v12
	v_mfma_f32_32x32x16_bf16 v[18:33], v[34:37], v[50:53], v[18:33]
	v_fmac_f32_e32 v2, v165, v11
	v_max_f32_e32 v13, 0, v13
	v_fmac_f32_e32 v2, v164, v12
	v_max_f32_e32 v14, 0, v14
	v_fmac_f32_e32 v2, v163, v13
	v_fmac_f32_e32 v2, v162, v14
	v_max_f32_e32 v3, 0, v15
	v_fmac_f32_e32 v2, v161, v3
	v_max_f32_e32 v3, 0, v16
	v_fmac_f32_e32 v2, v160, v3
	v_mfma_f32_32x32x16_bf16 v[18:33], v[42:45], v[62:65], v[18:33]
	v_max_f32_e32 v3, 0, v17
	v_fmac_f32_e32 v2, v89, v3
	v_cmp_gt_i32_e32 vcc, 0, v2
	v_not_b32_e32 v3, v2
	v_or_b32_e32 v4, 0x80000000, v2
	v_cndmask_b32_e32 v2, v4, v3, vcc
	v_cmp_le_u32_e32 vcc, v157, v87
	s_nop 1
	v_cndmask_b32_e32 v70, 0, v2, vcc
.LBB0_651:
	s_nop 11
	v_max_f32_e32 v18, 0, v18
	v_max_f32_e32 v19, 0, v19
	v_fma_f32 v18, v174, v18, 0
	v_max_f32_e32 v20, 0, v20
	v_fmac_f32_e32 v18, v173, v19
	v_max_f32_e32 v21, 0, v21
	v_fmac_f32_e32 v18, v172, v20
	v_max_f32_e32 v22, 0, v22
	v_fmac_f32_e32 v18, v171, v21
	v_max_f32_e32 v23, 0, v23
	v_fmac_f32_e32 v18, v170, v22
	v_max_f32_e32 v24, 0, v24
	v_fmac_f32_e32 v18, v169, v23
	v_max_f32_e32 v25, 0, v25
	v_fmac_f32_e32 v18, v168, v24
	v_max_f32_e32 v26, 0, v26
	v_fmac_f32_e32 v18, v167, v25
	v_max_f32_e32 v27, 0, v27
	v_fmac_f32_e32 v18, v166, v26
	v_max_f32_e32 v28, 0, v28
	v_fmac_f32_e32 v18, v165, v27
	v_max_f32_e32 v29, 0, v29
	v_fmac_f32_e32 v18, v164, v28
	v_max_f32_e32 v30, 0, v30
	v_fmac_f32_e32 v18, v163, v29
	v_max_f32_e32 v31, 0, v31
	v_fmac_f32_e32 v18, v162, v30
	v_max_f32_e32 v32, 0, v32
	v_fmac_f32_e32 v18, v161, v31
	v_fmac_f32_e32 v18, v160, v32
	v_max_f32_e32 v19, 0, v33
	v_fmac_f32_e32 v18, v89, v19
	v_cmp_gt_i32_e32 vcc, 0, v18
	v_not_b32_e32 v19, v18
	v_or_b32_e32 v20, 0x80000000, v18
	v_cndmask_b32_e32 v18, v20, v19, vcc
	v_cmp_le_u32_e32 vcc, v158, v87
	s_nop 1
	v_cndmask_b32_e32 v18, 0, v18, vcc
	s_branch .Lidxp_end
.Lidxp_e1:
	s_nop 11
	v_max_f32_e32 v2, 0, v2
	v_fma_f32 v2, v174, v2, 0
	v_max_f32_e32 v3, 0, v3
	v_fmac_f32_e32 v2, v173, v3
	v_max_f32_e32 v3, 0, v4
	v_fmac_f32_e32 v2, v172, v3
	v_max_f32_e32 v3, 0, v5
	v_fmac_f32_e32 v2, v171, v3
	v_max_f32_e32 v3, 0, v6
	v_fmac_f32_e32 v2, v170, v3
	v_max_f32_e32 v3, 0, v7
	v_fmac_f32_e32 v2, v169, v3
	v_max_f32_e32 v3, 0, v8
	v_fmac_f32_e32 v2, v168, v3
	v_max_f32_e32 v3, 0, v9
	v_fmac_f32_e32 v2, v167, v3
	v_max_f32_e32 v3, 0, v10
	v_fmac_f32_e32 v2, v166, v3
	v_max_f32_e32 v3, 0, v11
	v_fmac_f32_e32 v2, v165, v3
	v_max_f32_e32 v3, 0, v12
	v_fmac_f32_e32 v2, v164, v3
	v_max_f32_e32 v3, 0, v13
	v_fmac_f32_e32 v2, v163, v3
	v_max_f32_e32 v3, 0, v14
	v_fmac_f32_e32 v2, v162, v3
	v_max_f32_e32 v3, 0, v15
	v_fmac_f32_e32 v2, v161, v3
	v_max_f32_e32 v3, 0, v16
	v_fmac_f32_e32 v2, v160, v3
	v_max_f32_e32 v3, 0, v17
	v_fmac_f32_e32 v2, v89, v3
	v_cmp_gt_i32_e32 vcc, 0, v2
	v_not_b32_e32 v3, v2
	v_or_b32_e32 v4, 0x80000000, v2
	v_cndmask_b32_e32 v2, v4, v3, vcc
	v_cmp_le_u32_e32 vcc, v93, v87
	s_nop 1
	v_cndmask_b32_e32 v81, 0, v2, vcc
	s_branch .Lidxp_w2
.Lidxp_e2:
	v_max_f32_e32 v18, 0, v18
	v_max_f32_e32 v19, 0, v19
	v_fma_f32 v18, v174, v18, 0
	v_max_f32_e32 v20, 0, v20
	v_fmac_f32_e32 v18, v173, v19
	v_max_f32_e32 v21, 0, v21
	v_fmac_f32_e32 v18, v172, v20
	v_max_f32_e32 v22, 0, v22
	v_fmac_f32_e32 v18, v171, v21
	v_max_f32_e32 v23, 0, v23
	v_fmac_f32_e32 v18, v170, v22
	v_max_f32_e32 v24, 0, v24
	v_fmac_f32_e32 v18, v169, v23
	v_max_f32_e32 v25, 0, v25
	v_fmac_f32_e32 v18, v168, v24
	v_max_f32_e32 v26, 0, v26
	v_fmac_f32_e32 v18, v167, v25
	v_max_f32_e32 v27, 0, v27
	v_fmac_f32_e32 v18, v166, v26
	v_max_f32_e32 v28, 0, v28
	v_fmac_f32_e32 v18, v165, v27
	v_max_f32_e32 v29, 0, v29
	v_fmac_f32_e32 v18, v164, v28
	v_max_f32_e32 v30, 0, v30
	v_fmac_f32_e32 v18, v163, v29
	v_fmac_f32_e32 v18, v162, v30
	v_max_f32_e32 v19, 0, v31
	v_fmac_f32_e32 v18, v161, v19
	v_max_f32_e32 v19, 0, v32
	v_fmac_f32_e32 v18, v160, v19
	v_max_f32_e32 v19, 0, v33
	v_fmac_f32_e32 v18, v89, v19
	v_cmp_gt_i32_e32 vcc, 0, v18
	v_not_b32_e32 v19, v18
	v_or_b32_e32 v20, 0x80000000, v18
	v_cndmask_b32_e32 v18, v20, v19, vcc
	v_cmp_le_u32_e32 vcc, v96, v87
	s_nop 1
	v_cndmask_b32_e32 v175, 0, v18, vcc
	s_branch .Lidxp_w3
.Lidxp_e3:
	v_max_f32_e32 v2, 0, v2
	v_max_f32_e32 v3, 0, v3
	v_fma_f32 v2, v174, v2, 0
	v_max_f32_e32 v4, 0, v4
	v_fmac_f32_e32 v2, v173, v3
	v_max_f32_e32 v5, 0, v5
	v_fmac_f32_e32 v2, v172, v4
	v_max_f32_e32 v6, 0, v6
	v_fmac_f32_e32 v2, v171, v5
	v_max_f32_e32 v7, 0, v7
	v_fmac_f32_e32 v2, v170, v6
	v_max_f32_e32 v8, 0, v8
	v_fmac_f32_e32 v2, v169, v7
	v_max_f32_e32 v9, 0, v9
	v_fmac_f32_e32 v2, v168, v8
	v_max_f32_e32 v10, 0, v10
	v_fmac_f32_e32 v2, v167, v9
	v_max_f32_e32 v11, 0, v11
	v_fmac_f32_e32 v2, v166, v10
	v_max_f32_e32 v12, 0, v12
	v_fmac_f32_e32 v2, v165, v11
	v_max_f32_e32 v13, 0, v13
	v_fmac_f32_e32 v2, v164, v12
	v_max_f32_e32 v14, 0, v14
	v_fmac_f32_e32 v2, v163, v13
	v_fmac_f32_e32 v2, v162, v14
	v_max_f32_e32 v3, 0, v15
	v_fmac_f32_e32 v2, v161, v3
	v_max_f32_e32 v3, 0, v16
	v_fmac_f32_e32 v2, v160, v3
	v_max_f32_e32 v3, 0, v17
	v_fmac_f32_e32 v2, v89, v3
	v_cmp_gt_i32_e32 vcc, 0, v2
	v_not_b32_e32 v3, v2
	v_or_b32_e32 v4, 0x80000000, v2
	v_cndmask_b32_e32 v2, v4, v3, vcc
	v_cmp_le_u32_e32 vcc, v97, v87
	s_nop 1
	v_cndmask_b32_e32 v176, 0, v2, vcc
	s_branch .Lidxp_w4
.Lidxp_e4:
	v_max_f32_e32 v18, 0, v18
	v_max_f32_e32 v19, 0, v19
	v_fma_f32 v18, v174, v18, 0
	v_max_f32_e32 v20, 0, v20
	v_fmac_f32_e32 v18, v173, v19
	v_max_f32_e32 v21, 0, v21
	v_fmac_f32_e32 v18, v172, v20
	v_max_f32_e32 v22, 0, v22
	v_fmac_f32_e32 v18, v171, v21
	v_max_f32_e32 v23, 0, v23
	v_fmac_f32_e32 v18, v170, v22
	v_max_f32_e32 v24, 0, v24
	v_fmac_f32_e32 v18, v169, v23
	v_max_f32_e32 v25, 0, v25
	v_fmac_f32_e32 v18, v168, v24
	v_max_f32_e32 v26, 0, v26
	v_fmac_f32_e32 v18, v167, v25
	v_max_f32_e32 v27, 0, v27
	v_fmac_f32_e32 v18, v166, v26
	v_max_f32_e32 v28, 0, v28
	v_fmac_f32_e32 v18, v165, v27
	v_max_f32_e32 v29, 0, v29
	v_fmac_f32_e32 v18, v164, v28
	v_max_f32_e32 v30, 0, v30
	v_fmac_f32_e32 v18, v163, v29
	v_fmac_f32_e32 v18, v162, v30
	v_max_f32_e32 v19, 0, v31
	v_fmac_f32_e32 v18, v161, v19
	v_max_f32_e32 v19, 0, v32
	v_fmac_f32_e32 v18, v160, v19
	v_max_f32_e32 v19, 0, v33
	v_fmac_f32_e32 v18, v89, v19
	v_cmp_gt_i32_e32 vcc, 0, v18
	v_not_b32_e32 v19, v18
	v_or_b32_e32 v20, 0x80000000, v18
	v_cndmask_b32_e32 v18, v20, v19, vcc
	v_cmp_le_u32_e32 vcc, v98, v87
	s_nop 1
	v_cndmask_b32_e32 v179, 0, v18, vcc
	s_branch .Lidxp_w5
.Lidxp_e5:
	v_max_f32_e32 v2, 0, v2
	v_max_f32_e32 v3, 0, v3
	v_fma_f32 v2, v174, v2, 0
	v_max_f32_e32 v4, 0, v4
	v_fmac_f32_e32 v2, v173, v3
	v_max_f32_e32 v5, 0, v5
	v_fmac_f32_e32 v2, v172, v4
	v_max_f32_e32 v6, 0, v6
	v_fmac_f32_e32 v2, v171, v5
	v_max_f32_e32 v7, 0, v7
	v_fmac_f32_e32 v2, v170, v6
	v_max_f32_e32 v8, 0, v8
	v_fmac_f32_e32 v2, v169, v7
	v_max_f32_e32 v9, 0, v9
	v_fmac_f32_e32 v2, v168, v8
	v_max_f32_e32 v10, 0, v10
	v_fmac_f32_e32 v2, v167, v9
	v_max_f32_e32 v11, 0, v11
	v_fmac_f32_e32 v2, v166, v10
	v_max_f32_e32 v12, 0, v12
	v_fmac_f32_e32 v2, v165, v11
	v_max_f32_e32 v13, 0, v13
	v_fmac_f32_e32 v2, v164, v12
	v_max_f32_e32 v14, 0, v14
	v_fmac_f32_e32 v2, v163, v13
	v_fmac_f32_e32 v2, v162, v14
	v_max_f32_e32 v3, 0, v15
	v_fmac_f32_e32 v2, v161, v3
	v_max_f32_e32 v3, 0, v16
	v_fmac_f32_e32 v2, v160, v3
	v_max_f32_e32 v3, 0, v17
	v_fmac_f32_e32 v2, v89, v3
	v_cmp_gt_i32_e32 vcc, 0, v2
	v_not_b32_e32 v3, v2
	v_or_b32_e32 v4, 0x80000000, v2
	v_cndmask_b32_e32 v2, v4, v3, vcc
	v_cmp_le_u32_e32 vcc, v99, v87
	s_nop 1
	v_cndmask_b32_e32 v180, 0, v2, vcc
	s_branch .Lidxp_w6
.Lidxp_e6:
	v_max_f32_e32 v18, 0, v18
	v_max_f32_e32 v19, 0, v19
	v_fma_f32 v18, v174, v18, 0
	v_max_f32_e32 v20, 0, v20
	v_fmac_f32_e32 v18, v173, v19
	v_max_f32_e32 v21, 0, v21
	v_fmac_f32_e32 v18, v172, v20
	v_max_f32_e32 v22, 0, v22
	v_fmac_f32_e32 v18, v171, v21
	v_max_f32_e32 v23, 0, v23
	v_fmac_f32_e32 v18, v170, v22
	v_max_f32_e32 v24, 0, v24
	v_fmac_f32_e32 v18, v169, v23
	v_max_f32_e32 v25, 0, v25
	v_fmac_f32_e32 v18, v168, v24
	v_max_f32_e32 v26, 0, v26
	v_fmac_f32_e32 v18, v167, v25
	v_max_f32_e32 v27, 0, v27
	v_fmac_f32_e32 v18, v166, v26
	v_max_f32_e32 v28, 0, v28
	v_fmac_f32_e32 v18, v165, v27
	v_max_f32_e32 v29, 0, v29
	v_fmac_f32_e32 v18, v164, v28
	v_max_f32_e32 v30, 0, v30
	v_fmac_f32_e32 v18, v163, v29
	v_fmac_f32_e32 v18, v162, v30
	v_max_f32_e32 v19, 0, v31
	v_fmac_f32_e32 v18, v161, v19
	v_max_f32_e32 v19, 0, v32
	v_fmac_f32_e32 v18, v160, v19
	v_max_f32_e32 v19, 0, v33
	v_fmac_f32_e32 v18, v89, v19
	v_cmp_gt_i32_e32 vcc, 0, v18
	v_not_b32_e32 v19, v18
	v_or_b32_e32 v20, 0x80000000, v18
	v_cndmask_b32_e32 v18, v20, v19, vcc
	v_cmp_le_u32_e32 vcc, v100, v87
	s_nop 1
	v_cndmask_b32_e32 v181, 0, v18, vcc
	s_branch .Lidxp_w7
.Lidxp_e7:
	v_max_f32_e32 v2, 0, v2
	v_max_f32_e32 v3, 0, v3
	v_fma_f32 v2, v174, v2, 0
	v_max_f32_e32 v4, 0, v4
	v_fmac_f32_e32 v2, v173, v3
	v_max_f32_e32 v5, 0, v5
	v_fmac_f32_e32 v2, v172, v4
	v_max_f32_e32 v6, 0, v6
	v_fmac_f32_e32 v2, v171, v5
	v_max_f32_e32 v7, 0, v7
	v_fmac_f32_e32 v2, v170, v6
	v_max_f32_e32 v8, 0, v8
	v_fmac_f32_e32 v2, v169, v7
	v_max_f32_e32 v9, 0, v9
	v_fmac_f32_e32 v2, v168, v8
	v_max_f32_e32 v10, 0, v10
	v_fmac_f32_e32 v2, v167, v9
	v_max_f32_e32 v11, 0, v11
	v_fmac_f32_e32 v2, v166, v10
	v_max_f32_e32 v12, 0, v12
	v_fmac_f32_e32 v2, v165, v11
	v_max_f32_e32 v13, 0, v13
	v_fmac_f32_e32 v2, v164, v12
	v_max_f32_e32 v14, 0, v14
	v_fmac_f32_e32 v2, v163, v13
	v_fmac_f32_e32 v2, v162, v14
	v_max_f32_e32 v3, 0, v15
	v_fmac_f32_e32 v2, v161, v3
	v_max_f32_e32 v3, 0, v16
	v_fmac_f32_e32 v2, v160, v3
	v_max_f32_e32 v3, 0, v17
	v_fmac_f32_e32 v2, v89, v3
	v_cmp_gt_i32_e32 vcc, 0, v2
	v_not_b32_e32 v3, v2
	v_or_b32_e32 v4, 0x80000000, v2
	v_cndmask_b32_e32 v2, v4, v3, vcc
	v_cmp_le_u32_e32 vcc, v101, v87
	s_nop 1
	v_cndmask_b32_e32 v182, 0, v2, vcc
	s_branch .Lidxp_w8
.Lidxp_e8:
	v_max_f32_e32 v18, 0, v18
	v_max_f32_e32 v19, 0, v19
	v_fma_f32 v18, v174, v18, 0
	v_max_f32_e32 v20, 0, v20
	v_fmac_f32_e32 v18, v173, v19
	v_max_f32_e32 v21, 0, v21
	v_fmac_f32_e32 v18, v172, v20
	v_max_f32_e32 v22, 0, v22
	v_fmac_f32_e32 v18, v171, v21
	v_max_f32_e32 v23, 0, v23
	v_fmac_f32_e32 v18, v170, v22
	v_max_f32_e32 v24, 0, v24
	v_fmac_f32_e32 v18, v169, v23
	v_max_f32_e32 v25, 0, v25
	v_fmac_f32_e32 v18, v168, v24
	v_max_f32_e32 v26, 0, v26
	v_fmac_f32_e32 v18, v167, v25
	v_max_f32_e32 v27, 0, v27
	v_fmac_f32_e32 v18, v166, v26
	v_max_f32_e32 v28, 0, v28
	v_fmac_f32_e32 v18, v165, v27
	v_max_f32_e32 v29, 0, v29
	v_fmac_f32_e32 v18, v164, v28
	v_max_f32_e32 v30, 0, v30
	v_fmac_f32_e32 v18, v163, v29
	v_fmac_f32_e32 v18, v162, v30
	v_max_f32_e32 v19, 0, v31
	v_fmac_f32_e32 v18, v161, v19
	v_max_f32_e32 v19, 0, v32
	v_fmac_f32_e32 v18, v160, v19
	v_max_f32_e32 v19, 0, v33
	v_fmac_f32_e32 v18, v89, v19
	v_cmp_gt_i32_e32 vcc, 0, v18
	v_not_b32_e32 v19, v18
	v_or_b32_e32 v20, 0x80000000, v18
	v_cndmask_b32_e32 v18, v20, v19, vcc
	v_cmp_le_u32_e32 vcc, v102, v87
	s_nop 1
	v_cndmask_b32_e32 v183, 0, v18, vcc
	s_branch .Lidxp_w9
.Lidxp_e9:
	v_max_f32_e32 v2, 0, v2
	v_max_f32_e32 v3, 0, v3
	v_fma_f32 v2, v174, v2, 0
	v_max_f32_e32 v4, 0, v4
	v_fmac_f32_e32 v2, v173, v3
	v_max_f32_e32 v5, 0, v5
	v_fmac_f32_e32 v2, v172, v4
	v_max_f32_e32 v6, 0, v6
	v_fmac_f32_e32 v2, v171, v5
	v_max_f32_e32 v7, 0, v7
	v_fmac_f32_e32 v2, v170, v6
	v_max_f32_e32 v8, 0, v8
	v_fmac_f32_e32 v2, v169, v7
	v_max_f32_e32 v9, 0, v9
	v_fmac_f32_e32 v2, v168, v8
	v_max_f32_e32 v10, 0, v10
	v_fmac_f32_e32 v2, v167, v9
	v_max_f32_e32 v11, 0, v11
	v_fmac_f32_e32 v2, v166, v10
	v_max_f32_e32 v12, 0, v12
	v_fmac_f32_e32 v2, v165, v11
	v_max_f32_e32 v13, 0, v13
	v_fmac_f32_e32 v2, v164, v12
	v_max_f32_e32 v14, 0, v14
	v_fmac_f32_e32 v2, v163, v13
	v_fmac_f32_e32 v2, v162, v14
	v_max_f32_e32 v3, 0, v15
	v_fmac_f32_e32 v2, v161, v3
	v_max_f32_e32 v3, 0, v16
	v_fmac_f32_e32 v2, v160, v3
	v_max_f32_e32 v3, 0, v17
	v_fmac_f32_e32 v2, v89, v3
	v_cmp_gt_i32_e32 vcc, 0, v2
	v_not_b32_e32 v3, v2
	v_or_b32_e32 v4, 0x80000000, v2
	v_cndmask_b32_e32 v2, v4, v3, vcc
	v_cmp_le_u32_e32 vcc, v103, v87
	s_nop 1
	v_cndmask_b32_e32 v184, 0, v2, vcc
	s_branch .Lidxp_w10
.Lidxp_e10:
	v_max_f32_e32 v18, 0, v18
	v_max_f32_e32 v19, 0, v19
	v_fma_f32 v18, v174, v18, 0
	v_max_f32_e32 v20, 0, v20
	v_fmac_f32_e32 v18, v173, v19
	v_max_f32_e32 v21, 0, v21
	v_fmac_f32_e32 v18, v172, v20
	v_max_f32_e32 v22, 0, v22
	v_fmac_f32_e32 v18, v171, v21
	v_max_f32_e32 v23, 0, v23
	v_fmac_f32_e32 v18, v170, v22
	v_max_f32_e32 v24, 0, v24
	v_fmac_f32_e32 v18, v169, v23
	v_max_f32_e32 v25, 0, v25
	v_fmac_f32_e32 v18, v168, v24
	v_max_f32_e32 v26, 0, v26
	v_fmac_f32_e32 v18, v167, v25
	v_max_f32_e32 v27, 0, v27
	v_fmac_f32_e32 v18, v166, v26
	v_max_f32_e32 v28, 0, v28
	v_fmac_f32_e32 v18, v165, v27
	v_max_f32_e32 v29, 0, v29
	v_fmac_f32_e32 v18, v164, v28
	v_max_f32_e32 v30, 0, v30
	v_fmac_f32_e32 v18, v163, v29
	v_fmac_f32_e32 v18, v162, v30
	v_max_f32_e32 v19, 0, v31
	v_fmac_f32_e32 v18, v161, v19
	v_max_f32_e32 v19, 0, v32
	v_fmac_f32_e32 v18, v160, v19
	v_max_f32_e32 v19, 0, v33
	v_fmac_f32_e32 v18, v89, v19
	v_cmp_gt_i32_e32 vcc, 0, v18
	v_not_b32_e32 v19, v18
	v_or_b32_e32 v20, 0x80000000, v18
	v_cndmask_b32_e32 v18, v20, v19, vcc
	v_cmp_le_u32_e32 vcc, v104, v87
	s_nop 1
	v_cndmask_b32_e32 v185, 0, v18, vcc
	s_branch .Lidxp_w11
.Lidxp_e11:
	v_max_f32_e32 v2, 0, v2
	v_max_f32_e32 v3, 0, v3
	v_fma_f32 v2, v174, v2, 0
	v_max_f32_e32 v4, 0, v4
	v_fmac_f32_e32 v2, v173, v3
	v_max_f32_e32 v5, 0, v5
	v_fmac_f32_e32 v2, v172, v4
	v_max_f32_e32 v6, 0, v6
	v_fmac_f32_e32 v2, v171, v5
	v_max_f32_e32 v7, 0, v7
	v_fmac_f32_e32 v2, v170, v6
	v_max_f32_e32 v8, 0, v8
	v_fmac_f32_e32 v2, v169, v7
	v_max_f32_e32 v9, 0, v9
	v_fmac_f32_e32 v2, v168, v8
	v_max_f32_e32 v10, 0, v10
	v_fmac_f32_e32 v2, v167, v9
	v_max_f32_e32 v11, 0, v11
	v_fmac_f32_e32 v2, v166, v10
	v_max_f32_e32 v12, 0, v12
	v_fmac_f32_e32 v2, v165, v11
	v_max_f32_e32 v13, 0, v13
	v_fmac_f32_e32 v2, v164, v12
	v_max_f32_e32 v14, 0, v14
	v_fmac_f32_e32 v2, v163, v13
	v_fmac_f32_e32 v2, v162, v14
	v_max_f32_e32 v3, 0, v15
	v_fmac_f32_e32 v2, v161, v3
	v_max_f32_e32 v3, 0, v16
	v_fmac_f32_e32 v2, v160, v3
	v_max_f32_e32 v3, 0, v17
	v_fmac_f32_e32 v2, v89, v3
	v_cmp_gt_i32_e32 vcc, 0, v2
	v_not_b32_e32 v3, v2
	v_or_b32_e32 v4, 0x80000000, v2
	v_cndmask_b32_e32 v2, v4, v3, vcc
	v_cmp_le_u32_e32 vcc, v105, v87
	s_nop 1
	v_cndmask_b32_e32 v186, 0, v2, vcc
	s_branch .Lidxp_w12
.Lidxp_e12:
	v_max_f32_e32 v18, 0, v18
	v_max_f32_e32 v19, 0, v19
	v_fma_f32 v18, v174, v18, 0
	v_max_f32_e32 v20, 0, v20
	v_fmac_f32_e32 v18, v173, v19
	v_max_f32_e32 v21, 0, v21
	v_fmac_f32_e32 v18, v172, v20
	v_max_f32_e32 v22, 0, v22
	v_fmac_f32_e32 v18, v171, v21
	v_max_f32_e32 v23, 0, v23
	v_fmac_f32_e32 v18, v170, v22
	v_max_f32_e32 v24, 0, v24
	v_fmac_f32_e32 v18, v169, v23
	v_max_f32_e32 v25, 0, v25
	v_fmac_f32_e32 v18, v168, v24
	v_max_f32_e32 v26, 0, v26
	v_fmac_f32_e32 v18, v167, v25
	v_max_f32_e32 v27, 0, v27
	v_fmac_f32_e32 v18, v166, v26
	v_max_f32_e32 v28, 0, v28
	v_fmac_f32_e32 v18, v165, v27
	v_max_f32_e32 v29, 0, v29
	v_fmac_f32_e32 v18, v164, v28
	v_max_f32_e32 v30, 0, v30
	v_fmac_f32_e32 v18, v163, v29
	v_fmac_f32_e32 v18, v162, v30
	v_max_f32_e32 v19, 0, v31
	v_fmac_f32_e32 v18, v161, v19
	v_max_f32_e32 v19, 0, v32
	v_fmac_f32_e32 v18, v160, v19
	v_max_f32_e32 v19, 0, v33
	v_fmac_f32_e32 v18, v89, v19
	v_cmp_gt_i32_e32 vcc, 0, v18
	v_not_b32_e32 v19, v18
	v_or_b32_e32 v20, 0x80000000, v18
	v_cndmask_b32_e32 v18, v20, v19, vcc
	v_cmp_le_u32_e32 vcc, v106, v87
	s_nop 1
	v_cndmask_b32_e32 v187, 0, v18, vcc
	s_branch .Lidxp_w13
.Lidxp_e13:
	v_max_f32_e32 v2, 0, v2
	v_max_f32_e32 v3, 0, v3
	v_fma_f32 v2, v174, v2, 0
	v_max_f32_e32 v4, 0, v4
	v_fmac_f32_e32 v2, v173, v3
	v_max_f32_e32 v5, 0, v5
	v_fmac_f32_e32 v2, v172, v4
	v_max_f32_e32 v6, 0, v6
	v_fmac_f32_e32 v2, v171, v5
	v_max_f32_e32 v7, 0, v7
	v_fmac_f32_e32 v2, v170, v6
	v_max_f32_e32 v8, 0, v8
	v_fmac_f32_e32 v2, v169, v7
	v_max_f32_e32 v9, 0, v9
	v_fmac_f32_e32 v2, v168, v8
	v_max_f32_e32 v10, 0, v10
	v_fmac_f32_e32 v2, v167, v9
	v_max_f32_e32 v11, 0, v11
	v_fmac_f32_e32 v2, v166, v10
	v_max_f32_e32 v12, 0, v12
	v_fmac_f32_e32 v2, v165, v11
	v_max_f32_e32 v13, 0, v13
	v_fmac_f32_e32 v2, v164, v12
	v_max_f32_e32 v14, 0, v14
	v_fmac_f32_e32 v2, v163, v13
	v_fmac_f32_e32 v2, v162, v14
	v_max_f32_e32 v3, 0, v15
	v_fmac_f32_e32 v2, v161, v3
	v_max_f32_e32 v3, 0, v16
	v_fmac_f32_e32 v2, v160, v3
	v_max_f32_e32 v3, 0, v17
	v_fmac_f32_e32 v2, v89, v3
	v_cmp_gt_i32_e32 vcc, 0, v2
	v_not_b32_e32 v3, v2
	v_or_b32_e32 v4, 0x80000000, v2
	v_cndmask_b32_e32 v2, v4, v3, vcc
	v_cmp_le_u32_e32 vcc, v107, v87
	s_nop 1
	v_cndmask_b32_e32 v188, 0, v2, vcc
	s_branch .Lidxp_w14
.Lidxp_e14:
	v_max_f32_e32 v18, 0, v18
	v_max_f32_e32 v19, 0, v19
	v_fma_f32 v18, v174, v18, 0
	v_max_f32_e32 v20, 0, v20
	v_fmac_f32_e32 v18, v173, v19
	v_max_f32_e32 v21, 0, v21
	v_fmac_f32_e32 v18, v172, v20
	v_max_f32_e32 v22, 0, v22
	v_fmac_f32_e32 v18, v171, v21
	v_max_f32_e32 v23, 0, v23
	v_fmac_f32_e32 v18, v170, v22
	v_max_f32_e32 v24, 0, v24
	v_fmac_f32_e32 v18, v169, v23
	v_max_f32_e32 v25, 0, v25
	v_fmac_f32_e32 v18, v168, v24
	v_max_f32_e32 v26, 0, v26
	v_fmac_f32_e32 v18, v167, v25
	v_max_f32_e32 v27, 0, v27
	v_fmac_f32_e32 v18, v166, v26
	v_max_f32_e32 v28, 0, v28
	v_fmac_f32_e32 v18, v165, v27
	v_max_f32_e32 v29, 0, v29
	v_fmac_f32_e32 v18, v164, v28
	v_max_f32_e32 v30, 0, v30
	v_fmac_f32_e32 v18, v163, v29
	v_fmac_f32_e32 v18, v162, v30
	v_max_f32_e32 v19, 0, v31
	v_fmac_f32_e32 v18, v161, v19
	v_max_f32_e32 v19, 0, v32
	v_fmac_f32_e32 v18, v160, v19
	v_max_f32_e32 v19, 0, v33
	v_fmac_f32_e32 v18, v89, v19
	v_cmp_gt_i32_e32 vcc, 0, v18
	v_not_b32_e32 v19, v18
	v_or_b32_e32 v20, 0x80000000, v18
	v_cndmask_b32_e32 v18, v20, v19, vcc
	v_cmp_le_u32_e32 vcc, v108, v87
	s_nop 1
	v_cndmask_b32_e32 v189, 0, v18, vcc
	s_branch .Lidxp_w15
.Lidxp_e15:
	v_max_f32_e32 v2, 0, v2
	v_max_f32_e32 v3, 0, v3
	v_fma_f32 v2, v174, v2, 0
	v_max_f32_e32 v4, 0, v4
	v_fmac_f32_e32 v2, v173, v3
	v_max_f32_e32 v5, 0, v5
	v_fmac_f32_e32 v2, v172, v4
	v_max_f32_e32 v6, 0, v6
	v_fmac_f32_e32 v2, v171, v5
	v_max_f32_e32 v7, 0, v7
	v_fmac_f32_e32 v2, v170, v6
	v_max_f32_e32 v8, 0, v8
	v_fmac_f32_e32 v2, v169, v7
	v_max_f32_e32 v9, 0, v9
	v_fmac_f32_e32 v2, v168, v8
	v_max_f32_e32 v10, 0, v10
	v_fmac_f32_e32 v2, v167, v9
	v_max_f32_e32 v11, 0, v11
	v_fmac_f32_e32 v2, v166, v10
	v_max_f32_e32 v12, 0, v12
	v_fmac_f32_e32 v2, v165, v11
	v_max_f32_e32 v13, 0, v13
	v_fmac_f32_e32 v2, v164, v12
	v_max_f32_e32 v14, 0, v14
	v_fmac_f32_e32 v2, v163, v13
	v_fmac_f32_e32 v2, v162, v14
	v_max_f32_e32 v3, 0, v15
	v_fmac_f32_e32 v2, v161, v3
	v_max_f32_e32 v3, 0, v16
	v_fmac_f32_e32 v2, v160, v3
	v_max_f32_e32 v3, 0, v17
	v_fmac_f32_e32 v2, v89, v3
	v_cmp_gt_i32_e32 vcc, 0, v2
	v_not_b32_e32 v3, v2
	v_or_b32_e32 v4, 0x80000000, v2
	v_cndmask_b32_e32 v2, v4, v3, vcc
	v_cmp_le_u32_e32 vcc, v109, v87
	s_nop 1
	v_cndmask_b32_e32 v190, 0, v2, vcc
	s_branch .Lidxp_w16
.Lidxp_e16:
	v_max_f32_e32 v18, 0, v18
	v_max_f32_e32 v19, 0, v19
	v_fma_f32 v18, v174, v18, 0
	v_max_f32_e32 v20, 0, v20
	v_fmac_f32_e32 v18, v173, v19
	v_max_f32_e32 v21, 0, v21
	v_fmac_f32_e32 v18, v172, v20
	v_max_f32_e32 v22, 0, v22
	v_fmac_f32_e32 v18, v171, v21
	v_max_f32_e32 v23, 0, v23
	v_fmac_f32_e32 v18, v170, v22
	v_max_f32_e32 v24, 0, v24
	v_fmac_f32_e32 v18, v169, v23
	v_max_f32_e32 v25, 0, v25
	v_fmac_f32_e32 v18, v168, v24
	v_max_f32_e32 v26, 0, v26
	v_fmac_f32_e32 v18, v167, v25
	v_max_f32_e32 v27, 0, v27
	v_fmac_f32_e32 v18, v166, v26
	v_max_f32_e32 v28, 0, v28
	v_fmac_f32_e32 v18, v165, v27
	v_max_f32_e32 v29, 0, v29
	v_fmac_f32_e32 v18, v164, v28
	v_max_f32_e32 v30, 0, v30
	v_fmac_f32_e32 v18, v163, v29
	v_fmac_f32_e32 v18, v162, v30
	v_max_f32_e32 v19, 0, v31
	v_fmac_f32_e32 v18, v161, v19
	v_max_f32_e32 v19, 0, v32
	v_fmac_f32_e32 v18, v160, v19
	v_max_f32_e32 v19, 0, v33
	v_fmac_f32_e32 v18, v89, v19
	v_cmp_gt_i32_e32 vcc, 0, v18
	v_not_b32_e32 v19, v18
	v_or_b32_e32 v20, 0x80000000, v18
	v_cndmask_b32_e32 v18, v20, v19, vcc
	v_cmp_le_u32_e32 vcc, v110, v87
	s_nop 1
	v_cndmask_b32_e32 v191, 0, v18, vcc
	s_branch .Lidxp_w17
.Lidxp_e17:
	v_max_f32_e32 v2, 0, v2
	v_max_f32_e32 v3, 0, v3
	v_fma_f32 v2, v174, v2, 0
	v_max_f32_e32 v4, 0, v4
	v_fmac_f32_e32 v2, v173, v3
	v_max_f32_e32 v5, 0, v5
	v_fmac_f32_e32 v2, v172, v4
	v_max_f32_e32 v6, 0, v6
	v_fmac_f32_e32 v2, v171, v5
	v_max_f32_e32 v7, 0, v7
	v_fmac_f32_e32 v2, v170, v6
	v_max_f32_e32 v8, 0, v8
	v_fmac_f32_e32 v2, v169, v7
	v_max_f32_e32 v9, 0, v9
	v_fmac_f32_e32 v2, v168, v8
	v_max_f32_e32 v10, 0, v10
	v_fmac_f32_e32 v2, v167, v9
	v_max_f32_e32 v11, 0, v11
	v_fmac_f32_e32 v2, v166, v10
	v_max_f32_e32 v12, 0, v12
	v_fmac_f32_e32 v2, v165, v11
	v_max_f32_e32 v13, 0, v13
	v_fmac_f32_e32 v2, v164, v12
	v_max_f32_e32 v14, 0, v14
	v_fmac_f32_e32 v2, v163, v13
	v_fmac_f32_e32 v2, v162, v14
	v_max_f32_e32 v3, 0, v15
	v_fmac_f32_e32 v2, v161, v3
	v_max_f32_e32 v3, 0, v16
	v_fmac_f32_e32 v2, v160, v3
	v_max_f32_e32 v3, 0, v17
	v_fmac_f32_e32 v2, v89, v3
	v_cmp_gt_i32_e32 vcc, 0, v2
	v_not_b32_e32 v3, v2
	v_or_b32_e32 v4, 0x80000000, v2
	v_cndmask_b32_e32 v2, v4, v3, vcc
	v_cmp_le_u32_e32 vcc, v111, v87
	s_nop 1
	v_cndmask_b32_e32 v192, 0, v2, vcc
	s_branch .Lidxp_w18
.Lidxp_e18:
	v_max_f32_e32 v18, 0, v18
	v_max_f32_e32 v19, 0, v19
	v_fma_f32 v18, v174, v18, 0
	v_max_f32_e32 v20, 0, v20
	v_fmac_f32_e32 v18, v173, v19
	v_max_f32_e32 v21, 0, v21
	v_fmac_f32_e32 v18, v172, v20
	v_max_f32_e32 v22, 0, v22
	v_fmac_f32_e32 v18, v171, v21
	v_max_f32_e32 v23, 0, v23
	v_fmac_f32_e32 v18, v170, v22
	v_max_f32_e32 v24, 0, v24
	v_fmac_f32_e32 v18, v169, v23
	v_max_f32_e32 v25, 0, v25
	v_fmac_f32_e32 v18, v168, v24
	v_max_f32_e32 v26, 0, v26
	v_fmac_f32_e32 v18, v167, v25
	v_max_f32_e32 v27, 0, v27
	v_fmac_f32_e32 v18, v166, v26
	v_max_f32_e32 v28, 0, v28
	v_fmac_f32_e32 v18, v165, v27
	v_max_f32_e32 v29, 0, v29
	v_fmac_f32_e32 v18, v164, v28
	v_max_f32_e32 v30, 0, v30
	v_fmac_f32_e32 v18, v163, v29
	v_fmac_f32_e32 v18, v162, v30
	v_max_f32_e32 v19, 0, v31
	v_fmac_f32_e32 v18, v161, v19
	v_max_f32_e32 v19, 0, v32
	v_fmac_f32_e32 v18, v160, v19
	v_max_f32_e32 v19, 0, v33
	v_fmac_f32_e32 v18, v89, v19
	v_cmp_gt_i32_e32 vcc, 0, v18
	v_not_b32_e32 v19, v18
	v_or_b32_e32 v20, 0x80000000, v18
	v_cndmask_b32_e32 v18, v20, v19, vcc
	v_cmp_le_u32_e32 vcc, v112, v87
	s_nop 1
	v_cndmask_b32_e32 v193, 0, v18, vcc
	s_branch .Lidxp_w19
.Lidxp_e19:
	v_max_f32_e32 v2, 0, v2
	v_max_f32_e32 v3, 0, v3
	v_fma_f32 v2, v174, v2, 0
	v_max_f32_e32 v4, 0, v4
	v_fmac_f32_e32 v2, v173, v3
	v_max_f32_e32 v5, 0, v5
	v_fmac_f32_e32 v2, v172, v4
	v_max_f32_e32 v6, 0, v6
	v_fmac_f32_e32 v2, v171, v5
	v_max_f32_e32 v7, 0, v7
	v_fmac_f32_e32 v2, v170, v6
	v_max_f32_e32 v8, 0, v8
	v_fmac_f32_e32 v2, v169, v7
	v_max_f32_e32 v9, 0, v9
	v_fmac_f32_e32 v2, v168, v8
	v_max_f32_e32 v10, 0, v10
	v_fmac_f32_e32 v2, v167, v9
	v_max_f32_e32 v11, 0, v11
	v_fmac_f32_e32 v2, v166, v10
	v_max_f32_e32 v12, 0, v12
	v_fmac_f32_e32 v2, v165, v11
	v_max_f32_e32 v13, 0, v13
	v_fmac_f32_e32 v2, v164, v12
	v_max_f32_e32 v14, 0, v14
	v_fmac_f32_e32 v2, v163, v13
	v_fmac_f32_e32 v2, v162, v14
	v_max_f32_e32 v3, 0, v15
	v_fmac_f32_e32 v2, v161, v3
	v_max_f32_e32 v3, 0, v16
	v_fmac_f32_e32 v2, v160, v3
	v_max_f32_e32 v3, 0, v17
	v_fmac_f32_e32 v2, v89, v3
	v_cmp_gt_i32_e32 vcc, 0, v2
	v_not_b32_e32 v3, v2
	v_or_b32_e32 v4, 0x80000000, v2
	v_cndmask_b32_e32 v2, v4, v3, vcc
	v_cmp_le_u32_e32 vcc, v113, v87
	s_nop 1
	v_cndmask_b32_e32 v194, 0, v2, vcc
	s_branch .Lidxp_w20
.Lidxp_e20:
	v_max_f32_e32 v18, 0, v18
	v_max_f32_e32 v19, 0, v19
	v_fma_f32 v18, v174, v18, 0
	v_max_f32_e32 v20, 0, v20
	v_fmac_f32_e32 v18, v173, v19
	v_max_f32_e32 v21, 0, v21
	v_fmac_f32_e32 v18, v172, v20
	v_max_f32_e32 v22, 0, v22
	v_fmac_f32_e32 v18, v171, v21
	v_max_f32_e32 v23, 0, v23
	v_fmac_f32_e32 v18, v170, v22
	v_max_f32_e32 v24, 0, v24
	v_fmac_f32_e32 v18, v169, v23
	v_max_f32_e32 v25, 0, v25
	v_fmac_f32_e32 v18, v168, v24
	v_max_f32_e32 v26, 0, v26
	v_fmac_f32_e32 v18, v167, v25
	v_max_f32_e32 v27, 0, v27
	v_fmac_f32_e32 v18, v166, v26
	v_max_f32_e32 v28, 0, v28
	v_fmac_f32_e32 v18, v165, v27
	v_max_f32_e32 v29, 0, v29
	v_fmac_f32_e32 v18, v164, v28
	v_max_f32_e32 v30, 0, v30
	v_fmac_f32_e32 v18, v163, v29
	v_fmac_f32_e32 v18, v162, v30
	v_max_f32_e32 v19, 0, v31
	v_fmac_f32_e32 v18, v161, v19
	v_max_f32_e32 v19, 0, v32
	v_fmac_f32_e32 v18, v160, v19
	v_max_f32_e32 v19, 0, v33
	v_fmac_f32_e32 v18, v89, v19
	v_cmp_gt_i32_e32 vcc, 0, v18
	v_not_b32_e32 v19, v18
	v_or_b32_e32 v20, 0x80000000, v18
	v_cndmask_b32_e32 v18, v20, v19, vcc
	v_cmp_le_u32_e32 vcc, v114, v87
	s_nop 1
	v_cndmask_b32_e32 v195, 0, v18, vcc
	s_branch .Lidxp_w21
.Lidxp_e21:
	v_max_f32_e32 v2, 0, v2
	v_max_f32_e32 v3, 0, v3
	v_fma_f32 v2, v174, v2, 0
	v_max_f32_e32 v4, 0, v4
	v_fmac_f32_e32 v2, v173, v3
	v_max_f32_e32 v5, 0, v5
	v_fmac_f32_e32 v2, v172, v4
	v_max_f32_e32 v6, 0, v6
	v_fmac_f32_e32 v2, v171, v5
	v_max_f32_e32 v7, 0, v7
	v_fmac_f32_e32 v2, v170, v6
	v_max_f32_e32 v8, 0, v8
	v_fmac_f32_e32 v2, v169, v7
	v_max_f32_e32 v9, 0, v9
	v_fmac_f32_e32 v2, v168, v8
	v_max_f32_e32 v10, 0, v10
	v_fmac_f32_e32 v2, v167, v9
	v_max_f32_e32 v11, 0, v11
	v_fmac_f32_e32 v2, v166, v10
	v_max_f32_e32 v12, 0, v12
	v_fmac_f32_e32 v2, v165, v11
	v_max_f32_e32 v13, 0, v13
	v_fmac_f32_e32 v2, v164, v12
	v_max_f32_e32 v14, 0, v14
	v_fmac_f32_e32 v2, v163, v13
	v_fmac_f32_e32 v2, v162, v14
	v_max_f32_e32 v3, 0, v15
	v_fmac_f32_e32 v2, v161, v3
	v_max_f32_e32 v3, 0, v16
	v_fmac_f32_e32 v2, v160, v3
	v_max_f32_e32 v3, 0, v17
	v_fmac_f32_e32 v2, v89, v3
	v_cmp_gt_i32_e32 vcc, 0, v2
	v_not_b32_e32 v3, v2
	v_or_b32_e32 v4, 0x80000000, v2
	v_cndmask_b32_e32 v2, v4, v3, vcc
	v_cmp_le_u32_e32 vcc, v115, v87
	s_nop 1
	v_cndmask_b32_e32 v196, 0, v2, vcc
	s_branch .Lidxp_w22
.Lidxp_e22:
	v_max_f32_e32 v18, 0, v18
	v_max_f32_e32 v19, 0, v19
	v_fma_f32 v18, v174, v18, 0
	v_max_f32_e32 v20, 0, v20
	v_fmac_f32_e32 v18, v173, v19
	v_max_f32_e32 v21, 0, v21
	v_fmac_f32_e32 v18, v172, v20
	v_max_f32_e32 v22, 0, v22
	v_fmac_f32_e32 v18, v171, v21
	v_max_f32_e32 v23, 0, v23
	v_fmac_f32_e32 v18, v170, v22
	v_max_f32_e32 v24, 0, v24
	v_fmac_f32_e32 v18, v169, v23
	v_max_f32_e32 v25, 0, v25
	v_fmac_f32_e32 v18, v168, v24
	v_max_f32_e32 v26, 0, v26
	v_fmac_f32_e32 v18, v167, v25
	v_max_f32_e32 v27, 0, v27
	v_fmac_f32_e32 v18, v166, v26
	v_max_f32_e32 v28, 0, v28
	v_fmac_f32_e32 v18, v165, v27
	v_max_f32_e32 v29, 0, v29
	v_fmac_f32_e32 v18, v164, v28
	v_max_f32_e32 v30, 0, v30
	v_fmac_f32_e32 v18, v163, v29
	v_fmac_f32_e32 v18, v162, v30
	v_max_f32_e32 v19, 0, v31
	v_fmac_f32_e32 v18, v161, v19
	v_max_f32_e32 v19, 0, v32
	v_fmac_f32_e32 v18, v160, v19
	v_max_f32_e32 v19, 0, v33
	v_fmac_f32_e32 v18, v89, v19
	v_cmp_gt_i32_e32 vcc, 0, v18
	v_not_b32_e32 v19, v18
	v_or_b32_e32 v20, 0x80000000, v18
	v_cndmask_b32_e32 v18, v20, v19, vcc
	v_cmp_le_u32_e32 vcc, v116, v87
	s_nop 1
	v_cndmask_b32_e32 v197, 0, v18, vcc
	s_branch .Lidxp_w23
.Lidxp_e23:
	v_max_f32_e32 v2, 0, v2
	v_max_f32_e32 v3, 0, v3
	v_fma_f32 v2, v174, v2, 0
	v_max_f32_e32 v4, 0, v4
	v_fmac_f32_e32 v2, v173, v3
	v_max_f32_e32 v5, 0, v5
	v_fmac_f32_e32 v2, v172, v4
	v_max_f32_e32 v6, 0, v6
	v_fmac_f32_e32 v2, v171, v5
	v_max_f32_e32 v7, 0, v7
	v_fmac_f32_e32 v2, v170, v6
	v_max_f32_e32 v8, 0, v8
	v_fmac_f32_e32 v2, v169, v7
	v_max_f32_e32 v9, 0, v9
	v_fmac_f32_e32 v2, v168, v8
	v_max_f32_e32 v10, 0, v10
	v_fmac_f32_e32 v2, v167, v9
	v_max_f32_e32 v11, 0, v11
	v_fmac_f32_e32 v2, v166, v10
	v_max_f32_e32 v12, 0, v12
	v_fmac_f32_e32 v2, v165, v11
	v_max_f32_e32 v13, 0, v13
	v_fmac_f32_e32 v2, v164, v12
	v_max_f32_e32 v14, 0, v14
	v_fmac_f32_e32 v2, v163, v13
	v_fmac_f32_e32 v2, v162, v14
	v_max_f32_e32 v3, 0, v15
	v_fmac_f32_e32 v2, v161, v3
	v_max_f32_e32 v3, 0, v16
	v_fmac_f32_e32 v2, v160, v3
	v_max_f32_e32 v3, 0, v17
	v_fmac_f32_e32 v2, v89, v3
	v_cmp_gt_i32_e32 vcc, 0, v2
	v_not_b32_e32 v3, v2
	v_or_b32_e32 v4, 0x80000000, v2
	v_cndmask_b32_e32 v2, v4, v3, vcc
	v_cmp_le_u32_e32 vcc, v117, v87
	s_nop 1
	v_cndmask_b32_e32 v216, 0, v2, vcc
	s_branch .Lidxp_w24
.Lidxp_e24:
	v_max_f32_e32 v18, 0, v18
	v_max_f32_e32 v19, 0, v19
	v_fma_f32 v18, v174, v18, 0
	v_max_f32_e32 v20, 0, v20
	v_fmac_f32_e32 v18, v173, v19
	v_max_f32_e32 v21, 0, v21
	v_fmac_f32_e32 v18, v172, v20
	v_max_f32_e32 v22, 0, v22
	v_fmac_f32_e32 v18, v171, v21
	v_max_f32_e32 v23, 0, v23
	v_fmac_f32_e32 v18, v170, v22
	v_max_f32_e32 v24, 0, v24
	v_fmac_f32_e32 v18, v169, v23
	v_max_f32_e32 v25, 0, v25
	v_fmac_f32_e32 v18, v168, v24
	v_max_f32_e32 v26, 0, v26
	v_fmac_f32_e32 v18, v167, v25
	v_max_f32_e32 v27, 0, v27
	v_fmac_f32_e32 v18, v166, v26
	v_max_f32_e32 v28, 0, v28
	v_fmac_f32_e32 v18, v165, v27
	v_max_f32_e32 v29, 0, v29
	v_fmac_f32_e32 v18, v164, v28
	v_max_f32_e32 v30, 0, v30
	v_fmac_f32_e32 v18, v163, v29
	v_fmac_f32_e32 v18, v162, v30
	v_max_f32_e32 v19, 0, v31
	v_fmac_f32_e32 v18, v161, v19
	v_max_f32_e32 v19, 0, v32
	v_fmac_f32_e32 v18, v160, v19
	v_max_f32_e32 v19, 0, v33
	v_fmac_f32_e32 v18, v89, v19
	v_cmp_gt_i32_e32 vcc, 0, v18
	v_not_b32_e32 v19, v18
	v_or_b32_e32 v20, 0x80000000, v18
	v_cndmask_b32_e32 v18, v20, v19, vcc
	v_cmp_le_u32_e32 vcc, v118, v87
	s_nop 1
	v_cndmask_b32_e32 v217, 0, v18, vcc
	s_branch .Lidxp_w25
.Lidxp_e25:
	v_max_f32_e32 v2, 0, v2
	v_max_f32_e32 v3, 0, v3
	v_fma_f32 v2, v174, v2, 0
	v_max_f32_e32 v4, 0, v4
	v_fmac_f32_e32 v2, v173, v3
	v_max_f32_e32 v5, 0, v5
	v_fmac_f32_e32 v2, v172, v4
	v_max_f32_e32 v6, 0, v6
	v_fmac_f32_e32 v2, v171, v5
	v_max_f32_e32 v7, 0, v7
	v_fmac_f32_e32 v2, v170, v6
	v_max_f32_e32 v8, 0, v8
	v_fmac_f32_e32 v2, v169, v7
	v_max_f32_e32 v9, 0, v9
	v_fmac_f32_e32 v2, v168, v8
	v_max_f32_e32 v10, 0, v10
	v_fmac_f32_e32 v2, v167, v9
	v_max_f32_e32 v11, 0, v11
	v_fmac_f32_e32 v2, v166, v10
	v_max_f32_e32 v12, 0, v12
	v_fmac_f32_e32 v2, v165, v11
	v_max_f32_e32 v13, 0, v13
	v_fmac_f32_e32 v2, v164, v12
	v_max_f32_e32 v14, 0, v14
	v_fmac_f32_e32 v2, v163, v13
	v_fmac_f32_e32 v2, v162, v14
	v_max_f32_e32 v3, 0, v15
	v_fmac_f32_e32 v2, v161, v3
	v_max_f32_e32 v3, 0, v16
	v_fmac_f32_e32 v2, v160, v3
	v_max_f32_e32 v3, 0, v17
	v_fmac_f32_e32 v2, v89, v3
	v_cmp_gt_i32_e32 vcc, 0, v2
	v_not_b32_e32 v3, v2
	v_or_b32_e32 v4, 0x80000000, v2
	v_cndmask_b32_e32 v2, v4, v3, vcc
	v_cmp_le_u32_e32 vcc, v119, v87
	s_nop 1
	v_cndmask_b32_e32 v218, 0, v2, vcc
	s_branch .Lidxp_w26
.Lidxp_e26:
	v_max_f32_e32 v18, 0, v18
	v_max_f32_e32 v19, 0, v19
	v_fma_f32 v18, v174, v18, 0
	v_max_f32_e32 v20, 0, v20
	v_fmac_f32_e32 v18, v173, v19
	v_max_f32_e32 v21, 0, v21
	v_fmac_f32_e32 v18, v172, v20
	v_max_f32_e32 v22, 0, v22
	v_fmac_f32_e32 v18, v171, v21
	v_max_f32_e32 v23, 0, v23
	v_fmac_f32_e32 v18, v170, v22
	v_max_f32_e32 v24, 0, v24
	v_fmac_f32_e32 v18, v169, v23
	v_max_f32_e32 v25, 0, v25
	v_fmac_f32_e32 v18, v168, v24
	v_max_f32_e32 v26, 0, v26
	v_fmac_f32_e32 v18, v167, v25
	v_max_f32_e32 v27, 0, v27
	v_fmac_f32_e32 v18, v166, v26
	v_max_f32_e32 v28, 0, v28
	v_fmac_f32_e32 v18, v165, v27
	v_max_f32_e32 v29, 0, v29
	v_fmac_f32_e32 v18, v164, v28
	v_max_f32_e32 v30, 0, v30
	v_fmac_f32_e32 v18, v163, v29
	v_fmac_f32_e32 v18, v162, v30
	v_max_f32_e32 v19, 0, v31
	v_fmac_f32_e32 v18, v161, v19
	v_max_f32_e32 v19, 0, v32
	v_fmac_f32_e32 v18, v160, v19
	v_max_f32_e32 v19, 0, v33
	v_fmac_f32_e32 v18, v89, v19
	v_cmp_gt_i32_e32 vcc, 0, v18
	v_not_b32_e32 v19, v18
	v_or_b32_e32 v20, 0x80000000, v18
	v_cndmask_b32_e32 v18, v20, v19, vcc
	v_cmp_le_u32_e32 vcc, v120, v87
	s_nop 1
	v_cndmask_b32_e32 v219, 0, v18, vcc
	s_branch .Lidxp_w27
.Lidxp_e27:
	v_max_f32_e32 v2, 0, v2
	v_max_f32_e32 v3, 0, v3
	v_fma_f32 v2, v174, v2, 0
	v_max_f32_e32 v4, 0, v4
	v_fmac_f32_e32 v2, v173, v3
	v_max_f32_e32 v5, 0, v5
	v_fmac_f32_e32 v2, v172, v4
	v_max_f32_e32 v6, 0, v6
	v_fmac_f32_e32 v2, v171, v5
	v_max_f32_e32 v7, 0, v7
	v_fmac_f32_e32 v2, v170, v6
	v_max_f32_e32 v8, 0, v8
	v_fmac_f32_e32 v2, v169, v7
	v_max_f32_e32 v9, 0, v9
	v_fmac_f32_e32 v2, v168, v8
	v_max_f32_e32 v10, 0, v10
	v_fmac_f32_e32 v2, v167, v9
	v_max_f32_e32 v11, 0, v11
	v_fmac_f32_e32 v2, v166, v10
	v_max_f32_e32 v12, 0, v12
	v_fmac_f32_e32 v2, v165, v11
	v_max_f32_e32 v13, 0, v13
	v_fmac_f32_e32 v2, v164, v12
	v_max_f32_e32 v14, 0, v14
	v_fmac_f32_e32 v2, v163, v13
	v_fmac_f32_e32 v2, v162, v14
	v_max_f32_e32 v3, 0, v15
	v_fmac_f32_e32 v2, v161, v3
	v_max_f32_e32 v3, 0, v16
	v_fmac_f32_e32 v2, v160, v3
	v_max_f32_e32 v3, 0, v17
	v_fmac_f32_e32 v2, v89, v3
	v_cmp_gt_i32_e32 vcc, 0, v2
	v_not_b32_e32 v3, v2
	v_or_b32_e32 v4, 0x80000000, v2
	v_cndmask_b32_e32 v2, v4, v3, vcc
	v_cmp_le_u32_e32 vcc, v121, v87
	s_nop 1
	v_cndmask_b32_e32 v220, 0, v2, vcc
	s_branch .Lidxp_w28
.Lidxp_e28:
	v_max_f32_e32 v18, 0, v18
	v_max_f32_e32 v19, 0, v19
	v_fma_f32 v18, v174, v18, 0
	v_max_f32_e32 v20, 0, v20
	v_fmac_f32_e32 v18, v173, v19
	v_max_f32_e32 v21, 0, v21
	v_fmac_f32_e32 v18, v172, v20
	v_max_f32_e32 v22, 0, v22
	v_fmac_f32_e32 v18, v171, v21
	v_max_f32_e32 v23, 0, v23
	v_fmac_f32_e32 v18, v170, v22
	v_max_f32_e32 v24, 0, v24
	v_fmac_f32_e32 v18, v169, v23
	v_max_f32_e32 v25, 0, v25
	v_fmac_f32_e32 v18, v168, v24
	v_max_f32_e32 v26, 0, v26
	v_fmac_f32_e32 v18, v167, v25
	v_max_f32_e32 v27, 0, v27
	v_fmac_f32_e32 v18, v166, v26
	v_max_f32_e32 v28, 0, v28
	v_fmac_f32_e32 v18, v165, v27
	v_max_f32_e32 v29, 0, v29
	v_fmac_f32_e32 v18, v164, v28
	v_max_f32_e32 v30, 0, v30
	v_fmac_f32_e32 v18, v163, v29
	v_fmac_f32_e32 v18, v162, v30
	v_max_f32_e32 v19, 0, v31
	v_fmac_f32_e32 v18, v161, v19
	v_max_f32_e32 v19, 0, v32
	v_fmac_f32_e32 v18, v160, v19
	v_max_f32_e32 v19, 0, v33
	v_fmac_f32_e32 v18, v89, v19
	v_cmp_gt_i32_e32 vcc, 0, v18
	v_not_b32_e32 v19, v18
	v_or_b32_e32 v20, 0x80000000, v18
	v_cndmask_b32_e32 v18, v20, v19, vcc
	v_cmp_le_u32_e32 vcc, v122, v87
	s_nop 1
	v_cndmask_b32_e32 v221, 0, v18, vcc
	s_branch .Lidxp_w29
.Lidxp_e29:
	v_max_f32_e32 v2, 0, v2
	v_max_f32_e32 v3, 0, v3
	v_fma_f32 v2, v174, v2, 0
	v_max_f32_e32 v4, 0, v4
	v_fmac_f32_e32 v2, v173, v3
	v_max_f32_e32 v5, 0, v5
	v_fmac_f32_e32 v2, v172, v4
	v_max_f32_e32 v6, 0, v6
	v_fmac_f32_e32 v2, v171, v5
	v_max_f32_e32 v7, 0, v7
	v_fmac_f32_e32 v2, v170, v6
	v_max_f32_e32 v8, 0, v8
	v_fmac_f32_e32 v2, v169, v7
	v_max_f32_e32 v9, 0, v9
	v_fmac_f32_e32 v2, v168, v8
	v_max_f32_e32 v10, 0, v10
	v_fmac_f32_e32 v2, v167, v9
	v_max_f32_e32 v11, 0, v11
	v_fmac_f32_e32 v2, v166, v10
	v_max_f32_e32 v12, 0, v12
	v_fmac_f32_e32 v2, v165, v11
	v_max_f32_e32 v13, 0, v13
	v_fmac_f32_e32 v2, v164, v12
	v_max_f32_e32 v14, 0, v14
	v_fmac_f32_e32 v2, v163, v13
	v_fmac_f32_e32 v2, v162, v14
	v_max_f32_e32 v3, 0, v15
	v_fmac_f32_e32 v2, v161, v3
	v_max_f32_e32 v3, 0, v16
	v_fmac_f32_e32 v2, v160, v3
	v_max_f32_e32 v3, 0, v17
	v_fmac_f32_e32 v2, v89, v3
	v_cmp_gt_i32_e32 vcc, 0, v2
	v_not_b32_e32 v3, v2
	v_or_b32_e32 v4, 0x80000000, v2
	v_cndmask_b32_e32 v2, v4, v3, vcc
	v_cmp_le_u32_e32 vcc, v123, v87
	s_nop 1
	v_cndmask_b32_e32 v222, 0, v2, vcc
	s_branch .Lidxp_w30
.Lidxp_e30:
	v_max_f32_e32 v18, 0, v18
	v_max_f32_e32 v19, 0, v19
	v_fma_f32 v18, v174, v18, 0
	v_max_f32_e32 v20, 0, v20
	v_fmac_f32_e32 v18, v173, v19
	v_max_f32_e32 v21, 0, v21
	v_fmac_f32_e32 v18, v172, v20
	v_max_f32_e32 v22, 0, v22
	v_fmac_f32_e32 v18, v171, v21
	v_max_f32_e32 v23, 0, v23
	v_fmac_f32_e32 v18, v170, v22
	v_max_f32_e32 v24, 0, v24
	v_fmac_f32_e32 v18, v169, v23
	v_max_f32_e32 v25, 0, v25
	v_fmac_f32_e32 v18, v168, v24
	v_max_f32_e32 v26, 0, v26
	v_fmac_f32_e32 v18, v167, v25
	v_max_f32_e32 v27, 0, v27
	v_fmac_f32_e32 v18, v166, v26
	v_max_f32_e32 v28, 0, v28
	v_fmac_f32_e32 v18, v165, v27
	v_max_f32_e32 v29, 0, v29
	v_fmac_f32_e32 v18, v164, v28
	v_max_f32_e32 v30, 0, v30
	v_fmac_f32_e32 v18, v163, v29
	v_fmac_f32_e32 v18, v162, v30
	v_max_f32_e32 v19, 0, v31
	v_fmac_f32_e32 v18, v161, v19
	v_max_f32_e32 v19, 0, v32
	v_fmac_f32_e32 v18, v160, v19
	v_max_f32_e32 v19, 0, v33
	v_fmac_f32_e32 v18, v89, v19
	v_cmp_gt_i32_e32 vcc, 0, v18
	v_not_b32_e32 v19, v18
	v_or_b32_e32 v20, 0x80000000, v18
	v_cndmask_b32_e32 v18, v20, v19, vcc
	v_cmp_le_u32_e32 vcc, v124, v87
	s_nop 1
	v_cndmask_b32_e32 v223, 0, v18, vcc
	s_branch .Lidxp_w31
.Lidxp_e31:
	v_max_f32_e32 v2, 0, v2
	v_max_f32_e32 v3, 0, v3
	v_fma_f32 v2, v174, v2, 0
	v_max_f32_e32 v4, 0, v4
	v_fmac_f32_e32 v2, v173, v3
	v_max_f32_e32 v5, 0, v5
	v_fmac_f32_e32 v2, v172, v4
	v_max_f32_e32 v6, 0, v6
	v_fmac_f32_e32 v2, v171, v5
	v_max_f32_e32 v7, 0, v7
	v_fmac_f32_e32 v2, v170, v6
	v_max_f32_e32 v8, 0, v8
	v_fmac_f32_e32 v2, v169, v7
	v_max_f32_e32 v9, 0, v9
	v_fmac_f32_e32 v2, v168, v8
	v_max_f32_e32 v10, 0, v10
	v_fmac_f32_e32 v2, v167, v9
	v_max_f32_e32 v11, 0, v11
	v_fmac_f32_e32 v2, v166, v10
	v_max_f32_e32 v12, 0, v12
	v_fmac_f32_e32 v2, v165, v11
	v_max_f32_e32 v13, 0, v13
	v_fmac_f32_e32 v2, v164, v12
	v_max_f32_e32 v14, 0, v14
	v_fmac_f32_e32 v2, v163, v13
	v_fmac_f32_e32 v2, v162, v14
	v_max_f32_e32 v3, 0, v15
	v_fmac_f32_e32 v2, v161, v3
	v_max_f32_e32 v3, 0, v16
	v_fmac_f32_e32 v2, v160, v3
	v_max_f32_e32 v3, 0, v17
	v_fmac_f32_e32 v2, v89, v3
	v_cmp_gt_i32_e32 vcc, 0, v2
	v_not_b32_e32 v3, v2
	v_or_b32_e32 v4, 0x80000000, v2
	v_cndmask_b32_e32 v2, v4, v3, vcc
	v_cmp_le_u32_e32 vcc, v125, v87
	s_nop 1
	v_cndmask_b32_e32 v224, 0, v2, vcc
	s_branch .Lidxp_w32
.Lidxp_e32:
	v_max_f32_e32 v18, 0, v18
	v_max_f32_e32 v19, 0, v19
	v_fma_f32 v18, v174, v18, 0
	v_max_f32_e32 v20, 0, v20
	v_fmac_f32_e32 v18, v173, v19
	v_max_f32_e32 v21, 0, v21
	v_fmac_f32_e32 v18, v172, v20
	v_max_f32_e32 v22, 0, v22
	v_fmac_f32_e32 v18, v171, v21
	v_max_f32_e32 v23, 0, v23
	v_fmac_f32_e32 v18, v170, v22
	v_max_f32_e32 v24, 0, v24
	v_fmac_f32_e32 v18, v169, v23
	v_max_f32_e32 v25, 0, v25
	v_fmac_f32_e32 v18, v168, v24
	v_max_f32_e32 v26, 0, v26
	v_fmac_f32_e32 v18, v167, v25
	v_max_f32_e32 v27, 0, v27
	v_fmac_f32_e32 v18, v166, v26
	v_max_f32_e32 v28, 0, v28
	v_fmac_f32_e32 v18, v165, v27
	v_max_f32_e32 v29, 0, v29
	v_fmac_f32_e32 v18, v164, v28
	v_max_f32_e32 v30, 0, v30
	v_fmac_f32_e32 v18, v163, v29
	v_fmac_f32_e32 v18, v162, v30
	v_max_f32_e32 v19, 0, v31
	v_fmac_f32_e32 v18, v161, v19
	v_max_f32_e32 v19, 0, v32
	v_fmac_f32_e32 v18, v160, v19
	v_max_f32_e32 v19, 0, v33
	v_fmac_f32_e32 v18, v89, v19
	v_cmp_gt_i32_e32 vcc, 0, v18
	v_not_b32_e32 v19, v18
	v_or_b32_e32 v20, 0x80000000, v18
	v_cndmask_b32_e32 v18, v20, v19, vcc
	v_cmp_le_u32_e32 vcc, v126, v87
	s_nop 1
	v_cndmask_b32_e32 v225, 0, v18, vcc
	s_branch .Lidxp_w33
.Lidxp_e33:
	v_max_f32_e32 v2, 0, v2
	v_max_f32_e32 v3, 0, v3
	v_fma_f32 v2, v174, v2, 0
	v_max_f32_e32 v4, 0, v4
	v_fmac_f32_e32 v2, v173, v3
	v_max_f32_e32 v5, 0, v5
	v_fmac_f32_e32 v2, v172, v4
	v_max_f32_e32 v6, 0, v6
	v_fmac_f32_e32 v2, v171, v5
	v_max_f32_e32 v7, 0, v7
	v_fmac_f32_e32 v2, v170, v6
	v_max_f32_e32 v8, 0, v8
	v_fmac_f32_e32 v2, v169, v7
	v_max_f32_e32 v9, 0, v9
	v_fmac_f32_e32 v2, v168, v8
	v_max_f32_e32 v10, 0, v10
	v_fmac_f32_e32 v2, v167, v9
	v_max_f32_e32 v11, 0, v11
	v_fmac_f32_e32 v2, v166, v10
	v_max_f32_e32 v12, 0, v12
	v_fmac_f32_e32 v2, v165, v11
	v_max_f32_e32 v13, 0, v13
	v_fmac_f32_e32 v2, v164, v12
	v_max_f32_e32 v14, 0, v14
	v_fmac_f32_e32 v2, v163, v13
	v_fmac_f32_e32 v2, v162, v14
	v_max_f32_e32 v3, 0, v15
	v_fmac_f32_e32 v2, v161, v3
	v_max_f32_e32 v3, 0, v16
	v_fmac_f32_e32 v2, v160, v3
	v_max_f32_e32 v3, 0, v17
	v_fmac_f32_e32 v2, v89, v3
	v_cmp_gt_i32_e32 vcc, 0, v2
	v_not_b32_e32 v3, v2
	v_or_b32_e32 v4, 0x80000000, v2
	v_cndmask_b32_e32 v2, v4, v3, vcc
	v_cmp_le_u32_e32 vcc, v127, v87
	s_nop 1
	v_cndmask_b32_e32 v226, 0, v2, vcc
	s_branch .Lidxp_w34
.Lidxp_e34:
	v_max_f32_e32 v18, 0, v18
	v_max_f32_e32 v19, 0, v19
	v_fma_f32 v18, v174, v18, 0
	v_max_f32_e32 v20, 0, v20
	v_fmac_f32_e32 v18, v173, v19
	v_max_f32_e32 v21, 0, v21
	v_fmac_f32_e32 v18, v172, v20
	v_max_f32_e32 v22, 0, v22
	v_fmac_f32_e32 v18, v171, v21
	v_max_f32_e32 v23, 0, v23
	v_fmac_f32_e32 v18, v170, v22
	v_max_f32_e32 v24, 0, v24
	v_fmac_f32_e32 v18, v169, v23
	v_max_f32_e32 v25, 0, v25
	v_fmac_f32_e32 v18, v168, v24
	v_max_f32_e32 v26, 0, v26
	v_fmac_f32_e32 v18, v167, v25
	v_max_f32_e32 v27, 0, v27
	v_fmac_f32_e32 v18, v166, v26
	v_max_f32_e32 v28, 0, v28
	v_fmac_f32_e32 v18, v165, v27
	v_max_f32_e32 v29, 0, v29
	v_fmac_f32_e32 v18, v164, v28
	v_max_f32_e32 v30, 0, v30
	v_fmac_f32_e32 v18, v163, v29
	v_fmac_f32_e32 v18, v162, v30
	v_max_f32_e32 v19, 0, v31
	v_fmac_f32_e32 v18, v161, v19
	v_max_f32_e32 v19, 0, v32
	v_fmac_f32_e32 v18, v160, v19
	v_max_f32_e32 v19, 0, v33
	v_fmac_f32_e32 v18, v89, v19
	v_cmp_gt_i32_e32 vcc, 0, v18
	v_not_b32_e32 v19, v18
	v_or_b32_e32 v20, 0x80000000, v18
	v_cndmask_b32_e32 v18, v20, v19, vcc
	v_cmp_le_u32_e32 vcc, v128, v87
	s_nop 1
	v_cndmask_b32_e32 v227, 0, v18, vcc
	s_branch .Lidxp_w35
.Lidxp_e35:
	v_max_f32_e32 v2, 0, v2
	v_max_f32_e32 v3, 0, v3
	v_fma_f32 v2, v174, v2, 0
	v_max_f32_e32 v4, 0, v4
	v_fmac_f32_e32 v2, v173, v3
	v_max_f32_e32 v5, 0, v5
	v_fmac_f32_e32 v2, v172, v4
	v_max_f32_e32 v6, 0, v6
	v_fmac_f32_e32 v2, v171, v5
	v_max_f32_e32 v7, 0, v7
	v_fmac_f32_e32 v2, v170, v6
	v_max_f32_e32 v8, 0, v8
	v_fmac_f32_e32 v2, v169, v7
	v_max_f32_e32 v9, 0, v9
	v_fmac_f32_e32 v2, v168, v8
	v_max_f32_e32 v10, 0, v10
	v_fmac_f32_e32 v2, v167, v9
	v_max_f32_e32 v11, 0, v11
	v_fmac_f32_e32 v2, v166, v10
	v_max_f32_e32 v12, 0, v12
	v_fmac_f32_e32 v2, v165, v11
	v_max_f32_e32 v13, 0, v13
	v_fmac_f32_e32 v2, v164, v12
	v_max_f32_e32 v14, 0, v14
	v_fmac_f32_e32 v2, v163, v13
	v_fmac_f32_e32 v2, v162, v14
	v_max_f32_e32 v3, 0, v15
	v_fmac_f32_e32 v2, v161, v3
	v_max_f32_e32 v3, 0, v16
	v_fmac_f32_e32 v2, v160, v3
	v_max_f32_e32 v3, 0, v17
	v_fmac_f32_e32 v2, v89, v3
	v_cmp_gt_i32_e32 vcc, 0, v2
	v_not_b32_e32 v3, v2
	v_or_b32_e32 v4, 0x80000000, v2
	v_cndmask_b32_e32 v2, v4, v3, vcc
	v_cmp_le_u32_e32 vcc, v129, v87
	s_nop 1
	v_cndmask_b32_e32 v228, 0, v2, vcc
	s_branch .Lidxp_w36
.Lidxp_e36:
	v_max_f32_e32 v18, 0, v18
	v_max_f32_e32 v19, 0, v19
	v_fma_f32 v18, v174, v18, 0
	v_max_f32_e32 v20, 0, v20
	v_fmac_f32_e32 v18, v173, v19
	v_max_f32_e32 v21, 0, v21
	v_fmac_f32_e32 v18, v172, v20
	v_max_f32_e32 v22, 0, v22
	v_fmac_f32_e32 v18, v171, v21
	v_max_f32_e32 v23, 0, v23
	v_fmac_f32_e32 v18, v170, v22
	v_max_f32_e32 v24, 0, v24
	v_fmac_f32_e32 v18, v169, v23
	v_max_f32_e32 v25, 0, v25
	v_fmac_f32_e32 v18, v168, v24
	v_max_f32_e32 v26, 0, v26
	v_fmac_f32_e32 v18, v167, v25
	v_max_f32_e32 v27, 0, v27
	v_fmac_f32_e32 v18, v166, v26
	v_max_f32_e32 v28, 0, v28
	v_fmac_f32_e32 v18, v165, v27
	v_max_f32_e32 v29, 0, v29
	v_fmac_f32_e32 v18, v164, v28
	v_max_f32_e32 v30, 0, v30
	v_fmac_f32_e32 v18, v163, v29
	v_fmac_f32_e32 v18, v162, v30
	v_max_f32_e32 v19, 0, v31
	v_fmac_f32_e32 v18, v161, v19
	v_max_f32_e32 v19, 0, v32
	v_fmac_f32_e32 v18, v160, v19
	v_max_f32_e32 v19, 0, v33
	v_fmac_f32_e32 v18, v89, v19
	v_cmp_gt_i32_e32 vcc, 0, v18
	v_not_b32_e32 v19, v18
	v_or_b32_e32 v20, 0x80000000, v18
	v_cndmask_b32_e32 v18, v20, v19, vcc
	v_cmp_le_u32_e32 vcc, v130, v87
	s_nop 1
	v_cndmask_b32_e32 v229, 0, v18, vcc
	s_branch .Lidxp_w37
.Lidxp_e37:
	v_max_f32_e32 v2, 0, v2
	v_max_f32_e32 v3, 0, v3
	v_fma_f32 v2, v174, v2, 0
	v_max_f32_e32 v4, 0, v4
	v_fmac_f32_e32 v2, v173, v3
	v_max_f32_e32 v5, 0, v5
	v_fmac_f32_e32 v2, v172, v4
	v_max_f32_e32 v6, 0, v6
	v_fmac_f32_e32 v2, v171, v5
	v_max_f32_e32 v7, 0, v7
	v_fmac_f32_e32 v2, v170, v6
	v_max_f32_e32 v8, 0, v8
	v_fmac_f32_e32 v2, v169, v7
	v_max_f32_e32 v9, 0, v9
	v_fmac_f32_e32 v2, v168, v8
	v_max_f32_e32 v10, 0, v10
	v_fmac_f32_e32 v2, v167, v9
	v_max_f32_e32 v11, 0, v11
	v_fmac_f32_e32 v2, v166, v10
	v_max_f32_e32 v12, 0, v12
	v_fmac_f32_e32 v2, v165, v11
	v_max_f32_e32 v13, 0, v13
	v_fmac_f32_e32 v2, v164, v12
	v_max_f32_e32 v14, 0, v14
	v_fmac_f32_e32 v2, v163, v13
	v_fmac_f32_e32 v2, v162, v14
	v_max_f32_e32 v3, 0, v15
	v_fmac_f32_e32 v2, v161, v3
	v_max_f32_e32 v3, 0, v16
	v_fmac_f32_e32 v2, v160, v3
	v_max_f32_e32 v3, 0, v17
	v_fmac_f32_e32 v2, v89, v3
	v_cmp_gt_i32_e32 vcc, 0, v2
	v_not_b32_e32 v3, v2
	v_or_b32_e32 v4, 0x80000000, v2
	v_cndmask_b32_e32 v2, v4, v3, vcc
	v_cmp_le_u32_e32 vcc, v131, v87
	s_nop 1
	v_cndmask_b32_e32 v230, 0, v2, vcc
	s_branch .Lidxp_w38
.Lidxp_e38:
	v_max_f32_e32 v18, 0, v18
	v_max_f32_e32 v19, 0, v19
	v_fma_f32 v18, v174, v18, 0
	v_max_f32_e32 v20, 0, v20
	v_fmac_f32_e32 v18, v173, v19
	v_max_f32_e32 v21, 0, v21
	v_fmac_f32_e32 v18, v172, v20
	v_max_f32_e32 v22, 0, v22
	v_fmac_f32_e32 v18, v171, v21
	v_max_f32_e32 v23, 0, v23
	v_fmac_f32_e32 v18, v170, v22
	v_max_f32_e32 v24, 0, v24
	v_fmac_f32_e32 v18, v169, v23
	v_max_f32_e32 v25, 0, v25
	v_fmac_f32_e32 v18, v168, v24
	v_max_f32_e32 v26, 0, v26
	v_fmac_f32_e32 v18, v167, v25
	v_max_f32_e32 v27, 0, v27
	v_fmac_f32_e32 v18, v166, v26
	v_max_f32_e32 v28, 0, v28
	v_fmac_f32_e32 v18, v165, v27
	v_max_f32_e32 v29, 0, v29
	v_fmac_f32_e32 v18, v164, v28
	v_max_f32_e32 v30, 0, v30
	v_fmac_f32_e32 v18, v163, v29
	v_fmac_f32_e32 v18, v162, v30
	v_max_f32_e32 v19, 0, v31
	v_fmac_f32_e32 v18, v161, v19
	v_max_f32_e32 v19, 0, v32
	v_fmac_f32_e32 v18, v160, v19
	v_max_f32_e32 v19, 0, v33
	v_fmac_f32_e32 v18, v89, v19
	v_cmp_gt_i32_e32 vcc, 0, v18
	v_not_b32_e32 v19, v18
	v_or_b32_e32 v20, 0x80000000, v18
	v_cndmask_b32_e32 v18, v20, v19, vcc
	v_cmp_le_u32_e32 vcc, v132, v87
	s_nop 1
	v_cndmask_b32_e32 v231, 0, v18, vcc
	s_branch .Lidxp_w39
.Lidxp_e39:
	v_max_f32_e32 v2, 0, v2
	v_max_f32_e32 v3, 0, v3
	v_fma_f32 v2, v174, v2, 0
	v_max_f32_e32 v4, 0, v4
	v_fmac_f32_e32 v2, v173, v3
	v_max_f32_e32 v5, 0, v5
	v_fmac_f32_e32 v2, v172, v4
	v_max_f32_e32 v6, 0, v6
	v_fmac_f32_e32 v2, v171, v5
	v_max_f32_e32 v7, 0, v7
	v_fmac_f32_e32 v2, v170, v6
	v_max_f32_e32 v8, 0, v8
	v_fmac_f32_e32 v2, v169, v7
	v_max_f32_e32 v9, 0, v9
	v_fmac_f32_e32 v2, v168, v8
	v_max_f32_e32 v10, 0, v10
	v_fmac_f32_e32 v2, v167, v9
	v_max_f32_e32 v11, 0, v11
	v_fmac_f32_e32 v2, v166, v10
	v_max_f32_e32 v12, 0, v12
	v_fmac_f32_e32 v2, v165, v11
	v_max_f32_e32 v13, 0, v13
	v_fmac_f32_e32 v2, v164, v12
	v_max_f32_e32 v14, 0, v14
	v_fmac_f32_e32 v2, v163, v13
	v_fmac_f32_e32 v2, v162, v14
	v_max_f32_e32 v3, 0, v15
	v_fmac_f32_e32 v2, v161, v3
	v_max_f32_e32 v3, 0, v16
	v_fmac_f32_e32 v2, v160, v3
	v_max_f32_e32 v3, 0, v17
	v_fmac_f32_e32 v2, v89, v3
	v_cmp_gt_i32_e32 vcc, 0, v2
	v_not_b32_e32 v3, v2
	v_or_b32_e32 v4, 0x80000000, v2
	v_cndmask_b32_e32 v2, v4, v3, vcc
	v_cmp_le_u32_e32 vcc, v133, v87
	s_nop 1
	v_cndmask_b32_e32 v232, 0, v2, vcc
	s_branch .Lidxp_w40
.Lidxp_e40:
	v_max_f32_e32 v18, 0, v18
	v_max_f32_e32 v19, 0, v19
	v_fma_f32 v18, v174, v18, 0
	v_max_f32_e32 v20, 0, v20
	v_fmac_f32_e32 v18, v173, v19
	v_max_f32_e32 v21, 0, v21
	v_fmac_f32_e32 v18, v172, v20
	v_max_f32_e32 v22, 0, v22
	v_fmac_f32_e32 v18, v171, v21
	v_max_f32_e32 v23, 0, v23
	v_fmac_f32_e32 v18, v170, v22
	v_max_f32_e32 v24, 0, v24
	v_fmac_f32_e32 v18, v169, v23
	v_max_f32_e32 v25, 0, v25
	v_fmac_f32_e32 v18, v168, v24
	v_max_f32_e32 v26, 0, v26
	v_fmac_f32_e32 v18, v167, v25
	v_max_f32_e32 v27, 0, v27
	v_fmac_f32_e32 v18, v166, v26
	v_max_f32_e32 v28, 0, v28
	v_fmac_f32_e32 v18, v165, v27
	v_max_f32_e32 v29, 0, v29
	v_fmac_f32_e32 v18, v164, v28
	v_max_f32_e32 v30, 0, v30
	v_fmac_f32_e32 v18, v163, v29
	v_fmac_f32_e32 v18, v162, v30
	v_max_f32_e32 v19, 0, v31
	v_fmac_f32_e32 v18, v161, v19
	v_max_f32_e32 v19, 0, v32
	v_fmac_f32_e32 v18, v160, v19
	v_max_f32_e32 v19, 0, v33
	v_fmac_f32_e32 v18, v89, v19
	v_cmp_gt_i32_e32 vcc, 0, v18
	v_not_b32_e32 v19, v18
	v_or_b32_e32 v20, 0x80000000, v18
	v_cndmask_b32_e32 v18, v20, v19, vcc
	v_cmp_le_u32_e32 vcc, v134, v87
	s_nop 1
	v_cndmask_b32_e32 v233, 0, v18, vcc
	s_branch .Lidxp_w41
.Lidxp_e41:
	v_max_f32_e32 v2, 0, v2
	v_max_f32_e32 v3, 0, v3
	v_fma_f32 v2, v174, v2, 0
	v_max_f32_e32 v4, 0, v4
	v_fmac_f32_e32 v2, v173, v3
	v_max_f32_e32 v5, 0, v5
	v_fmac_f32_e32 v2, v172, v4
	v_max_f32_e32 v6, 0, v6
	v_fmac_f32_e32 v2, v171, v5
	v_max_f32_e32 v7, 0, v7
	v_fmac_f32_e32 v2, v170, v6
	v_max_f32_e32 v8, 0, v8
	v_fmac_f32_e32 v2, v169, v7
	v_max_f32_e32 v9, 0, v9
	v_fmac_f32_e32 v2, v168, v8
	v_max_f32_e32 v10, 0, v10
	v_fmac_f32_e32 v2, v167, v9
	v_max_f32_e32 v11, 0, v11
	v_fmac_f32_e32 v2, v166, v10
	v_max_f32_e32 v12, 0, v12
	v_fmac_f32_e32 v2, v165, v11
	v_max_f32_e32 v13, 0, v13
	v_fmac_f32_e32 v2, v164, v12
	v_max_f32_e32 v14, 0, v14
	v_fmac_f32_e32 v2, v163, v13
	v_fmac_f32_e32 v2, v162, v14
	v_max_f32_e32 v3, 0, v15
	v_fmac_f32_e32 v2, v161, v3
	v_max_f32_e32 v3, 0, v16
	v_fmac_f32_e32 v2, v160, v3
	v_max_f32_e32 v3, 0, v17
	v_fmac_f32_e32 v2, v89, v3
	v_cmp_gt_i32_e32 vcc, 0, v2
	v_not_b32_e32 v3, v2
	v_or_b32_e32 v4, 0x80000000, v2
	v_cndmask_b32_e32 v2, v4, v3, vcc
	v_cmp_le_u32_e32 vcc, v135, v87
	s_nop 1
	v_cndmask_b32_e32 v234, 0, v2, vcc
	s_branch .Lidxp_w42
.Lidxp_e42:
	v_max_f32_e32 v18, 0, v18
	v_max_f32_e32 v19, 0, v19
	v_fma_f32 v18, v174, v18, 0
	v_max_f32_e32 v20, 0, v20
	v_fmac_f32_e32 v18, v173, v19
	v_max_f32_e32 v21, 0, v21
	v_fmac_f32_e32 v18, v172, v20
	v_max_f32_e32 v22, 0, v22
	v_fmac_f32_e32 v18, v171, v21
	v_max_f32_e32 v23, 0, v23
	v_fmac_f32_e32 v18, v170, v22
	v_max_f32_e32 v24, 0, v24
	v_fmac_f32_e32 v18, v169, v23
	v_max_f32_e32 v25, 0, v25
	v_fmac_f32_e32 v18, v168, v24
	v_max_f32_e32 v26, 0, v26
	v_fmac_f32_e32 v18, v167, v25
	v_max_f32_e32 v27, 0, v27
	v_fmac_f32_e32 v18, v166, v26
	v_max_f32_e32 v28, 0, v28
	v_fmac_f32_e32 v18, v165, v27
	v_max_f32_e32 v29, 0, v29
	v_fmac_f32_e32 v18, v164, v28
	v_max_f32_e32 v30, 0, v30
	v_fmac_f32_e32 v18, v163, v29
	v_fmac_f32_e32 v18, v162, v30
	v_max_f32_e32 v19, 0, v31
	v_fmac_f32_e32 v18, v161, v19
	v_max_f32_e32 v19, 0, v32
	v_fmac_f32_e32 v18, v160, v19
	v_max_f32_e32 v19, 0, v33
	v_fmac_f32_e32 v18, v89, v19
	v_cmp_gt_i32_e32 vcc, 0, v18
	v_not_b32_e32 v19, v18
	v_or_b32_e32 v20, 0x80000000, v18
	v_cndmask_b32_e32 v18, v20, v19, vcc
	v_cmp_le_u32_e32 vcc, v136, v87
	s_nop 1
	v_cndmask_b32_e32 v235, 0, v18, vcc
	s_branch .Lidxp_w43
.Lidxp_e43:
	v_max_f32_e32 v2, 0, v2
	v_max_f32_e32 v3, 0, v3
	v_fma_f32 v2, v174, v2, 0
	v_max_f32_e32 v4, 0, v4
	v_fmac_f32_e32 v2, v173, v3
	v_max_f32_e32 v5, 0, v5
	v_fmac_f32_e32 v2, v172, v4
	v_max_f32_e32 v6, 0, v6
	v_fmac_f32_e32 v2, v171, v5
	v_max_f32_e32 v7, 0, v7
	v_fmac_f32_e32 v2, v170, v6
	v_max_f32_e32 v8, 0, v8
	v_fmac_f32_e32 v2, v169, v7
	v_max_f32_e32 v9, 0, v9
	v_fmac_f32_e32 v2, v168, v8
	v_max_f32_e32 v10, 0, v10
	v_fmac_f32_e32 v2, v167, v9
	v_max_f32_e32 v11, 0, v11
	v_fmac_f32_e32 v2, v166, v10
	v_max_f32_e32 v12, 0, v12
	v_fmac_f32_e32 v2, v165, v11
	v_max_f32_e32 v13, 0, v13
	v_fmac_f32_e32 v2, v164, v12
	v_max_f32_e32 v14, 0, v14
	v_fmac_f32_e32 v2, v163, v13
	v_fmac_f32_e32 v2, v162, v14
	v_max_f32_e32 v3, 0, v15
	v_fmac_f32_e32 v2, v161, v3
	v_max_f32_e32 v3, 0, v16
	v_fmac_f32_e32 v2, v160, v3
	v_max_f32_e32 v3, 0, v17
	v_fmac_f32_e32 v2, v89, v3
	v_cmp_gt_i32_e32 vcc, 0, v2
	v_not_b32_e32 v3, v2
	v_or_b32_e32 v4, 0x80000000, v2
	v_cndmask_b32_e32 v2, v4, v3, vcc
	v_cmp_le_u32_e32 vcc, v137, v87
	s_nop 1
	v_cndmask_b32_e32 v236, 0, v2, vcc
	s_branch .Lidxp_w44
.Lidxp_e44:
	v_max_f32_e32 v18, 0, v18
	v_max_f32_e32 v19, 0, v19
	v_fma_f32 v18, v174, v18, 0
	v_max_f32_e32 v20, 0, v20
	v_fmac_f32_e32 v18, v173, v19
	v_max_f32_e32 v21, 0, v21
	v_fmac_f32_e32 v18, v172, v20
	v_max_f32_e32 v22, 0, v22
	v_fmac_f32_e32 v18, v171, v21
	v_max_f32_e32 v23, 0, v23
	v_fmac_f32_e32 v18, v170, v22
	v_max_f32_e32 v24, 0, v24
	v_fmac_f32_e32 v18, v169, v23
	v_max_f32_e32 v25, 0, v25
	v_fmac_f32_e32 v18, v168, v24
	v_max_f32_e32 v26, 0, v26
	v_fmac_f32_e32 v18, v167, v25
	v_max_f32_e32 v27, 0, v27
	v_fmac_f32_e32 v18, v166, v26
	v_max_f32_e32 v28, 0, v28
	v_fmac_f32_e32 v18, v165, v27
	v_max_f32_e32 v29, 0, v29
	v_fmac_f32_e32 v18, v164, v28
	v_max_f32_e32 v30, 0, v30
	v_fmac_f32_e32 v18, v163, v29
	v_fmac_f32_e32 v18, v162, v30
	v_max_f32_e32 v19, 0, v31
	v_fmac_f32_e32 v18, v161, v19
	v_max_f32_e32 v19, 0, v32
	v_fmac_f32_e32 v18, v160, v19
	v_max_f32_e32 v19, 0, v33
	v_fmac_f32_e32 v18, v89, v19
	v_cmp_gt_i32_e32 vcc, 0, v18
	v_not_b32_e32 v19, v18
	v_or_b32_e32 v20, 0x80000000, v18
	v_cndmask_b32_e32 v18, v20, v19, vcc
	v_cmp_le_u32_e32 vcc, v138, v87
	s_nop 1
	v_cndmask_b32_e32 v237, 0, v18, vcc
	s_branch .Lidxp_w45
.Lidxp_e45:
	v_max_f32_e32 v2, 0, v2
	v_max_f32_e32 v3, 0, v3
	v_fma_f32 v2, v174, v2, 0
	v_max_f32_e32 v4, 0, v4
	v_fmac_f32_e32 v2, v173, v3
	v_max_f32_e32 v5, 0, v5
	v_fmac_f32_e32 v2, v172, v4
	v_max_f32_e32 v6, 0, v6
	v_fmac_f32_e32 v2, v171, v5
	v_max_f32_e32 v7, 0, v7
	v_fmac_f32_e32 v2, v170, v6
	v_max_f32_e32 v8, 0, v8
	v_fmac_f32_e32 v2, v169, v7
	v_max_f32_e32 v9, 0, v9
	v_fmac_f32_e32 v2, v168, v8
	v_max_f32_e32 v10, 0, v10
	v_fmac_f32_e32 v2, v167, v9
	v_max_f32_e32 v11, 0, v11
	v_fmac_f32_e32 v2, v166, v10
	v_max_f32_e32 v12, 0, v12
	v_fmac_f32_e32 v2, v165, v11
	v_max_f32_e32 v13, 0, v13
	v_fmac_f32_e32 v2, v164, v12
	v_max_f32_e32 v14, 0, v14
	v_fmac_f32_e32 v2, v163, v13
	v_fmac_f32_e32 v2, v162, v14
	v_max_f32_e32 v3, 0, v15
	v_fmac_f32_e32 v2, v161, v3
	v_max_f32_e32 v3, 0, v16
	v_fmac_f32_e32 v2, v160, v3
	v_max_f32_e32 v3, 0, v17
	v_fmac_f32_e32 v2, v89, v3
	v_cmp_gt_i32_e32 vcc, 0, v2
	v_not_b32_e32 v3, v2
	v_or_b32_e32 v4, 0x80000000, v2
	v_cndmask_b32_e32 v2, v4, v3, vcc
	v_cmp_le_u32_e32 vcc, v139, v87
	s_nop 1
	v_cndmask_b32_e32 v238, 0, v2, vcc
	s_branch .Lidxp_w46
.Lidxp_e46:
	v_max_f32_e32 v18, 0, v18
	v_max_f32_e32 v19, 0, v19
	v_fma_f32 v18, v174, v18, 0
	v_max_f32_e32 v20, 0, v20
	v_fmac_f32_e32 v18, v173, v19
	v_max_f32_e32 v21, 0, v21
	v_fmac_f32_e32 v18, v172, v20
	v_max_f32_e32 v22, 0, v22
	v_fmac_f32_e32 v18, v171, v21
	v_max_f32_e32 v23, 0, v23
	v_fmac_f32_e32 v18, v170, v22
	v_max_f32_e32 v24, 0, v24
	v_fmac_f32_e32 v18, v169, v23
	v_max_f32_e32 v25, 0, v25
	v_fmac_f32_e32 v18, v168, v24
	v_max_f32_e32 v26, 0, v26
	v_fmac_f32_e32 v18, v167, v25
	v_max_f32_e32 v27, 0, v27
	v_fmac_f32_e32 v18, v166, v26
	v_max_f32_e32 v28, 0, v28
	v_fmac_f32_e32 v18, v165, v27
	v_max_f32_e32 v29, 0, v29
	v_fmac_f32_e32 v18, v164, v28
	v_max_f32_e32 v30, 0, v30
	v_fmac_f32_e32 v18, v163, v29
	v_fmac_f32_e32 v18, v162, v30
	v_max_f32_e32 v19, 0, v31
	v_fmac_f32_e32 v18, v161, v19
	v_max_f32_e32 v19, 0, v32
	v_fmac_f32_e32 v18, v160, v19
	v_max_f32_e32 v19, 0, v33
	v_fmac_f32_e32 v18, v89, v19
	v_cmp_gt_i32_e32 vcc, 0, v18
	v_not_b32_e32 v19, v18
	v_or_b32_e32 v20, 0x80000000, v18
	v_cndmask_b32_e32 v18, v20, v19, vcc
	v_cmp_le_u32_e32 vcc, v140, v87
	s_nop 1
	v_cndmask_b32_e32 v239, 0, v18, vcc
	s_branch .Lidxp_w47
.Lidxp_e47:
	v_max_f32_e32 v2, 0, v2
	v_max_f32_e32 v3, 0, v3
	v_fma_f32 v2, v174, v2, 0
	v_max_f32_e32 v4, 0, v4
	v_fmac_f32_e32 v2, v173, v3
	v_max_f32_e32 v5, 0, v5
	v_fmac_f32_e32 v2, v172, v4
	v_max_f32_e32 v6, 0, v6
	v_fmac_f32_e32 v2, v171, v5
	v_max_f32_e32 v7, 0, v7
	v_fmac_f32_e32 v2, v170, v6
	v_max_f32_e32 v8, 0, v8
	v_fmac_f32_e32 v2, v169, v7
	v_max_f32_e32 v9, 0, v9
	v_fmac_f32_e32 v2, v168, v8
	v_max_f32_e32 v10, 0, v10
	v_fmac_f32_e32 v2, v167, v9
	v_max_f32_e32 v11, 0, v11
	v_fmac_f32_e32 v2, v166, v10
	v_max_f32_e32 v12, 0, v12
	v_fmac_f32_e32 v2, v165, v11
	v_max_f32_e32 v13, 0, v13
	v_fmac_f32_e32 v2, v164, v12
	v_max_f32_e32 v14, 0, v14
	v_fmac_f32_e32 v2, v163, v13
	v_fmac_f32_e32 v2, v162, v14
	v_max_f32_e32 v3, 0, v15
	v_fmac_f32_e32 v2, v161, v3
	v_max_f32_e32 v3, 0, v16
	v_fmac_f32_e32 v2, v160, v3
	v_max_f32_e32 v3, 0, v17
	v_fmac_f32_e32 v2, v89, v3
	v_cmp_gt_i32_e32 vcc, 0, v2
	v_not_b32_e32 v3, v2
	v_or_b32_e32 v4, 0x80000000, v2
	v_cndmask_b32_e32 v2, v4, v3, vcc
	v_cmp_le_u32_e32 vcc, v141, v87
	s_nop 1
	v_cndmask_b32_e32 v240, 0, v2, vcc
	s_branch .Lidxp_w48
.Lidxp_e48:
	v_max_f32_e32 v18, 0, v18
	v_max_f32_e32 v19, 0, v19
	v_fma_f32 v18, v174, v18, 0
	v_max_f32_e32 v20, 0, v20
	v_fmac_f32_e32 v18, v173, v19
	v_max_f32_e32 v21, 0, v21
	v_fmac_f32_e32 v18, v172, v20
	v_max_f32_e32 v22, 0, v22
	v_fmac_f32_e32 v18, v171, v21
	v_max_f32_e32 v23, 0, v23
	v_fmac_f32_e32 v18, v170, v22
	v_max_f32_e32 v24, 0, v24
	v_fmac_f32_e32 v18, v169, v23
	v_max_f32_e32 v25, 0, v25
	v_fmac_f32_e32 v18, v168, v24
	v_max_f32_e32 v26, 0, v26
	v_fmac_f32_e32 v18, v167, v25
	v_max_f32_e32 v27, 0, v27
	v_fmac_f32_e32 v18, v166, v26
	v_max_f32_e32 v28, 0, v28
	v_fmac_f32_e32 v18, v165, v27
	v_max_f32_e32 v29, 0, v29
	v_fmac_f32_e32 v18, v164, v28
	v_max_f32_e32 v30, 0, v30
	v_fmac_f32_e32 v18, v163, v29
	v_fmac_f32_e32 v18, v162, v30
	v_max_f32_e32 v19, 0, v31
	v_fmac_f32_e32 v18, v161, v19
	v_max_f32_e32 v19, 0, v32
	v_fmac_f32_e32 v18, v160, v19
	v_max_f32_e32 v19, 0, v33
	v_fmac_f32_e32 v18, v89, v19
	v_cmp_gt_i32_e32 vcc, 0, v18
	v_not_b32_e32 v19, v18
	v_or_b32_e32 v20, 0x80000000, v18
	v_cndmask_b32_e32 v18, v20, v19, vcc
	v_cmp_le_u32_e32 vcc, v142, v87
	s_nop 1
	v_cndmask_b32_e32 v241, 0, v18, vcc
	s_branch .Lidxp_w49
.Lidxp_e49:
	v_max_f32_e32 v2, 0, v2
	v_max_f32_e32 v3, 0, v3
	v_fma_f32 v2, v174, v2, 0
	v_max_f32_e32 v4, 0, v4
	v_fmac_f32_e32 v2, v173, v3
	v_max_f32_e32 v5, 0, v5
	v_fmac_f32_e32 v2, v172, v4
	v_max_f32_e32 v6, 0, v6
	v_fmac_f32_e32 v2, v171, v5
	v_max_f32_e32 v7, 0, v7
	v_fmac_f32_e32 v2, v170, v6
	v_max_f32_e32 v8, 0, v8
	v_fmac_f32_e32 v2, v169, v7
	v_max_f32_e32 v9, 0, v9
	v_fmac_f32_e32 v2, v168, v8
	v_max_f32_e32 v10, 0, v10
	v_fmac_f32_e32 v2, v167, v9
	v_max_f32_e32 v11, 0, v11
	v_fmac_f32_e32 v2, v166, v10
	v_max_f32_e32 v12, 0, v12
	v_fmac_f32_e32 v2, v165, v11
	v_max_f32_e32 v13, 0, v13
	v_fmac_f32_e32 v2, v164, v12
	v_max_f32_e32 v14, 0, v14
	v_fmac_f32_e32 v2, v163, v13
	v_fmac_f32_e32 v2, v162, v14
	v_max_f32_e32 v3, 0, v15
	v_fmac_f32_e32 v2, v161, v3
	v_max_f32_e32 v3, 0, v16
	v_fmac_f32_e32 v2, v160, v3
	v_max_f32_e32 v3, 0, v17
	v_fmac_f32_e32 v2, v89, v3
	v_cmp_gt_i32_e32 vcc, 0, v2
	v_not_b32_e32 v3, v2
	v_or_b32_e32 v4, 0x80000000, v2
	v_cndmask_b32_e32 v2, v4, v3, vcc
	v_cmp_le_u32_e32 vcc, v143, v87
	s_nop 1
	v_cndmask_b32_e32 v242, 0, v2, vcc
	s_branch .Lidxp_w50
.Lidxp_e50:
	v_max_f32_e32 v18, 0, v18
	v_max_f32_e32 v19, 0, v19
	v_fma_f32 v18, v174, v18, 0
	v_max_f32_e32 v20, 0, v20
	v_fmac_f32_e32 v18, v173, v19
	v_max_f32_e32 v21, 0, v21
	v_fmac_f32_e32 v18, v172, v20
	v_max_f32_e32 v22, 0, v22
	v_fmac_f32_e32 v18, v171, v21
	v_max_f32_e32 v23, 0, v23
	v_fmac_f32_e32 v18, v170, v22
	v_max_f32_e32 v24, 0, v24
	v_fmac_f32_e32 v18, v169, v23
	v_max_f32_e32 v25, 0, v25
	v_fmac_f32_e32 v18, v168, v24
	v_max_f32_e32 v26, 0, v26
	v_fmac_f32_e32 v18, v167, v25
	v_max_f32_e32 v27, 0, v27
	v_fmac_f32_e32 v18, v166, v26
	v_max_f32_e32 v28, 0, v28
	v_fmac_f32_e32 v18, v165, v27
	v_max_f32_e32 v29, 0, v29
	v_fmac_f32_e32 v18, v164, v28
	v_max_f32_e32 v30, 0, v30
	v_fmac_f32_e32 v18, v163, v29
	v_fmac_f32_e32 v18, v162, v30
	v_max_f32_e32 v19, 0, v31
	v_fmac_f32_e32 v18, v161, v19
	v_max_f32_e32 v19, 0, v32
	v_fmac_f32_e32 v18, v160, v19
	v_max_f32_e32 v19, 0, v33
	v_fmac_f32_e32 v18, v89, v19
	v_cmp_gt_i32_e32 vcc, 0, v18
	v_not_b32_e32 v19, v18
	v_or_b32_e32 v20, 0x80000000, v18
	v_cndmask_b32_e32 v18, v20, v19, vcc
	v_cmp_le_u32_e32 vcc, v144, v87
	s_nop 1
	v_cndmask_b32_e32 v243, 0, v18, vcc
	s_branch .Lidxp_w51
.Lidxp_e51:
	v_max_f32_e32 v2, 0, v2
	v_max_f32_e32 v3, 0, v3
	v_fma_f32 v2, v174, v2, 0
	v_max_f32_e32 v4, 0, v4
	v_fmac_f32_e32 v2, v173, v3
	v_max_f32_e32 v5, 0, v5
	v_fmac_f32_e32 v2, v172, v4
	v_max_f32_e32 v6, 0, v6
	v_fmac_f32_e32 v2, v171, v5
	v_max_f32_e32 v7, 0, v7
	v_fmac_f32_e32 v2, v170, v6
	v_max_f32_e32 v8, 0, v8
	v_fmac_f32_e32 v2, v169, v7
	v_max_f32_e32 v9, 0, v9
	v_fmac_f32_e32 v2, v168, v8
	v_max_f32_e32 v10, 0, v10
	v_fmac_f32_e32 v2, v167, v9
	v_max_f32_e32 v11, 0, v11
	v_fmac_f32_e32 v2, v166, v10
	v_max_f32_e32 v12, 0, v12
	v_fmac_f32_e32 v2, v165, v11
	v_max_f32_e32 v13, 0, v13
	v_fmac_f32_e32 v2, v164, v12
	v_max_f32_e32 v14, 0, v14
	v_fmac_f32_e32 v2, v163, v13
	v_fmac_f32_e32 v2, v162, v14
	v_max_f32_e32 v3, 0, v15
	v_fmac_f32_e32 v2, v161, v3
	v_max_f32_e32 v3, 0, v16
	v_fmac_f32_e32 v2, v160, v3
	v_max_f32_e32 v3, 0, v17
	v_fmac_f32_e32 v2, v89, v3
	v_cmp_gt_i32_e32 vcc, 0, v2
	v_not_b32_e32 v3, v2
	v_or_b32_e32 v4, 0x80000000, v2
	v_cndmask_b32_e32 v2, v4, v3, vcc
	v_cmp_le_u32_e32 vcc, v145, v87
	s_nop 1
	v_cndmask_b32_e32 v244, 0, v2, vcc
	s_branch .Lidxp_w52
.Lidxp_e52:
	v_max_f32_e32 v18, 0, v18
	v_max_f32_e32 v19, 0, v19
	v_fma_f32 v18, v174, v18, 0
	v_max_f32_e32 v20, 0, v20
	v_fmac_f32_e32 v18, v173, v19
	v_max_f32_e32 v21, 0, v21
	v_fmac_f32_e32 v18, v172, v20
	v_max_f32_e32 v22, 0, v22
	v_fmac_f32_e32 v18, v171, v21
	v_max_f32_e32 v23, 0, v23
	v_fmac_f32_e32 v18, v170, v22
	v_max_f32_e32 v24, 0, v24
	v_fmac_f32_e32 v18, v169, v23
	v_max_f32_e32 v25, 0, v25
	v_fmac_f32_e32 v18, v168, v24
	v_max_f32_e32 v26, 0, v26
	v_fmac_f32_e32 v18, v167, v25
	v_max_f32_e32 v27, 0, v27
	v_fmac_f32_e32 v18, v166, v26
	v_max_f32_e32 v28, 0, v28
	v_fmac_f32_e32 v18, v165, v27
	v_max_f32_e32 v29, 0, v29
	v_fmac_f32_e32 v18, v164, v28
	v_max_f32_e32 v30, 0, v30
	v_fmac_f32_e32 v18, v163, v29
	v_fmac_f32_e32 v18, v162, v30
	v_max_f32_e32 v19, 0, v31
	v_fmac_f32_e32 v18, v161, v19
	v_max_f32_e32 v19, 0, v32
	v_fmac_f32_e32 v18, v160, v19
	v_max_f32_e32 v19, 0, v33
	v_fmac_f32_e32 v18, v89, v19
	v_cmp_gt_i32_e32 vcc, 0, v18
	v_not_b32_e32 v19, v18
	v_or_b32_e32 v20, 0x80000000, v18
	v_cndmask_b32_e32 v18, v20, v19, vcc
	v_cmp_le_u32_e32 vcc, v146, v87
	s_nop 1
	v_cndmask_b32_e32 v245, 0, v18, vcc
	s_branch .Lidxp_w53
.Lidxp_e53:
	v_max_f32_e32 v2, 0, v2
	v_max_f32_e32 v3, 0, v3
	v_fma_f32 v2, v174, v2, 0
	v_max_f32_e32 v4, 0, v4
	v_fmac_f32_e32 v2, v173, v3
	v_max_f32_e32 v5, 0, v5
	v_fmac_f32_e32 v2, v172, v4
	v_max_f32_e32 v6, 0, v6
	v_fmac_f32_e32 v2, v171, v5
	v_max_f32_e32 v7, 0, v7
	v_fmac_f32_e32 v2, v170, v6
	v_max_f32_e32 v8, 0, v8
	v_fmac_f32_e32 v2, v169, v7
	v_max_f32_e32 v9, 0, v9
	v_fmac_f32_e32 v2, v168, v8
	v_max_f32_e32 v10, 0, v10
	v_fmac_f32_e32 v2, v167, v9
	v_max_f32_e32 v11, 0, v11
	v_fmac_f32_e32 v2, v166, v10
	v_max_f32_e32 v12, 0, v12
	v_fmac_f32_e32 v2, v165, v11
	v_max_f32_e32 v13, 0, v13
	v_fmac_f32_e32 v2, v164, v12
	v_max_f32_e32 v14, 0, v14
	v_fmac_f32_e32 v2, v163, v13
	v_fmac_f32_e32 v2, v162, v14
	v_max_f32_e32 v3, 0, v15
	v_fmac_f32_e32 v2, v161, v3
	v_max_f32_e32 v3, 0, v16
	v_fmac_f32_e32 v2, v160, v3
	v_max_f32_e32 v3, 0, v17
	v_fmac_f32_e32 v2, v89, v3
	v_cmp_gt_i32_e32 vcc, 0, v2
	v_not_b32_e32 v3, v2
	v_or_b32_e32 v4, 0x80000000, v2
	v_cndmask_b32_e32 v2, v4, v3, vcc
	v_cmp_le_u32_e32 vcc, v147, v87
	s_nop 1
	v_cndmask_b32_e32 v246, 0, v2, vcc
	s_branch .Lidxp_w54
.Lidxp_e54:
	v_max_f32_e32 v18, 0, v18
	v_max_f32_e32 v19, 0, v19
	v_fma_f32 v18, v174, v18, 0
	v_max_f32_e32 v20, 0, v20
	v_fmac_f32_e32 v18, v173, v19
	v_max_f32_e32 v21, 0, v21
	v_fmac_f32_e32 v18, v172, v20
	v_max_f32_e32 v22, 0, v22
	v_fmac_f32_e32 v18, v171, v21
	v_max_f32_e32 v23, 0, v23
	v_fmac_f32_e32 v18, v170, v22
	v_max_f32_e32 v24, 0, v24
	v_fmac_f32_e32 v18, v169, v23
	v_max_f32_e32 v25, 0, v25
	v_fmac_f32_e32 v18, v168, v24
	v_max_f32_e32 v26, 0, v26
	v_fmac_f32_e32 v18, v167, v25
	v_max_f32_e32 v27, 0, v27
	v_fmac_f32_e32 v18, v166, v26
	v_max_f32_e32 v28, 0, v28
	v_fmac_f32_e32 v18, v165, v27
	v_max_f32_e32 v29, 0, v29
	v_fmac_f32_e32 v18, v164, v28
	v_max_f32_e32 v30, 0, v30
	v_fmac_f32_e32 v18, v163, v29
	v_fmac_f32_e32 v18, v162, v30
	v_max_f32_e32 v19, 0, v31
	v_fmac_f32_e32 v18, v161, v19
	v_max_f32_e32 v19, 0, v32
	v_fmac_f32_e32 v18, v160, v19
	v_max_f32_e32 v19, 0, v33
	v_fmac_f32_e32 v18, v89, v19
	v_cmp_gt_i32_e32 vcc, 0, v18
	v_not_b32_e32 v19, v18
	v_or_b32_e32 v20, 0x80000000, v18
	v_cndmask_b32_e32 v18, v20, v19, vcc
	v_cmp_le_u32_e32 vcc, v148, v87
	s_nop 1
	v_cndmask_b32_e32 v247, 0, v18, vcc
	s_branch .Lidxp_w55
.Lidxp_e55:
	v_max_f32_e32 v2, 0, v2
	v_max_f32_e32 v3, 0, v3
	v_fma_f32 v2, v174, v2, 0
	v_max_f32_e32 v4, 0, v4
	v_fmac_f32_e32 v2, v173, v3
	v_max_f32_e32 v5, 0, v5
	v_fmac_f32_e32 v2, v172, v4
	v_max_f32_e32 v6, 0, v6
	v_fmac_f32_e32 v2, v171, v5
	v_max_f32_e32 v7, 0, v7
	v_fmac_f32_e32 v2, v170, v6
	v_max_f32_e32 v8, 0, v8
	v_fmac_f32_e32 v2, v169, v7
	v_max_f32_e32 v9, 0, v9
	v_fmac_f32_e32 v2, v168, v8
	v_max_f32_e32 v10, 0, v10
	v_fmac_f32_e32 v2, v167, v9
	v_max_f32_e32 v11, 0, v11
	v_fmac_f32_e32 v2, v166, v10
	v_max_f32_e32 v12, 0, v12
	v_fmac_f32_e32 v2, v165, v11
	v_max_f32_e32 v13, 0, v13
	v_fmac_f32_e32 v2, v164, v12
	v_max_f32_e32 v14, 0, v14
	v_fmac_f32_e32 v2, v163, v13
	v_fmac_f32_e32 v2, v162, v14
	v_max_f32_e32 v3, 0, v15
	v_fmac_f32_e32 v2, v161, v3
	v_max_f32_e32 v3, 0, v16
	v_fmac_f32_e32 v2, v160, v3
	v_max_f32_e32 v3, 0, v17
	v_fmac_f32_e32 v2, v89, v3
	v_cmp_gt_i32_e32 vcc, 0, v2
	v_not_b32_e32 v3, v2
	v_or_b32_e32 v4, 0x80000000, v2
	v_cndmask_b32_e32 v2, v4, v3, vcc
	v_cmp_le_u32_e32 vcc, v149, v87
	s_nop 1
	v_cndmask_b32_e32 v248, 0, v2, vcc
	s_branch .Lidxp_w56
.Lidxp_e56:
	v_max_f32_e32 v18, 0, v18
	v_max_f32_e32 v19, 0, v19
	v_fma_f32 v18, v174, v18, 0
	v_max_f32_e32 v20, 0, v20
	v_fmac_f32_e32 v18, v173, v19
	v_max_f32_e32 v21, 0, v21
	v_fmac_f32_e32 v18, v172, v20
	v_max_f32_e32 v22, 0, v22
	v_fmac_f32_e32 v18, v171, v21
	v_max_f32_e32 v23, 0, v23
	v_fmac_f32_e32 v18, v170, v22
	v_max_f32_e32 v24, 0, v24
	v_fmac_f32_e32 v18, v169, v23
	v_max_f32_e32 v25, 0, v25
	v_fmac_f32_e32 v18, v168, v24
	v_max_f32_e32 v26, 0, v26
	v_fmac_f32_e32 v18, v167, v25
	v_max_f32_e32 v27, 0, v27
	v_fmac_f32_e32 v18, v166, v26
	v_max_f32_e32 v28, 0, v28
	v_fmac_f32_e32 v18, v165, v27
	v_max_f32_e32 v29, 0, v29
	v_fmac_f32_e32 v18, v164, v28
	v_max_f32_e32 v30, 0, v30
	v_fmac_f32_e32 v18, v163, v29
	v_fmac_f32_e32 v18, v162, v30
	v_max_f32_e32 v19, 0, v31
	v_fmac_f32_e32 v18, v161, v19
	v_max_f32_e32 v19, 0, v32
	v_fmac_f32_e32 v18, v160, v19
	v_max_f32_e32 v19, 0, v33
	v_fmac_f32_e32 v18, v89, v19
	v_cmp_gt_i32_e32 vcc, 0, v18
	v_not_b32_e32 v19, v18
	v_or_b32_e32 v20, 0x80000000, v18
	v_cndmask_b32_e32 v18, v20, v19, vcc
	v_cmp_le_u32_e32 vcc, v150, v87
	s_nop 1
	v_cndmask_b32_e32 v249, 0, v18, vcc
	s_branch .Lidxp_w57
.Lidxp_e57:
	v_max_f32_e32 v2, 0, v2
	v_max_f32_e32 v3, 0, v3
	v_fma_f32 v2, v174, v2, 0
	v_max_f32_e32 v4, 0, v4
	v_fmac_f32_e32 v2, v173, v3
	v_max_f32_e32 v5, 0, v5
	v_fmac_f32_e32 v2, v172, v4
	v_max_f32_e32 v6, 0, v6
	v_fmac_f32_e32 v2, v171, v5
	v_max_f32_e32 v7, 0, v7
	v_fmac_f32_e32 v2, v170, v6
	v_max_f32_e32 v8, 0, v8
	v_fmac_f32_e32 v2, v169, v7
	v_max_f32_e32 v9, 0, v9
	v_fmac_f32_e32 v2, v168, v8
	v_max_f32_e32 v10, 0, v10
	v_fmac_f32_e32 v2, v167, v9
	v_max_f32_e32 v11, 0, v11
	v_fmac_f32_e32 v2, v166, v10
	v_max_f32_e32 v12, 0, v12
	v_fmac_f32_e32 v2, v165, v11
	v_max_f32_e32 v13, 0, v13
	v_fmac_f32_e32 v2, v164, v12
	v_max_f32_e32 v14, 0, v14
	v_fmac_f32_e32 v2, v163, v13
	v_fmac_f32_e32 v2, v162, v14
	v_max_f32_e32 v3, 0, v15
	v_fmac_f32_e32 v2, v161, v3
	v_max_f32_e32 v3, 0, v16
	v_fmac_f32_e32 v2, v160, v3
	v_max_f32_e32 v3, 0, v17
	v_fmac_f32_e32 v2, v89, v3
	v_cmp_gt_i32_e32 vcc, 0, v2
	v_not_b32_e32 v3, v2
	v_or_b32_e32 v4, 0x80000000, v2
	v_cndmask_b32_e32 v2, v4, v3, vcc
	v_cmp_le_u32_e32 vcc, v151, v87
	s_nop 1
	v_cndmask_b32_e32 v250, 0, v2, vcc
	s_branch .Lidxp_w58
.Lidxp_e58:
	v_max_f32_e32 v18, 0, v18
	v_max_f32_e32 v19, 0, v19
	v_fma_f32 v18, v174, v18, 0
	v_max_f32_e32 v20, 0, v20
	v_fmac_f32_e32 v18, v173, v19
	v_max_f32_e32 v21, 0, v21
	v_fmac_f32_e32 v18, v172, v20
	v_max_f32_e32 v22, 0, v22
	v_fmac_f32_e32 v18, v171, v21
	v_max_f32_e32 v23, 0, v23
	v_fmac_f32_e32 v18, v170, v22
	v_max_f32_e32 v24, 0, v24
	v_fmac_f32_e32 v18, v169, v23
	v_max_f32_e32 v25, 0, v25
	v_fmac_f32_e32 v18, v168, v24
	v_max_f32_e32 v26, 0, v26
	v_fmac_f32_e32 v18, v167, v25
	v_max_f32_e32 v27, 0, v27
	v_fmac_f32_e32 v18, v166, v26
	v_max_f32_e32 v28, 0, v28
	v_fmac_f32_e32 v18, v165, v27
	v_max_f32_e32 v29, 0, v29
	v_fmac_f32_e32 v18, v164, v28
	v_max_f32_e32 v30, 0, v30
	v_fmac_f32_e32 v18, v163, v29
	v_fmac_f32_e32 v18, v162, v30
	v_max_f32_e32 v19, 0, v31
	v_fmac_f32_e32 v18, v161, v19
	v_max_f32_e32 v19, 0, v32
	v_fmac_f32_e32 v18, v160, v19
	v_max_f32_e32 v19, 0, v33
	v_fmac_f32_e32 v18, v89, v19
	v_cmp_gt_i32_e32 vcc, 0, v18
	v_not_b32_e32 v19, v18
	v_or_b32_e32 v20, 0x80000000, v18
	v_cndmask_b32_e32 v18, v20, v19, vcc
	v_cmp_le_u32_e32 vcc, v152, v87
	s_nop 1
	v_cndmask_b32_e32 v199, 0, v18, vcc
	s_branch .Lidxp_w59
.Lidxp_e59:
	v_max_f32_e32 v2, 0, v2
	v_max_f32_e32 v3, 0, v3
	v_fma_f32 v2, v174, v2, 0
	v_max_f32_e32 v4, 0, v4
	v_fmac_f32_e32 v2, v173, v3
	v_max_f32_e32 v5, 0, v5
	v_fmac_f32_e32 v2, v172, v4
	v_max_f32_e32 v6, 0, v6
	v_fmac_f32_e32 v2, v171, v5
	v_max_f32_e32 v7, 0, v7
	v_fmac_f32_e32 v2, v170, v6
	v_max_f32_e32 v8, 0, v8
	v_fmac_f32_e32 v2, v169, v7
	v_max_f32_e32 v9, 0, v9
	v_fmac_f32_e32 v2, v168, v8
	v_max_f32_e32 v10, 0, v10
	v_fmac_f32_e32 v2, v167, v9
	v_max_f32_e32 v11, 0, v11
	v_fmac_f32_e32 v2, v166, v10
	v_max_f32_e32 v12, 0, v12
	v_fmac_f32_e32 v2, v165, v11
	v_max_f32_e32 v13, 0, v13
	v_fmac_f32_e32 v2, v164, v12
	v_max_f32_e32 v14, 0, v14
	v_fmac_f32_e32 v2, v163, v13
	v_fmac_f32_e32 v2, v162, v14
	v_max_f32_e32 v3, 0, v15
	v_fmac_f32_e32 v2, v161, v3
	v_max_f32_e32 v3, 0, v16
	v_fmac_f32_e32 v2, v160, v3
	v_max_f32_e32 v3, 0, v17
	v_fmac_f32_e32 v2, v89, v3
	v_cmp_gt_i32_e32 vcc, 0, v2
	v_not_b32_e32 v3, v2
	v_or_b32_e32 v4, 0x80000000, v2
	v_cndmask_b32_e32 v2, v4, v3, vcc
	v_cmp_le_u32_e32 vcc, v153, v87
	s_nop 1
	v_cndmask_b32_e32 v200, 0, v2, vcc
	s_branch .Lidxp_w60
.Lidxp_e60:
	v_max_f32_e32 v18, 0, v18
	v_max_f32_e32 v19, 0, v19
	v_fma_f32 v18, v174, v18, 0
	v_max_f32_e32 v20, 0, v20
	v_fmac_f32_e32 v18, v173, v19
	v_max_f32_e32 v21, 0, v21
	v_fmac_f32_e32 v18, v172, v20
	v_max_f32_e32 v22, 0, v22
	v_fmac_f32_e32 v18, v171, v21
	v_max_f32_e32 v23, 0, v23
	v_fmac_f32_e32 v18, v170, v22
	v_max_f32_e32 v24, 0, v24
	v_fmac_f32_e32 v18, v169, v23
	v_max_f32_e32 v25, 0, v25
	v_fmac_f32_e32 v18, v168, v24
	v_max_f32_e32 v26, 0, v26
	v_fmac_f32_e32 v18, v167, v25
	v_max_f32_e32 v27, 0, v27
	v_fmac_f32_e32 v18, v166, v26
	v_max_f32_e32 v28, 0, v28
	v_fmac_f32_e32 v18, v165, v27
	v_max_f32_e32 v29, 0, v29
	v_fmac_f32_e32 v18, v164, v28
	v_max_f32_e32 v30, 0, v30
	v_fmac_f32_e32 v18, v163, v29
	v_fmac_f32_e32 v18, v162, v30
	v_max_f32_e32 v19, 0, v31
	v_fmac_f32_e32 v18, v161, v19
	v_max_f32_e32 v19, 0, v32
	v_fmac_f32_e32 v18, v160, v19
	v_max_f32_e32 v19, 0, v33
	v_fmac_f32_e32 v18, v89, v19
	v_cmp_gt_i32_e32 vcc, 0, v18
	v_not_b32_e32 v19, v18
	v_or_b32_e32 v20, 0x80000000, v18
	v_cndmask_b32_e32 v18, v20, v19, vcc
	v_cmp_le_u32_e32 vcc, v154, v87
	s_nop 1
	v_cndmask_b32_e32 v207, 0, v18, vcc
	s_branch .Lidxp_w61
.Lidxp_e61:
	v_max_f32_e32 v2, 0, v2
	v_max_f32_e32 v3, 0, v3
	v_fma_f32 v2, v174, v2, 0
	v_max_f32_e32 v4, 0, v4
	v_fmac_f32_e32 v2, v173, v3
	v_max_f32_e32 v5, 0, v5
	v_fmac_f32_e32 v2, v172, v4
	v_max_f32_e32 v6, 0, v6
	v_fmac_f32_e32 v2, v171, v5
	v_max_f32_e32 v7, 0, v7
	v_fmac_f32_e32 v2, v170, v6
	v_max_f32_e32 v8, 0, v8
	v_fmac_f32_e32 v2, v169, v7
	v_max_f32_e32 v9, 0, v9
	v_fmac_f32_e32 v2, v168, v8
	v_max_f32_e32 v10, 0, v10
	v_fmac_f32_e32 v2, v167, v9
	v_max_f32_e32 v11, 0, v11
	v_fmac_f32_e32 v2, v166, v10
	v_max_f32_e32 v12, 0, v12
	v_fmac_f32_e32 v2, v165, v11
	v_max_f32_e32 v13, 0, v13
	v_fmac_f32_e32 v2, v164, v12
	v_max_f32_e32 v14, 0, v14
	v_fmac_f32_e32 v2, v163, v13
	v_fmac_f32_e32 v2, v162, v14
	v_max_f32_e32 v3, 0, v15
	v_fmac_f32_e32 v2, v161, v3
	v_max_f32_e32 v3, 0, v16
	v_fmac_f32_e32 v2, v160, v3
	v_max_f32_e32 v3, 0, v17
	v_fmac_f32_e32 v2, v89, v3
	v_cmp_gt_i32_e32 vcc, 0, v2
	v_not_b32_e32 v3, v2
	v_or_b32_e32 v4, 0x80000000, v2
	v_cndmask_b32_e32 v2, v4, v3, vcc
	v_cmp_le_u32_e32 vcc, v155, v87
	s_nop 1
	v_cndmask_b32_e32 v208, 0, v2, vcc
	s_branch .Lidxp_w62
.Lidxp_e62:
	v_max_f32_e32 v18, 0, v18
	v_max_f32_e32 v19, 0, v19
	v_fma_f32 v18, v174, v18, 0
	v_max_f32_e32 v20, 0, v20
	v_fmac_f32_e32 v18, v173, v19
	v_max_f32_e32 v21, 0, v21
	v_fmac_f32_e32 v18, v172, v20
	v_max_f32_e32 v22, 0, v22
	v_fmac_f32_e32 v18, v171, v21
	v_max_f32_e32 v23, 0, v23
	v_fmac_f32_e32 v18, v170, v22
	v_max_f32_e32 v24, 0, v24
	v_fmac_f32_e32 v18, v169, v23
	v_max_f32_e32 v25, 0, v25
	v_fmac_f32_e32 v18, v168, v24
	v_max_f32_e32 v26, 0, v26
	v_fmac_f32_e32 v18, v167, v25
	v_max_f32_e32 v27, 0, v27
	v_fmac_f32_e32 v18, v166, v26
	v_max_f32_e32 v28, 0, v28
	v_fmac_f32_e32 v18, v165, v27
	v_max_f32_e32 v29, 0, v29
	v_fmac_f32_e32 v18, v164, v28
	v_max_f32_e32 v30, 0, v30
	v_fmac_f32_e32 v18, v163, v29
	v_fmac_f32_e32 v18, v162, v30
	v_max_f32_e32 v19, 0, v31
	v_fmac_f32_e32 v18, v161, v19
	v_max_f32_e32 v19, 0, v32
	v_fmac_f32_e32 v18, v160, v19
	v_max_f32_e32 v19, 0, v33
	v_fmac_f32_e32 v18, v89, v19
	v_cmp_gt_i32_e32 vcc, 0, v18
	v_not_b32_e32 v19, v18
	v_or_b32_e32 v20, 0x80000000, v18
	v_cndmask_b32_e32 v18, v20, v19, vcc
	v_cmp_le_u32_e32 vcc, v156, v87
	s_nop 1
	v_cndmask_b32_e32 v210, 0, v18, vcc
	s_branch .Lidxp_w63
.Lidxp_e63:
	v_max_f32_e32 v2, 0, v2
	v_max_f32_e32 v3, 0, v3
	v_fma_f32 v2, v174, v2, 0
	v_max_f32_e32 v4, 0, v4
	v_fmac_f32_e32 v2, v173, v3
	v_max_f32_e32 v5, 0, v5
	v_fmac_f32_e32 v2, v172, v4
	v_max_f32_e32 v6, 0, v6
	v_fmac_f32_e32 v2, v171, v5
	v_max_f32_e32 v7, 0, v7
	v_fmac_f32_e32 v2, v170, v6
	v_max_f32_e32 v8, 0, v8
	v_fmac_f32_e32 v2, v169, v7
	v_max_f32_e32 v9, 0, v9
	v_fmac_f32_e32 v2, v168, v8
	v_max_f32_e32 v10, 0, v10
	v_fmac_f32_e32 v2, v167, v9
	v_max_f32_e32 v11, 0, v11
	v_fmac_f32_e32 v2, v166, v10
	v_max_f32_e32 v12, 0, v12
	v_fmac_f32_e32 v2, v165, v11
	v_max_f32_e32 v13, 0, v13
	v_fmac_f32_e32 v2, v164, v12
	v_max_f32_e32 v14, 0, v14
	v_fmac_f32_e32 v2, v163, v13
	v_fmac_f32_e32 v2, v162, v14
	v_max_f32_e32 v3, 0, v15
	v_fmac_f32_e32 v2, v161, v3
	v_max_f32_e32 v3, 0, v16
	v_fmac_f32_e32 v2, v160, v3
	v_max_f32_e32 v3, 0, v17
	v_fmac_f32_e32 v2, v89, v3
	v_cmp_gt_i32_e32 vcc, 0, v2
	v_not_b32_e32 v3, v2
	v_or_b32_e32 v4, 0x80000000, v2
	v_cndmask_b32_e32 v2, v4, v3, vcc
	v_cmp_le_u32_e32 vcc, v157, v87
	s_nop 1
	v_cndmask_b32_e32 v70, 0, v2, vcc
	s_branch .Lidxp_end
